# static s_setprio 1 for waves 4-7 inside the six GEMM K-loops (reset to 0 after each loop)
# speedup vs baseline: 1.0018x; 1.0018x over previous
; DI int otid() { int t = threadIdx.x; asm volatile("" : "+v"(t)); return t; }
; DI void glds16(const void* g, unsigned char* l) { __builtin_amdgcn_global_load_lds((const unsigned*)g, (lds_u32*)l, 16, 0, 0); }
;     ...
;   const int tid = otid(), lane = tid & 63, w = tid >> 6, wr = w / WC, wc = w % WC, fr = lane & 15, fq = lane >> 4;
;   const int srow = tid >> 3, kch = (tid & 7) ^ ((tid >> 4) & 7);
;   const unsigned voA = (unsigned)(srow * lda + kch * 8) * 2u, voB = (unsigned)(srow * ldb + kch * 8) * 2u;
;   const char* Ab = (const char*)A;
;   const char* Bb = (const char*)B;
;   const int nk = K >> 6;
;   if (!primed) {
; #pragma unroll
;     for (int i = 0; i < NA; ++i) glds16(Ab + (size_t)i * 128 * lda + voA, smem + (i * 512 + tid) * 16);
; #pragma unroll
;     for (int i = 0; i < NB; ++i) glds16(Bb + (size_t)i * 128 * ldb + voB, smem + AB + (i * 512 + tid) * 16);
;   }
;   const int sw = (fr >> 1) & 7;
;   const unsigned lds_base = (unsigned)(size_t)(__attribute__((address_space(3))) unsigned char*)smem;
;   const unsigned a_row = (wr * 16 * MT + fr) * 128, b_row = AB + (wc * 16 * NT + fr) * 128;
; template <int MT, int NT>
; DI void zero_acc(f32x4 (&acc)[MT][NT]) {
; #pragma unroll
;   for (int m = 0; m < MT; ++m)
; #pragma unroll
;     for (int n = 0; n < NT; ++n) acc[m][n] = (f32x4){0.f, 0.f, 0.f, 0.f};
; }
.LBB0_133:
	v_ashrrev_i32_e32 v1, 6, v0
	v_lshrrev_b32_e32 v5, 30, v1
	v_add_u32_e32 v5, v1, v5
	v_ashrrev_i32_e32 v5, 2, v5
	s_add_i32 s16, s2, s21
	v_mul_i32_i24_e32 v6, 4, v5
	v_bfe_u32 v7, v0, 1, 3
	v_lshlrev_b32_e32 v0, 7, v0
	s_ashr_i32 s17, s16, 31
	v_sub_u32_e32 v1, v1, v6
	v_and_b32_e32 v0, 0x780, v0
	s_lshl_b64 s[16:17], s[16:17], 19
	v_readlane_b32 s48, v252, 0
	v_lshl_or_b32 v141, v5, 14, v0
	v_lshl_or_b32 v0, v1, 13, v0
	v_readlane_b32 s49, v252, 1
	s_add_u32 s16, s48, s16
	v_and_b32_e32 v6, 3, v4
	v_add_u32_e32 v142, 0x8000, v0
	v_bitop3_b32 v0, v4, v7, 3 bitop3:0x6c
	s_addc_u32 s17, s49, s17
	v_lshlrev_b32_e32 v140, 4, v0
	v_bitop3_b32 v0, v6, v7, 4 bitop3:0x36
	s_add_u32 s14, s18, s14
	v_lshlrev_b32_e32 v138, 4, v0
	v_add_u32_e32 v0, v2, v3
	v_mov_b32_e32 v1, v129
	s_addc_u32 s15, s19, s15
	v_lshl_add_u64 v[134:135], s[16:17], 0, v[0:1]
	v_lshl_add_u64 v[136:137], s[14:15], 0, v[0:1]
	v_mov_b32_e32 v0, 0
	s_mov_b32 s13, 0
	s_mov_b64 s[46:47], 0
	v_mov_b32_e32 v1, v0
	v_mov_b32_e32 v2, v0
	v_mov_b32_e32 v3, v0
	v_mov_b32_e32 v4, v0
	v_mov_b32_e32 v5, v0
	v_mov_b32_e32 v6, v0
	v_mov_b32_e32 v7, v0
	v_mov_b32_e32 v8, v0
	v_mov_b32_e32 v9, v0
	v_mov_b32_e32 v10, v0
	v_mov_b32_e32 v11, v0
	v_mov_b32_e32 v12, v0
	v_mov_b32_e32 v13, v0
	v_mov_b32_e32 v14, v0
	v_mov_b32_e32 v15, v0
	v_mov_b32_e32 v16, v0
	v_mov_b32_e32 v17, v0
	v_mov_b32_e32 v18, v0
	v_mov_b32_e32 v19, v0
	v_mov_b32_e32 v20, v0
	v_mov_b32_e32 v21, v0
	v_mov_b32_e32 v22, v0
	v_mov_b32_e32 v23, v0
	v_mov_b32_e32 v24, v0
	v_mov_b32_e32 v25, v0
	v_mov_b32_e32 v26, v0
	v_mov_b32_e32 v27, v0
	v_mov_b32_e32 v28, v0
	v_mov_b32_e32 v29, v0
	v_mov_b32_e32 v30, v0
	v_mov_b32_e32 v31, v0
	v_mov_b32_e32 v32, v0
	v_mov_b32_e32 v33, v0
	v_mov_b32_e32 v34, v0
	v_mov_b32_e32 v35, v0
	v_mov_b32_e32 v36, v0
	v_mov_b32_e32 v37, v0
	v_mov_b32_e32 v38, v0
	v_mov_b32_e32 v39, v0
	v_mov_b32_e32 v40, v0
	v_mov_b32_e32 v41, v0
	v_mov_b32_e32 v42, v0
	v_mov_b32_e32 v43, v0
	v_mov_b32_e32 v44, v0
	v_mov_b32_e32 v45, v0
	v_mov_b32_e32 v46, v0
	v_mov_b32_e32 v47, v0
	v_mov_b32_e32 v48, v0
	v_mov_b32_e32 v49, v0
	v_mov_b32_e32 v50, v0
	v_mov_b32_e32 v51, v0
	v_mov_b32_e32 v52, v0
	v_mov_b32_e32 v53, v0
	v_mov_b32_e32 v54, v0
	v_mov_b32_e32 v55, v0
	v_mov_b32_e32 v56, v0
	v_mov_b32_e32 v57, v0
	v_mov_b32_e32 v58, v0
	v_mov_b32_e32 v59, v0
	v_mov_b32_e32 v60, v0
	v_mov_b32_e32 v61, v0
	v_mov_b32_e32 v62, v0
	v_mov_b32_e32 v63, v0
	v_mov_b32_e32 v64, v0
	v_mov_b32_e32 v65, v0
	v_mov_b32_e32 v66, v0
	v_mov_b32_e32 v67, v0
	v_mov_b32_e32 v68, v0
	v_mov_b32_e32 v69, v0
	v_mov_b32_e32 v70, v0
	v_mov_b32_e32 v71, v0
	v_mov_b32_e32 v72, v0
	v_mov_b32_e32 v73, v0
	v_mov_b32_e32 v74, v0
	v_mov_b32_e32 v75, v0
	v_mov_b32_e32 v76, v0
	v_mov_b32_e32 v77, v0
	v_mov_b32_e32 v78, v0
	v_mov_b32_e32 v79, v0
	v_mov_b32_e32 v80, v0
	v_mov_b32_e32 v81, v0
	v_mov_b32_e32 v82, v0
	v_mov_b32_e32 v83, v0
	v_mov_b32_e32 v84, v0
	v_mov_b32_e32 v85, v0
	v_mov_b32_e32 v86, v0
	v_mov_b32_e32 v87, v0
	v_mov_b32_e32 v88, v0
	v_mov_b32_e32 v89, v0
	v_mov_b32_e32 v90, v0
	v_mov_b32_e32 v91, v0
	v_mov_b32_e32 v92, v0
	v_mov_b32_e32 v93, v0
	v_mov_b32_e32 v94, v0
	v_mov_b32_e32 v95, v0
	v_mov_b32_e32 v96, v0
	v_mov_b32_e32 v97, v0
	v_mov_b32_e32 v98, v0
	v_mov_b32_e32 v99, v0
	v_mov_b32_e32 v100, v0
	v_mov_b32_e32 v101, v0
	v_mov_b32_e32 v102, v0
	v_mov_b32_e32 v103, v0
	v_mov_b32_e32 v104, v0
	v_mov_b32_e32 v105, v0
	v_mov_b32_e32 v106, v0
	v_mov_b32_e32 v107, v0
	v_mov_b32_e32 v108, v0
	v_mov_b32_e32 v109, v0
	v_mov_b32_e32 v110, v0
	v_mov_b32_e32 v111, v0
	v_mov_b32_e32 v112, v0
	v_mov_b32_e32 v113, v0
	v_mov_b32_e32 v114, v0
	v_mov_b32_e32 v115, v0
	v_mov_b32_e32 v116, v0
	v_mov_b32_e32 v117, v0
	v_mov_b32_e32 v118, v0
	v_mov_b32_e32 v119, v0
	v_mov_b32_e32 v120, v0
	v_mov_b32_e32 v121, v0
	v_mov_b32_e32 v122, v0
	v_mov_b32_e32 v123, v0
	v_mov_b32_e32 v124, v0
	v_mov_b32_e32 v125, v0
	v_mov_b32_e32 v126, v0
	v_mov_b32_e32 v127, v0
	s_mov_b64 s[16:17], 0x8080
	v_readlane_b32 s50, v252, 2
	v_readlane_b32 s51, v252, 3
	v_mov_b32_e32 v188, 0
	v_mov_b32_e32 v189, 0
	v_mov_b32_e32 v190, 0
	v_mov_b32_e32 v191, 0
	v_mov_b32_e32 v192, 0
	v_mov_b32_e32 v193, 0
	v_mov_b32_e32 v194, 0
	v_mov_b32_e32 v195, 0
	v_mov_b32_e32 v196, 0
	v_mov_b32_e32 v197, 0
	v_mov_b32_e32 v198, 0
	v_mov_b32_e32 v199, 0
	v_mov_b32_e32 v200, 0
	v_mov_b32_e32 v201, 0
	v_mov_b32_e32 v202, 0
	v_mov_b32_e32 v203, 0
	v_mov_b32_e32 v204, 0
	v_mov_b32_e32 v205, 0
	v_mov_b32_e32 v206, 0
	v_mov_b32_e32 v207, 0
	v_mov_b32_e32 v208, 0
	v_mov_b32_e32 v209, 0
	v_mov_b32_e32 v210, 0
	v_mov_b32_e32 v211, 0
	v_mov_b32_e32 v228, 0
	v_mov_b32_e32 v229, 0
	v_mov_b32_e32 v230, 0
	v_mov_b32_e32 v231, 0
	v_mov_b32_e32 v232, 0
	v_mov_b32_e32 v233, 0
	v_mov_b32_e32 v234, 0
	v_mov_b32_e32 v235, 0
	v_lshrrev_b32_e32 v240, 8, v212
	s_nop 0
	v_readfirstlane_b32 s98, v240
	s_cmp_eq_u32 s98, 0
	s_cbranch_scc1 .Lprio_0
	s_setprio 1
; #define MFMA16(a, b, c) __builtin_amdgcn_mfma_f32_16x16x32_bf16((a), (b), (c), 0, 0, 0)
; DI void glds16(const void* g, unsigned char* l) { __builtin_amdgcn_global_load_lds((const unsigned*)g, (lds_u32*)l, 16, 0, 0); }
; template <int N> DI void wait_vm() { asm volatile("s_waitcnt vmcnt(%0)" :: "n"(N) : "memory"); }
;     ...
;   for (int kt = 0; kt < nk; ++kt) {
;     wait_vm<0>();
;     __builtin_amdgcn_s_barrier();
;     if (kt + 1 < nk) {
;       unsigned char* sn = smem + ((kt + 1) & 1) * STG;
;       const int ko = (kt + 1) * 64;
; #pragma unroll
;       for (int i = 0; i < NA; ++i) glds16(Ab + ((size_t)i * 128 * lda + ko * 2) + voA, sn + (i * 512 + tid) * 16);
; #pragma unroll
;       for (int i = 0; i < NB; ++i) glds16(Bb + ((size_t)i * 128 * ldb + ko * 2) + voB, sn + AB + (i * 512 + tid) * 16);
;     } else if (nA) {
;       const unsigned nvoA = (unsigned)(srow * nlda + kch * 8) * 2u, nvoB = (unsigned)(srow * nldb + kch * 8) * 2u;
; #pragma unroll
;       for (int i = 0; i < NA; ++i) glds16((const char*)nA + (size_t)i * 128 * nlda + nvoA, smem + (i * 512 + tid) * 16);
; #pragma unroll
;       for (int i = 0; i < NB; ++i) glds16((const char*)nB + (size_t)i * 128 * nldb + nvoB, smem + AB + (i * 512 + tid) * 16);
;     }
;     const unsigned stb = lds_base + (kt & 1) * STG;
; #pragma unroll
;     for (int ks = 0; ks < 2; ++ks) {
;       const unsigned co = ((ks * 4 + fq) ^ sw) * 16;
;       const unsigned sa = stb + a_row + co, sb = stb + b_row + co;
;       bf16x8 af[4], bfr[NT];
; #pragma unroll
;       for (int n = 0; n < NT; ++n) asm volatile("ds_read_b128 %0, %1 offset:%2" : "=v"(bfr[n]) : "v"(sb), "n"(n * 2048) : "memory");
; #pragma unroll
;       for (int mg = 0; mg < MT / 4; ++mg) {
; #pragma unroll
;         for (int m = 0; m < 4; ++m) asm volatile("ds_read_b128 %0, %1 offset:%2" : "=v"(af[m]) : "v"(sa), "n"((mg * 4 + m) * 2048) : "memory");
;         if (mg == 0) {
; #pragma unroll
;           for (int n = 0; n < NT; ++n) asm volatile("s_waitcnt lgkmcnt(%1)" : "+v"(bfr[n]) : "n"(4 + NT - 1 - n) : "memory");
;         }
; #pragma unroll
;         for (int m = 0; m < 4; ++m) {
;           asm volatile("s_waitcnt lgkmcnt(%1)" : "+v"(af[m]) : "n"(3 - m) : "memory");
; #pragma unroll
;           for (int n = 0; n < NT; ++n) acc[mg * 4 + m][n] = MFMA16(bfr[n], af[m], acc[mg * 4 + m][n]);
;         }
;       }
.Lprio_0:
.LBB0_134:
	s_add_i32 s2, s13, 0x10000
	s_and_b32 s14, s2, 0x10000
	v_add_u32_e32 v143, s14, v139
	v_lshl_add_u64 v[144:145], v[134:135], 0, s[46:47]
	v_readfirstlane_b32 s14, v143
	v_add_u32_e32 v148, 0x2000, v143
	v_lshl_add_u64 v[146:147], v[144:145], 0, s[58:59]
	s_mov_b32 m0, s14
	v_readfirstlane_b32 s14, v148
	v_add_u32_e32 v148, 0x4000, v143
	s_waitcnt vmcnt(0)
	s_waitcnt lgkmcnt(0)
	s_barrier
	s_and_b32 s13, s13, 0x10000
	v_add_u32_e32 v240, s13, v142
	v_add_u32_e32 v236, v240, v140
	v_add_u32_e32 v237, v240, v138
	v_add_u32_e32 v240, s13, v141
	v_add_u32_e32 v238, v240, v140
	v_add_u32_e32 v239, v240, v138
	v_mfma_f32_16x16x32_bf16 v[60:63], v[188:191], v[204:207], v[60:63]
	ds_read_b128 v[152:155], v236 offset:0
	ds_read_b128 v[156:159], v236 offset:2048
	v_mfma_f32_16x16x32_bf16 v[56:59], v[192:195], v[204:207], v[56:59]
	ds_read_b128 v[160:163], v236 offset:4096
	ds_read_b128 v[164:167], v236 offset:6144
	global_load_lds_dwordx4 v[146:147], off
	v_mfma_f32_16x16x32_bf16 v[52:55], v[196:199], v[204:207], v[52:55]
	ds_read_b128 v[168:171], v238 offset:0
	ds_read_b128 v[172:175], v238 offset:2048
	v_mfma_f32_16x16x32_bf16 v[48:51], v[200:203], v[204:207], v[48:51]
	ds_read_b128 v[180:183], v238 offset:4096
	ds_read_b128 v[184:187], v238 offset:6144
	v_mfma_f32_16x16x32_bf16 v[44:47], v[188:191], v[208:211], v[44:47]
	v_mfma_f32_16x16x32_bf16 v[40:43], v[192:195], v[208:211], v[40:43]
	v_mfma_f32_16x16x32_bf16 v[36:39], v[196:199], v[208:211], v[36:39]
	v_lshl_add_u64 v[146:147], v[144:145], 0, s[60:61]
	s_mov_b32 m0, s14
	v_readfirstlane_b32 s14, v148
	global_load_lds_dwordx4 v[146:147], off
	v_mfma_f32_16x16x32_bf16 v[32:35], v[200:203], v[208:211], v[32:35]
	v_mfma_f32_16x16x32_bf16 v[28:31], v[188:191], v[228:231], v[28:31]
	v_mfma_f32_16x16x32_bf16 v[24:27], v[192:195], v[228:231], v[24:27]
	v_mfma_f32_16x16x32_bf16 v[20:23], v[196:199], v[228:231], v[20:23]
	v_mfma_f32_16x16x32_bf16 v[16:19], v[200:203], v[228:231], v[16:19]
	v_lshl_add_u64 v[146:147], v[144:145], 0, s[62:63]
	s_mov_b32 m0, s14
	v_lshl_add_u64 v[144:145], v[144:145], 0, s[64:65]
	global_load_lds_dwordx4 v[146:147], off
	v_mfma_f32_16x16x32_bf16 v[12:15], v[188:191], v[232:235], v[12:15]
	v_mfma_f32_16x16x32_bf16 v[8:11], v[192:195], v[232:235], v[8:11]
	v_mfma_f32_16x16x32_bf16 v[4:7], v[196:199], v[232:235], v[4:7]
	v_mfma_f32_16x16x32_bf16 v[0:3], v[200:203], v[232:235], v[0:3]
	s_waitcnt lgkmcnt(3)
	v_mfma_f32_16x16x32_bf16 v[124:127], v[152:155], v[168:171], v[124:127]
	v_add_u32_e32 v146, 0x6000, v143
	v_add_u32_e32 v148, 0x8000, v143
	v_readfirstlane_b32 s14, v146
	s_mov_b32 m0, s14
	v_readfirstlane_b32 s14, v148
	global_load_lds_dwordx4 v[144:145], off
	v_mfma_f32_16x16x32_bf16 v[120:123], v[156:159], v[168:171], v[120:123]
	ds_read_b128 v[204:207], v238 offset:8192
	v_mfma_f32_16x16x32_bf16 v[116:119], v[160:163], v[168:171], v[116:119]
	v_mfma_f32_16x16x32_bf16 v[112:115], v[164:167], v[168:171], v[112:115]
	ds_read_b128 v[208:211], v238 offset:10240
	s_waitcnt lgkmcnt(4)
	v_mfma_f32_16x16x32_bf16 v[108:111], v[152:155], v[172:175], v[108:111]
	v_mfma_f32_16x16x32_bf16 v[104:107], v[156:159], v[172:175], v[104:107]
	ds_read_b128 v[228:231], v238 offset:12288
	v_lshl_add_u64 v[144:145], v[136:137], 0, s[46:47]
	v_lshl_add_u64 v[146:147], v[144:145], 0, s[16:17]
	s_mov_b32 m0, s14
	s_mov_b64 s[14:15], 0x28080
	v_add_u32_e32 v148, 0xa000, v143
	global_load_lds_dwordx4 v[146:147], off
	v_mfma_f32_16x16x32_bf16 v[100:103], v[160:163], v[172:175], v[100:103]
	v_mfma_f32_16x16x32_bf16 v[96:99], v[164:167], v[172:175], v[96:99]
	ds_read_b128 v[232:235], v238 offset:14336
	s_waitcnt lgkmcnt(5)
	v_mfma_f32_16x16x32_bf16 v[92:95], v[152:155], v[180:183], v[92:95]
	v_mfma_f32_16x16x32_bf16 v[88:91], v[156:159], v[180:183], v[88:91]
	ds_read_b128 v[188:191], v237 offset:0
	v_mfma_f32_16x16x32_bf16 v[84:87], v[160:163], v[180:183], v[84:87]
	v_lshl_add_u64 v[146:147], v[144:145], 0, s[14:15]
	v_readfirstlane_b32 s14, v148
	s_mov_b32 m0, s14
	s_mov_b64 s[14:15], 0x48080
	v_add_u32_e32 v148, 0xc000, v143
	global_load_lds_dwordx4 v[146:147], off
	v_mfma_f32_16x16x32_bf16 v[80:83], v[164:167], v[180:183], v[80:83]
	ds_read_b128 v[192:195], v237 offset:2048
	s_waitcnt lgkmcnt(6)
	v_mfma_f32_16x16x32_bf16 v[76:79], v[152:155], v[184:187], v[76:79]
	v_mfma_f32_16x16x32_bf16 v[72:75], v[156:159], v[184:187], v[72:75]
	ds_read_b128 v[196:199], v237 offset:4096
	v_mfma_f32_16x16x32_bf16 v[68:71], v[160:163], v[184:187], v[68:71]
	v_mfma_f32_16x16x32_bf16 v[64:67], v[164:167], v[184:187], v[64:67]
	ds_read_b128 v[200:203], v237 offset:6144
	v_lshl_add_u64 v[146:147], v[144:145], 0, s[14:15]
	v_readfirstlane_b32 s14, v148
	s_mov_b32 m0, s14
	s_mov_b64 s[14:15], 0x68080
	v_add_u32_e32 v143, 0xe000, v143
	v_lshl_add_u64 v[144:145], v[144:145], 0, s[14:15]
	v_readfirstlane_b32 s14, v143
	global_load_lds_dwordx4 v[146:147], off
	s_waitcnt lgkmcnt(7)
	v_mfma_f32_16x16x32_bf16 v[60:63], v[152:155], v[204:207], v[60:63]
	v_mfma_f32_16x16x32_bf16 v[56:59], v[156:159], v[204:207], v[56:59]
	ds_read_b128 v[168:171], v239 offset:0
	v_mfma_f32_16x16x32_bf16 v[52:55], v[160:163], v[204:207], v[52:55]
	v_mfma_f32_16x16x32_bf16 v[48:51], v[164:167], v[204:207], v[48:51]
	ds_read_b128 v[172:175], v239 offset:2048
	s_waitcnt lgkmcnt(8)
; #define MFMA16(a, b, c) __builtin_amdgcn_mfma_f32_16x16x32_bf16((a), (b), (c), 0, 0, 0)
; DI void glds16(const void* g, unsigned char* l) { __builtin_amdgcn_global_load_lds((const unsigned*)g, (lds_u32*)l, 16, 0, 0); }
; template <int N> DI void wait_vm() { asm volatile("s_waitcnt vmcnt(%0)" :: "n"(N) : "memory"); }
;     ...
;   for (int kt = 0; kt < nk; ++kt) {
;     wait_vm<0>();
;     __builtin_amdgcn_s_barrier();
;     if (kt + 1 < nk) {
;       unsigned char* sn = smem + ((kt + 1) & 1) * STG;
;       const int ko = (kt + 1) * 64;
; #pragma unroll
;       for (int i = 0; i < NA; ++i) glds16(Ab + ((size_t)i * 128 * lda + ko * 2) + voA, sn + (i * 512 + tid) * 16);
; #pragma unroll
;       for (int i = 0; i < NB; ++i) glds16(Bb + ((size_t)i * 128 * ldb + ko * 2) + voB, sn + AB + (i * 512 + tid) * 16);
;     } else if (nA) {
;       const unsigned nvoA = (unsigned)(srow * nlda + kch * 8) * 2u, nvoB = (unsigned)(srow * nldb + kch * 8) * 2u;
; #pragma unroll
;       for (int i = 0; i < NA; ++i) glds16((const char*)nA + (size_t)i * 128 * nlda + nvoA, smem + (i * 512 + tid) * 16);
; #pragma unroll
;       for (int i = 0; i < NB; ++i) glds16((const char*)nB + (size_t)i * 128 * nldb + nvoB, smem + AB + (i * 512 + tid) * 16);
;     }
;     const unsigned stb = lds_base + (kt & 1) * STG;
; #pragma unroll
;     for (int ks = 0; ks < 2; ++ks) {
;       const unsigned co = ((ks * 4 + fq) ^ sw) * 16;
;       const unsigned sa = stb + a_row + co, sb = stb + b_row + co;
;       bf16x8 af[4], bfr[NT];
; #pragma unroll
;       for (int n = 0; n < NT; ++n) asm volatile("ds_read_b128 %0, %1 offset:%2" : "=v"(bfr[n]) : "v"(sb), "n"(n * 2048) : "memory");
; #pragma unroll
;       for (int mg = 0; mg < MT / 4; ++mg) {
; #pragma unroll
;         for (int m = 0; m < 4; ++m) asm volatile("ds_read_b128 %0, %1 offset:%2" : "=v"(af[m]) : "v"(sa), "n"((mg * 4 + m) * 2048) : "memory");
;         if (mg == 0) {
; #pragma unroll
;           for (int n = 0; n < NT; ++n) asm volatile("s_waitcnt lgkmcnt(%1)" : "+v"(bfr[n]) : "n"(4 + NT - 1 - n) : "memory");
;         }
; #pragma unroll
;         for (int m = 0; m < 4; ++m) {
;           asm volatile("s_waitcnt lgkmcnt(%1)" : "+v"(af[m]) : "n"(3 - m) : "memory");
; #pragma unroll
;           for (int n = 0; n < NT; ++n) acc[mg * 4 + m][n] = MFMA16(bfr[n], af[m], acc[mg * 4 + m][n]);
;         }
;       }
;     }
	v_mfma_f32_16x16x32_bf16 v[44:47], v[152:155], v[208:211], v[44:47]
	s_mov_b32 m0, s14
	s_nop 0
	global_load_lds_dwordx4 v[144:145], off
	v_mfma_f32_16x16x32_bf16 v[40:43], v[156:159], v[208:211], v[40:43]
	ds_read_b128 v[180:183], v239 offset:4096
	v_mfma_f32_16x16x32_bf16 v[36:39], v[160:163], v[208:211], v[36:39]
	v_mfma_f32_16x16x32_bf16 v[32:35], v[164:167], v[208:211], v[32:35]
	ds_read_b128 v[184:187], v239 offset:6144
	s_waitcnt lgkmcnt(9)
	v_mfma_f32_16x16x32_bf16 v[28:31], v[152:155], v[228:231], v[28:31]
	v_mfma_f32_16x16x32_bf16 v[24:27], v[156:159], v[228:231], v[24:27]
	v_mfma_f32_16x16x32_bf16 v[20:23], v[160:163], v[228:231], v[20:23]
	v_mfma_f32_16x16x32_bf16 v[16:19], v[164:167], v[228:231], v[16:19]
	s_waitcnt lgkmcnt(8)
	v_mfma_f32_16x16x32_bf16 v[12:15], v[152:155], v[232:235], v[12:15]
	v_mfma_f32_16x16x32_bf16 v[8:11], v[156:159], v[232:235], v[8:11]
	v_mfma_f32_16x16x32_bf16 v[4:7], v[160:163], v[232:235], v[4:7]
	v_mfma_f32_16x16x32_bf16 v[0:3], v[164:167], v[232:235], v[0:3]
	s_waitcnt lgkmcnt(3)
	v_mfma_f32_16x16x32_bf16 v[124:127], v[188:191], v[168:171], v[124:127]
	v_mfma_f32_16x16x32_bf16 v[120:123], v[192:195], v[168:171], v[120:123]
	ds_read_b128 v[204:207], v239 offset:8192
	v_mfma_f32_16x16x32_bf16 v[116:119], v[196:199], v[168:171], v[116:119]
	v_mfma_f32_16x16x32_bf16 v[112:115], v[200:203], v[168:171], v[112:115]
	ds_read_b128 v[208:211], v239 offset:10240
	s_waitcnt lgkmcnt(4)
	v_mfma_f32_16x16x32_bf16 v[108:111], v[188:191], v[172:175], v[108:111]
	v_mfma_f32_16x16x32_bf16 v[104:107], v[192:195], v[172:175], v[104:107]
	ds_read_b128 v[228:231], v239 offset:12288
	v_mfma_f32_16x16x32_bf16 v[100:103], v[196:199], v[172:175], v[100:103]
	v_mfma_f32_16x16x32_bf16 v[96:99], v[200:203], v[172:175], v[96:99]
	ds_read_b128 v[232:235], v239 offset:14336
	s_waitcnt lgkmcnt(5)
	v_mfma_f32_16x16x32_bf16 v[92:95], v[188:191], v[180:183], v[92:95]
	v_mfma_f32_16x16x32_bf16 v[88:91], v[192:195], v[180:183], v[88:91]
	v_mfma_f32_16x16x32_bf16 v[84:87], v[196:199], v[180:183], v[84:87]
	v_mfma_f32_16x16x32_bf16 v[80:83], v[200:203], v[180:183], v[80:83]
	s_waitcnt lgkmcnt(4)
	v_mfma_f32_16x16x32_bf16 v[76:79], v[188:191], v[184:187], v[76:79]
	v_mfma_f32_16x16x32_bf16 v[72:75], v[192:195], v[184:187], v[72:75]
	v_mfma_f32_16x16x32_bf16 v[68:71], v[196:199], v[184:187], v[68:71]
	v_mfma_f32_16x16x32_bf16 v[64:67], v[200:203], v[184:187], v[64:67]
	s_add_u32 s46, s46, 0x80
	s_addc_u32 s47, s47, 0
	s_cmpk_eq_i32 s46, 0x780
	s_mov_b32 s13, s2
	s_cbranch_scc0 .LBB0_134
	s_waitcnt lgkmcnt(0)
	v_mfma_f32_16x16x32_bf16 v[60:63], v[188:191], v[204:207], v[60:63]
	v_mfma_f32_16x16x32_bf16 v[56:59], v[192:195], v[204:207], v[56:59]
	v_mfma_f32_16x16x32_bf16 v[52:55], v[196:199], v[204:207], v[52:55]
	v_mfma_f32_16x16x32_bf16 v[48:51], v[200:203], v[204:207], v[48:51]
	v_mfma_f32_16x16x32_bf16 v[44:47], v[188:191], v[208:211], v[44:47]
	v_mfma_f32_16x16x32_bf16 v[40:43], v[192:195], v[208:211], v[40:43]
	v_mfma_f32_16x16x32_bf16 v[36:39], v[196:199], v[208:211], v[36:39]
	v_mfma_f32_16x16x32_bf16 v[32:35], v[200:203], v[208:211], v[32:35]
	v_mfma_f32_16x16x32_bf16 v[28:31], v[188:191], v[228:231], v[28:31]
	v_mfma_f32_16x16x32_bf16 v[24:27], v[192:195], v[228:231], v[24:27]
	v_mfma_f32_16x16x32_bf16 v[20:23], v[196:199], v[228:231], v[20:23]
	v_mfma_f32_16x16x32_bf16 v[16:19], v[200:203], v[228:231], v[16:19]
	v_mfma_f32_16x16x32_bf16 v[12:15], v[188:191], v[232:235], v[12:15]
	v_mfma_f32_16x16x32_bf16 v[8:11], v[192:195], v[232:235], v[8:11]
	v_mfma_f32_16x16x32_bf16 v[4:7], v[196:199], v[232:235], v[4:7]
	v_mfma_f32_16x16x32_bf16 v[0:3], v[200:203], v[232:235], v[0:3]
	s_setprio 0
	s_waitcnt vmcnt(0)
	s_andn2_b64 vcc, exec, s[10:11]
	s_mov_b64 s[48:49], s[26:27]
	s_mov_b64 s[50:51], 0xe3f8080
	s_barrier
	s_cbranch_vccnz .LBB0_137
	s_add_u32 s2, s54, s42
	s_addc_u32 s13, s55, s43
	s_and_b64 s[10:11], exec, s[38:39]
	s_cselect_b32 s11, 0, s13
	s_cselect_b32 s10, 0, s2
	v_readfirstlane_b32 s2, v139
	v_lshl_add_u64 v[134:135], s[10:11], 0, v[128:129]
	s_mov_b32 m0, s2
	v_lshl_add_u64 v[144:145], v[134:135], 0, s[80:81]
	v_lshl_add_u64 v[152:153], v[134:135], 0, s[82:83]
	v_lshl_add_u64 v[154:155], v[134:135], 0, s[70:71]
	global_load_lds_dwordx4 v[134:135], off
	v_add_u32_e32 v134, 0x2000, v139
	v_add_u32_e32 v143, 0x4000, v139
	v_readfirstlane_b32 s2, v134
	s_mov_b32 m0, s2
	v_readfirstlane_b32 s2, v143
	v_add_u32_e32 v134, 0x6000, v139
	s_add_u32 s14, s33, s44
	global_load_lds_dwordx4 v[154:155], off
	s_mov_b32 m0, s2
	v_readfirstlane_b32 s2, v134
	v_add_u32_e32 v134, 0x8000, v139
	s_addc_u32 s15, s34, s45
	global_load_lds_dwordx4 v[144:145], off
	s_mov_b32 m0, s2
	v_readfirstlane_b32 s2, v134
	v_add_u32_e32 v134, 0xa000, v139
	v_lshl_add_u64 v[136:137], s[14:15], 0, v[128:129]
	v_add_u32_e32 v128, 0xc000, v139
	global_load_lds_dwordx4 v[152:153], off
	s_mov_b32 m0, s2
	v_readfirstlane_b32 s2, v134
	v_lshl_add_u64 v[150:151], v[136:137], 0, s[70:71]
	global_load_lds_dwordx4 v[136:137], off
	s_mov_b32 m0, s2
	v_readfirstlane_b32 s2, v128
	v_add_u32_e32 v128, 0xe000, v139
	v_lshl_add_u64 v[146:147], v[136:137], 0, s[80:81]
	global_load_lds_dwordx4 v[150:151], off
	s_mov_b32 m0, s2
	v_readfirstlane_b32 s2, v128
	v_lshl_add_u64 v[148:149], v[136:137], 0, s[82:83]
	global_load_lds_dwordx4 v[146:147], off
	s_mov_b32 m0, s2
	s_nop 0
	global_load_lds_dwordx4 v[148:149], off

; DI int otid() { int t = threadIdx.x; asm volatile("" : "+v"(t)); return t; }
; DI void glds16(const void* g, unsigned char* l) { __builtin_amdgcn_global_load_lds((const unsigned*)g, (lds_u32*)l, 16, 0, 0); }
;     ...
;   const int tid = otid(), lane = tid & 63, w = tid >> 6, wr = w / WC, wc = w % WC, fr = lane & 15, fq = lane >> 4;
;   const int srow = tid >> 3, kch = (tid & 7) ^ ((tid >> 4) & 7);
;   const unsigned voA = (unsigned)(srow * lda + kch * 8) * 2u, voB = (unsigned)(srow * ldb + kch * 8) * 2u;
;   const char* Ab = (const char*)A;
;   const char* Bb = (const char*)B;
;   const int nk = K >> 6;
;   if (!primed) {
; #pragma unroll
;     for (int i = 0; i < NA; ++i) glds16(Ab + (size_t)i * 128 * lda + voA, smem + (i * 512 + tid) * 16);
; #pragma unroll
;     for (int i = 0; i < NB; ++i) glds16(Bb + (size_t)i * 128 * ldb + voB, smem + AB + (i * 512 + tid) * 16);
;   }
;   const int sw = (fr >> 1) & 7;
;   const unsigned lds_base = (unsigned)(size_t)(__attribute__((address_space(3))) unsigned char*)smem;
;   const unsigned a_row = (wr * 16 * MT + fr) * 128, b_row = AB + (wc * 16 * NT + fr) * 128;
; template <int MT, int NT>
; DI void zero_acc(f32x4 (&acc)[MT][NT]) {
; #pragma unroll
;   for (int m = 0; m < MT; ++m)
; #pragma unroll
;     for (int n = 0; n < NT; ++n) acc[m][n] = (f32x4){0.f, 0.f, 0.f, 0.f};
; }
.LBB0_201:
	v_ashrrev_i32_e32 v1, 6, v0
	v_lshrrev_b32_e32 v5, 30, v1
	v_add_u32_e32 v5, v1, v5
	v_ashrrev_i32_e32 v5, 2, v5
	v_mul_i32_i24_e32 v6, 4, v5
	v_bfe_u32 v7, v0, 1, 3
	v_lshlrev_b32_e32 v0, 7, v0
	v_sub_u32_e32 v1, v1, v6
	v_and_b32_e32 v0, 0x780, v0
	s_add_i32 s16, s23, s26
	v_lshl_or_b32 v141, v5, 14, v0
	v_lshl_or_b32 v0, v1, 13, v0
	s_mul_hi_i32 s17, s16, 0x160000
	s_mul_i32 s16, s16, 0x160000
	v_readlane_b32 s44, v252, 0
	v_and_b32_e32 v6, 3, v4
	v_add_u32_e32 v142, 0x8000, v0
	v_bitop3_b32 v0, v4, v7, 3 bitop3:0x6c
	v_readlane_b32 s45, v252, 1
	s_add_u32 s16, s44, s16
	v_lshlrev_b32_e32 v140, 4, v0
	v_bitop3_b32 v0, v6, v7, 4 bitop3:0x36
	s_movk_i32 s23, 0x1600
	s_addc_u32 s17, s45, s17
	s_lshl_b64 s[14:15], s[14:15], 1
	v_lshlrev_b32_e32 v131, 4, v0
	v_mul_lo_u32 v0, v2, s23
	v_and_b32_e32 v1, 7, v3
	s_add_u32 s14, s20, s14
	v_lshl_or_b32 v0, v1, 4, v0
	v_mov_b32_e32 v1, v129
	s_addc_u32 s15, s21, s15
	v_lshl_add_u64 v[136:137], s[16:17], 0, v[0:1]
	v_lshl_add_u64 v[138:139], s[14:15], 0, v[0:1]
	v_mov_b32_e32 v0, 0
	s_mov_b64 s[44:45], 0
	s_mov_b32 s15, 0
	v_mov_b32_e32 v1, v0
	v_mov_b32_e32 v2, v0
	v_mov_b32_e32 v3, v0
	v_mov_b32_e32 v4, v0
	v_mov_b32_e32 v5, v0
	v_mov_b32_e32 v6, v0
	v_mov_b32_e32 v7, v0
	v_mov_b32_e32 v8, v0
	v_mov_b32_e32 v9, v0
	v_mov_b32_e32 v10, v0
	v_mov_b32_e32 v11, v0
	v_mov_b32_e32 v12, v0
	v_mov_b32_e32 v13, v0
	v_mov_b32_e32 v14, v0
	v_mov_b32_e32 v15, v0
	v_mov_b32_e32 v16, v0
	v_mov_b32_e32 v17, v0
	v_mov_b32_e32 v18, v0
	v_mov_b32_e32 v19, v0
	v_mov_b32_e32 v20, v0
	v_mov_b32_e32 v21, v0
	v_mov_b32_e32 v22, v0
	v_mov_b32_e32 v23, v0
	v_mov_b32_e32 v24, v0
	v_mov_b32_e32 v25, v0
	v_mov_b32_e32 v26, v0
	v_mov_b32_e32 v27, v0
	v_mov_b32_e32 v28, v0
	v_mov_b32_e32 v29, v0
	v_mov_b32_e32 v30, v0
	v_mov_b32_e32 v31, v0
	v_mov_b32_e32 v32, v0
	v_mov_b32_e32 v33, v0
	v_mov_b32_e32 v34, v0
	v_mov_b32_e32 v35, v0
	v_mov_b32_e32 v36, v0
	v_mov_b32_e32 v37, v0
	v_mov_b32_e32 v38, v0
	v_mov_b32_e32 v39, v0
	v_mov_b32_e32 v40, v0
	v_mov_b32_e32 v41, v0
	v_mov_b32_e32 v42, v0
	v_mov_b32_e32 v43, v0
	v_mov_b32_e32 v44, v0
	v_mov_b32_e32 v45, v0
	v_mov_b32_e32 v46, v0
	v_mov_b32_e32 v47, v0
	v_mov_b32_e32 v48, v0
	v_mov_b32_e32 v49, v0
	v_mov_b32_e32 v50, v0
	v_mov_b32_e32 v51, v0
	v_mov_b32_e32 v52, v0
	v_mov_b32_e32 v53, v0
	v_mov_b32_e32 v54, v0
	v_mov_b32_e32 v55, v0
	v_mov_b32_e32 v56, v0
	v_mov_b32_e32 v57, v0
	v_mov_b32_e32 v58, v0
	v_mov_b32_e32 v59, v0
	v_mov_b32_e32 v60, v0
	v_mov_b32_e32 v61, v0
	v_mov_b32_e32 v62, v0
	v_mov_b32_e32 v63, v0
	v_mov_b32_e32 v64, v0
	v_mov_b32_e32 v65, v0
	v_mov_b32_e32 v66, v0
	v_mov_b32_e32 v67, v0
	v_mov_b32_e32 v68, v0
	v_mov_b32_e32 v69, v0
	v_mov_b32_e32 v70, v0
	v_mov_b32_e32 v71, v0
	v_mov_b32_e32 v72, v0
	v_mov_b32_e32 v73, v0
	v_mov_b32_e32 v74, v0
	v_mov_b32_e32 v75, v0
	v_mov_b32_e32 v76, v0
	v_mov_b32_e32 v77, v0
	v_mov_b32_e32 v78, v0
	v_mov_b32_e32 v79, v0
	v_mov_b32_e32 v80, v0
	v_mov_b32_e32 v81, v0
	v_mov_b32_e32 v82, v0
	v_mov_b32_e32 v83, v0
	v_mov_b32_e32 v84, v0
	v_mov_b32_e32 v85, v0
	v_mov_b32_e32 v86, v0
	v_mov_b32_e32 v87, v0
	v_mov_b32_e32 v88, v0
	v_mov_b32_e32 v89, v0
	v_mov_b32_e32 v90, v0
	v_mov_b32_e32 v91, v0
	v_mov_b32_e32 v92, v0
	v_mov_b32_e32 v93, v0
	v_mov_b32_e32 v94, v0
	v_mov_b32_e32 v95, v0
	v_mov_b32_e32 v96, v0
	v_mov_b32_e32 v97, v0
	v_mov_b32_e32 v98, v0
	v_mov_b32_e32 v99, v0
	v_mov_b32_e32 v100, v0
	v_mov_b32_e32 v101, v0
	v_mov_b32_e32 v102, v0
	v_mov_b32_e32 v103, v0
	v_mov_b32_e32 v104, v0
	v_mov_b32_e32 v105, v0
	v_mov_b32_e32 v106, v0
	v_mov_b32_e32 v107, v0
	v_mov_b32_e32 v108, v0
	v_mov_b32_e32 v109, v0
	v_mov_b32_e32 v110, v0
	v_mov_b32_e32 v111, v0
	v_mov_b32_e32 v112, v0
	v_mov_b32_e32 v113, v0
	v_mov_b32_e32 v114, v0
	v_mov_b32_e32 v115, v0
	v_mov_b32_e32 v116, v0
	v_mov_b32_e32 v117, v0
	v_mov_b32_e32 v118, v0
	v_mov_b32_e32 v119, v0
	v_mov_b32_e32 v120, v0
	v_mov_b32_e32 v121, v0
	v_mov_b32_e32 v122, v0
	v_mov_b32_e32 v123, v0
	v_mov_b32_e32 v124, v0
	v_mov_b32_e32 v125, v0
	v_mov_b32_e32 v126, v0
	v_mov_b32_e32 v127, v0
	s_mov_b64 s[26:27], 0xe450080
	v_readlane_b32 s46, v252, 2
	v_readlane_b32 s47, v252, 3
	v_mov_b32_e32 v188, 0
	v_mov_b32_e32 v189, 0
	v_mov_b32_e32 v190, 0
	v_mov_b32_e32 v191, 0
	v_mov_b32_e32 v192, 0
	v_mov_b32_e32 v193, 0
	v_mov_b32_e32 v194, 0
	v_mov_b32_e32 v195, 0
	v_mov_b32_e32 v196, 0
	v_mov_b32_e32 v197, 0
	v_mov_b32_e32 v198, 0
	v_mov_b32_e32 v199, 0
	v_mov_b32_e32 v200, 0
	v_mov_b32_e32 v201, 0
	v_mov_b32_e32 v202, 0
	v_mov_b32_e32 v203, 0
	v_mov_b32_e32 v204, 0
	v_mov_b32_e32 v205, 0
	v_mov_b32_e32 v206, 0
	v_mov_b32_e32 v207, 0
	v_mov_b32_e32 v208, 0
	v_mov_b32_e32 v209, 0
	v_mov_b32_e32 v210, 0
	v_mov_b32_e32 v211, 0
	v_mov_b32_e32 v228, 0
	v_mov_b32_e32 v229, 0
	v_mov_b32_e32 v230, 0
	v_mov_b32_e32 v231, 0
	v_mov_b32_e32 v232, 0
	v_mov_b32_e32 v233, 0
	v_mov_b32_e32 v234, 0
	v_mov_b32_e32 v235, 0
	v_lshrrev_b32_e32 v240, 8, v212
	s_nop 0
	v_readfirstlane_b32 s98, v240
	s_cmp_eq_u32 s98, 0
	s_cbranch_scc1 .Lprio_1
	s_setprio 1
; #define MFMA16(a, b, c) __builtin_amdgcn_mfma_f32_16x16x32_bf16((a), (b), (c), 0, 0, 0)
; DI void glds16(const void* g, unsigned char* l) { __builtin_amdgcn_global_load_lds((const unsigned*)g, (lds_u32*)l, 16, 0, 0); }
; template <int N> DI void wait_vm() { asm volatile("s_waitcnt vmcnt(%0)" :: "n"(N) : "memory"); }
;     ...
;   for (int kt = 0; kt < nk; ++kt) {
;     wait_vm<0>();
;     __builtin_amdgcn_s_barrier();
;     if (kt + 1 < nk) {
;       unsigned char* sn = smem + ((kt + 1) & 1) * STG;
;       const int ko = (kt + 1) * 64;
; #pragma unroll
;       for (int i = 0; i < NA; ++i) glds16(Ab + ((size_t)i * 128 * lda + ko * 2) + voA, sn + (i * 512 + tid) * 16);
; #pragma unroll
;       for (int i = 0; i < NB; ++i) glds16(Bb + ((size_t)i * 128 * ldb + ko * 2) + voB, sn + AB + (i * 512 + tid) * 16);
;     } else if (nA) {
;       const unsigned nvoA = (unsigned)(srow * nlda + kch * 8) * 2u, nvoB = (unsigned)(srow * nldb + kch * 8) * 2u;
; #pragma unroll
;       for (int i = 0; i < NA; ++i) glds16((const char*)nA + (size_t)i * 128 * nlda + nvoA, smem + (i * 512 + tid) * 16);
; #pragma unroll
;       for (int i = 0; i < NB; ++i) glds16((const char*)nB + (size_t)i * 128 * nldb + nvoB, smem + AB + (i * 512 + tid) * 16);
;     }
;     const unsigned stb = lds_base + (kt & 1) * STG;
; #pragma unroll
;     for (int ks = 0; ks < 2; ++ks) {
;       const unsigned co = ((ks * 4 + fq) ^ sw) * 16;
;       const unsigned sa = stb + a_row + co, sb = stb + b_row + co;
;       bf16x8 af[4], bfr[NT];
; #pragma unroll
;       for (int n = 0; n < NT; ++n) asm volatile("ds_read_b128 %0, %1 offset:%2" : "=v"(bfr[n]) : "v"(sb), "n"(n * 2048) : "memory");
; #pragma unroll
;       for (int mg = 0; mg < MT / 4; ++mg) {
; #pragma unroll
;         for (int m = 0; m < 4; ++m) asm volatile("ds_read_b128 %0, %1 offset:%2" : "=v"(af[m]) : "v"(sa), "n"((mg * 4 + m) * 2048) : "memory");
;         if (mg == 0) {
; #pragma unroll
;           for (int n = 0; n < NT; ++n) asm volatile("s_waitcnt lgkmcnt(%1)" : "+v"(bfr[n]) : "n"(4 + NT - 1 - n) : "memory");
;         }
; #pragma unroll
;         for (int m = 0; m < 4; ++m) {
;           asm volatile("s_waitcnt lgkmcnt(%1)" : "+v"(af[m]) : "n"(3 - m) : "memory");
; #pragma unroll
;           for (int n = 0; n < NT; ++n) acc[mg * 4 + m][n] = MFMA16(bfr[n], af[m], acc[mg * 4 + m][n]);
;         }
;       }
.Lprio_1:
.LBB0_202:
	s_add_i32 s14, s15, 0x10000
	s_and_b32 s16, s14, 0x10000
	v_add_u32_e32 v143, s16, v133
	v_lshl_add_u64 v[144:145], v[136:137], 0, s[44:45]
	v_readfirstlane_b32 s16, v143
	v_add_u32_e32 v148, 0x2000, v143
	v_lshl_add_u64 v[146:147], v[144:145], 0, s[96:97]
	s_mov_b32 m0, s16
	v_readfirstlane_b32 s16, v148
	v_add_u32_e32 v148, 0x4000, v143
	s_waitcnt vmcnt(0)
	s_waitcnt lgkmcnt(0)
	s_barrier
	s_and_b32 s15, s15, 0x10000
	v_add_u32_e32 v240, s15, v142
	v_add_u32_e32 v236, v240, v140
	v_add_u32_e32 v237, v240, v131
	v_add_u32_e32 v240, s15, v141
	v_add_u32_e32 v238, v240, v140
	v_add_u32_e32 v239, v240, v131
	v_mfma_f32_16x16x32_bf16 v[60:63], v[188:191], v[204:207], v[60:63]
	ds_read_b128 v[152:155], v236 offset:0
	ds_read_b128 v[156:159], v236 offset:2048
	v_mfma_f32_16x16x32_bf16 v[56:59], v[192:195], v[204:207], v[56:59]
	ds_read_b128 v[160:163], v236 offset:4096
	ds_read_b128 v[164:167], v236 offset:6144
	global_load_lds_dwordx4 v[146:147], off
	v_mfma_f32_16x16x32_bf16 v[52:55], v[196:199], v[204:207], v[52:55]
	ds_read_b128 v[168:171], v238 offset:0
	ds_read_b128 v[172:175], v238 offset:2048
	v_mfma_f32_16x16x32_bf16 v[48:51], v[200:203], v[204:207], v[48:51]
	ds_read_b128 v[180:183], v238 offset:4096
	ds_read_b128 v[184:187], v238 offset:6144
	v_mfma_f32_16x16x32_bf16 v[44:47], v[188:191], v[208:211], v[44:47]
	v_mfma_f32_16x16x32_bf16 v[40:43], v[192:195], v[208:211], v[40:43]
	v_mfma_f32_16x16x32_bf16 v[36:39], v[196:199], v[208:211], v[36:39]
	v_lshl_add_u64 v[146:147], v[144:145], 0, s[78:79]
	s_mov_b32 m0, s16
	v_readfirstlane_b32 s16, v148
	global_load_lds_dwordx4 v[146:147], off
	v_mfma_f32_16x16x32_bf16 v[32:35], v[200:203], v[208:211], v[32:35]
	v_mfma_f32_16x16x32_bf16 v[28:31], v[188:191], v[228:231], v[28:31]
	v_mfma_f32_16x16x32_bf16 v[24:27], v[192:195], v[228:231], v[24:27]
	v_mfma_f32_16x16x32_bf16 v[20:23], v[196:199], v[228:231], v[20:23]
	v_mfma_f32_16x16x32_bf16 v[16:19], v[200:203], v[228:231], v[16:19]
	v_lshl_add_u64 v[146:147], v[144:145], 0, s[50:51]
	s_mov_b32 m0, s16
	v_lshl_add_u64 v[144:145], v[144:145], 0, s[26:27]
	global_load_lds_dwordx4 v[146:147], off
	v_mfma_f32_16x16x32_bf16 v[12:15], v[188:191], v[232:235], v[12:15]
	v_mfma_f32_16x16x32_bf16 v[8:11], v[192:195], v[232:235], v[8:11]
	v_mfma_f32_16x16x32_bf16 v[4:7], v[196:199], v[232:235], v[4:7]
	v_mfma_f32_16x16x32_bf16 v[0:3], v[200:203], v[232:235], v[0:3]
	s_waitcnt lgkmcnt(3)
	v_mfma_f32_16x16x32_bf16 v[124:127], v[152:155], v[168:171], v[124:127]
	v_add_u32_e32 v146, 0x6000, v143
	v_add_u32_e32 v148, 0x8000, v143
	v_readfirstlane_b32 s16, v146
	s_mov_b32 m0, s16
	s_mov_b64 s[16:17], 0xb08080
	global_load_lds_dwordx4 v[144:145], off
	v_mfma_f32_16x16x32_bf16 v[120:123], v[156:159], v[168:171], v[120:123]
	ds_read_b128 v[204:207], v238 offset:8192
	v_mfma_f32_16x16x32_bf16 v[116:119], v[160:163], v[168:171], v[116:119]
	v_mfma_f32_16x16x32_bf16 v[112:115], v[164:167], v[168:171], v[112:115]
	ds_read_b128 v[208:211], v238 offset:10240
	s_waitcnt lgkmcnt(4)
	v_mfma_f32_16x16x32_bf16 v[108:111], v[152:155], v[172:175], v[108:111]
	v_mfma_f32_16x16x32_bf16 v[104:107], v[156:159], v[172:175], v[104:107]
	ds_read_b128 v[228:231], v238 offset:12288
	v_lshl_add_u64 v[144:145], v[138:139], 0, s[44:45]
	v_lshl_add_u64 v[146:147], v[144:145], 0, s[16:17]
	v_readfirstlane_b32 s16, v148
	s_mov_b32 m0, s16
	s_mov_b64 s[16:17], 0xb60080
	v_add_u32_e32 v148, 0xa000, v143
	global_load_lds_dwordx4 v[146:147], off
	v_mfma_f32_16x16x32_bf16 v[100:103], v[160:163], v[172:175], v[100:103]
	v_mfma_f32_16x16x32_bf16 v[96:99], v[164:167], v[172:175], v[96:99]
	ds_read_b128 v[232:235], v238 offset:14336
	s_waitcnt lgkmcnt(5)
	v_mfma_f32_16x16x32_bf16 v[92:95], v[152:155], v[180:183], v[92:95]
	v_mfma_f32_16x16x32_bf16 v[88:91], v[156:159], v[180:183], v[88:91]
	ds_read_b128 v[188:191], v237 offset:0
	v_mfma_f32_16x16x32_bf16 v[84:87], v[160:163], v[180:183], v[84:87]
	v_lshl_add_u64 v[146:147], v[144:145], 0, s[16:17]
	v_readfirstlane_b32 s16, v148
	s_mov_b32 m0, s16
	s_mov_b64 s[16:17], 0xbb8080
	v_add_u32_e32 v148, 0xc000, v143
	global_load_lds_dwordx4 v[146:147], off
	v_mfma_f32_16x16x32_bf16 v[80:83], v[164:167], v[180:183], v[80:83]
	ds_read_b128 v[192:195], v237 offset:2048
	s_waitcnt lgkmcnt(6)
	v_mfma_f32_16x16x32_bf16 v[76:79], v[152:155], v[184:187], v[76:79]
	v_mfma_f32_16x16x32_bf16 v[72:75], v[156:159], v[184:187], v[72:75]
	ds_read_b128 v[196:199], v237 offset:4096
	v_mfma_f32_16x16x32_bf16 v[68:71], v[160:163], v[184:187], v[68:71]
	v_mfma_f32_16x16x32_bf16 v[64:67], v[164:167], v[184:187], v[64:67]
	ds_read_b128 v[200:203], v237 offset:6144
	v_lshl_add_u64 v[146:147], v[144:145], 0, s[16:17]
	v_readfirstlane_b32 s16, v148
	s_mov_b32 m0, s16
	s_mov_b64 s[16:17], 0xc10080
	v_add_u32_e32 v143, 0xe000, v143
	v_lshl_add_u64 v[144:145], v[144:145], 0, s[16:17]
	v_readfirstlane_b32 s16, v143
	global_load_lds_dwordx4 v[146:147], off
	s_waitcnt lgkmcnt(7)
	v_mfma_f32_16x16x32_bf16 v[60:63], v[152:155], v[204:207], v[60:63]
	v_mfma_f32_16x16x32_bf16 v[56:59], v[156:159], v[204:207], v[56:59]
	ds_read_b128 v[168:171], v239 offset:0
	v_mfma_f32_16x16x32_bf16 v[52:55], v[160:163], v[204:207], v[52:55]
	v_mfma_f32_16x16x32_bf16 v[48:51], v[164:167], v[204:207], v[48:51]
	ds_read_b128 v[172:175], v239 offset:2048
	s_waitcnt lgkmcnt(8)
; #define MFMA16(a, b, c) __builtin_amdgcn_mfma_f32_16x16x32_bf16((a), (b), (c), 0, 0, 0)
; DI void glds16(const void* g, unsigned char* l) { __builtin_amdgcn_global_load_lds((const unsigned*)g, (lds_u32*)l, 16, 0, 0); }
; template <int N> DI void wait_vm() { asm volatile("s_waitcnt vmcnt(%0)" :: "n"(N) : "memory"); }
;     ...
;   for (int kt = 0; kt < nk; ++kt) {
;     wait_vm<0>();
;     __builtin_amdgcn_s_barrier();
;     if (kt + 1 < nk) {
;       unsigned char* sn = smem + ((kt + 1) & 1) * STG;
;       const int ko = (kt + 1) * 64;
; #pragma unroll
;       for (int i = 0; i < NA; ++i) glds16(Ab + ((size_t)i * 128 * lda + ko * 2) + voA, sn + (i * 512 + tid) * 16);
; #pragma unroll
;       for (int i = 0; i < NB; ++i) glds16(Bb + ((size_t)i * 128 * ldb + ko * 2) + voB, sn + AB + (i * 512 + tid) * 16);
;     } else if (nA) {
;       const unsigned nvoA = (unsigned)(srow * nlda + kch * 8) * 2u, nvoB = (unsigned)(srow * nldb + kch * 8) * 2u;
; #pragma unroll
;       for (int i = 0; i < NA; ++i) glds16((const char*)nA + (size_t)i * 128 * nlda + nvoA, smem + (i * 512 + tid) * 16);
; #pragma unroll
;       for (int i = 0; i < NB; ++i) glds16((const char*)nB + (size_t)i * 128 * nldb + nvoB, smem + AB + (i * 512 + tid) * 16);
;     }
;     const unsigned stb = lds_base + (kt & 1) * STG;
; #pragma unroll
;     for (int ks = 0; ks < 2; ++ks) {
;       const unsigned co = ((ks * 4 + fq) ^ sw) * 16;
;       const unsigned sa = stb + a_row + co, sb = stb + b_row + co;
;       bf16x8 af[4], bfr[NT];
; #pragma unroll
;       for (int n = 0; n < NT; ++n) asm volatile("ds_read_b128 %0, %1 offset:%2" : "=v"(bfr[n]) : "v"(sb), "n"(n * 2048) : "memory");
; #pragma unroll
;       for (int mg = 0; mg < MT / 4; ++mg) {
; #pragma unroll
;         for (int m = 0; m < 4; ++m) asm volatile("ds_read_b128 %0, %1 offset:%2" : "=v"(af[m]) : "v"(sa), "n"((mg * 4 + m) * 2048) : "memory");
;         if (mg == 0) {
; #pragma unroll
;           for (int n = 0; n < NT; ++n) asm volatile("s_waitcnt lgkmcnt(%1)" : "+v"(bfr[n]) : "n"(4 + NT - 1 - n) : "memory");
;         }
; #pragma unroll
;         for (int m = 0; m < 4; ++m) {
;           asm volatile("s_waitcnt lgkmcnt(%1)" : "+v"(af[m]) : "n"(3 - m) : "memory");
; #pragma unroll
;           for (int n = 0; n < NT; ++n) acc[mg * 4 + m][n] = MFMA16(bfr[n], af[m], acc[mg * 4 + m][n]);
;         }
;       }
;     }
	v_mfma_f32_16x16x32_bf16 v[44:47], v[152:155], v[208:211], v[44:47]
	s_mov_b32 m0, s16
	s_nop 0
	global_load_lds_dwordx4 v[144:145], off
	v_mfma_f32_16x16x32_bf16 v[40:43], v[156:159], v[208:211], v[40:43]
	ds_read_b128 v[180:183], v239 offset:4096
	v_mfma_f32_16x16x32_bf16 v[36:39], v[160:163], v[208:211], v[36:39]
	v_mfma_f32_16x16x32_bf16 v[32:35], v[164:167], v[208:211], v[32:35]
	ds_read_b128 v[184:187], v239 offset:6144
	s_waitcnt lgkmcnt(9)
	v_mfma_f32_16x16x32_bf16 v[28:31], v[152:155], v[228:231], v[28:31]
	v_mfma_f32_16x16x32_bf16 v[24:27], v[156:159], v[228:231], v[24:27]
	v_mfma_f32_16x16x32_bf16 v[20:23], v[160:163], v[228:231], v[20:23]
	v_mfma_f32_16x16x32_bf16 v[16:19], v[164:167], v[228:231], v[16:19]
	s_waitcnt lgkmcnt(8)
	v_mfma_f32_16x16x32_bf16 v[12:15], v[152:155], v[232:235], v[12:15]
	v_mfma_f32_16x16x32_bf16 v[8:11], v[156:159], v[232:235], v[8:11]
	v_mfma_f32_16x16x32_bf16 v[4:7], v[160:163], v[232:235], v[4:7]
	v_mfma_f32_16x16x32_bf16 v[0:3], v[164:167], v[232:235], v[0:3]
	s_waitcnt lgkmcnt(3)
	v_mfma_f32_16x16x32_bf16 v[124:127], v[188:191], v[168:171], v[124:127]
	v_mfma_f32_16x16x32_bf16 v[120:123], v[192:195], v[168:171], v[120:123]
	ds_read_b128 v[204:207], v239 offset:8192
	v_mfma_f32_16x16x32_bf16 v[116:119], v[196:199], v[168:171], v[116:119]
	v_mfma_f32_16x16x32_bf16 v[112:115], v[200:203], v[168:171], v[112:115]
	ds_read_b128 v[208:211], v239 offset:10240
	s_waitcnt lgkmcnt(4)
	v_mfma_f32_16x16x32_bf16 v[108:111], v[188:191], v[172:175], v[108:111]
	v_mfma_f32_16x16x32_bf16 v[104:107], v[192:195], v[172:175], v[104:107]
	ds_read_b128 v[228:231], v239 offset:12288
	v_mfma_f32_16x16x32_bf16 v[100:103], v[196:199], v[172:175], v[100:103]
	v_mfma_f32_16x16x32_bf16 v[96:99], v[200:203], v[172:175], v[96:99]
	ds_read_b128 v[232:235], v239 offset:14336
	s_waitcnt lgkmcnt(5)
	v_mfma_f32_16x16x32_bf16 v[92:95], v[188:191], v[180:183], v[92:95]
	v_mfma_f32_16x16x32_bf16 v[88:91], v[192:195], v[180:183], v[88:91]
	v_mfma_f32_16x16x32_bf16 v[84:87], v[196:199], v[180:183], v[84:87]
	v_mfma_f32_16x16x32_bf16 v[80:83], v[200:203], v[180:183], v[80:83]
	s_waitcnt lgkmcnt(4)
	v_mfma_f32_16x16x32_bf16 v[76:79], v[188:191], v[184:187], v[76:79]
	v_mfma_f32_16x16x32_bf16 v[72:75], v[192:195], v[184:187], v[72:75]
	v_mfma_f32_16x16x32_bf16 v[68:71], v[196:199], v[184:187], v[68:71]
	v_mfma_f32_16x16x32_bf16 v[64:67], v[200:203], v[184:187], v[64:67]
	s_add_u32 s44, s44, 0x80
	s_addc_u32 s45, s45, 0
	s_cmpk_eq_i32 s44, 0x1580
	s_mov_b32 s15, s14
	s_cbranch_scc0 .LBB0_202
	s_waitcnt lgkmcnt(0)
	v_mfma_f32_16x16x32_bf16 v[60:63], v[188:191], v[204:207], v[60:63]
	v_mfma_f32_16x16x32_bf16 v[56:59], v[192:195], v[204:207], v[56:59]
	v_mfma_f32_16x16x32_bf16 v[52:55], v[196:199], v[204:207], v[52:55]
	v_mfma_f32_16x16x32_bf16 v[48:51], v[200:203], v[204:207], v[48:51]
	v_mfma_f32_16x16x32_bf16 v[44:47], v[188:191], v[208:211], v[44:47]
	v_mfma_f32_16x16x32_bf16 v[40:43], v[192:195], v[208:211], v[40:43]
	v_mfma_f32_16x16x32_bf16 v[36:39], v[196:199], v[208:211], v[36:39]
	v_mfma_f32_16x16x32_bf16 v[32:35], v[200:203], v[208:211], v[32:35]
	v_mfma_f32_16x16x32_bf16 v[28:31], v[188:191], v[228:231], v[28:31]
	v_mfma_f32_16x16x32_bf16 v[24:27], v[192:195], v[228:231], v[24:27]
	v_mfma_f32_16x16x32_bf16 v[20:23], v[196:199], v[228:231], v[20:23]
	v_mfma_f32_16x16x32_bf16 v[16:19], v[200:203], v[228:231], v[16:19]
	v_mfma_f32_16x16x32_bf16 v[12:15], v[188:191], v[232:235], v[12:15]
	v_mfma_f32_16x16x32_bf16 v[8:11], v[192:195], v[232:235], v[8:11]
	v_mfma_f32_16x16x32_bf16 v[4:7], v[196:199], v[232:235], v[4:7]
	v_mfma_f32_16x16x32_bf16 v[0:3], v[200:203], v[232:235], v[0:3]
	s_setprio 0
	s_waitcnt vmcnt(0)
	s_andn2_b64 vcc, exec, s[12:13]
	s_mov_b32 s23, 0x10000
	s_barrier
	s_cbranch_vccnz .LBB0_205
	s_lshl_b64 s[10:11], s[10:11], 1
	s_add_u32 s12, s52, s10
	s_addc_u32 s13, s53, s11
	s_and_b64 s[10:11], exec, s[38:39]
	s_cselect_b32 s11, 0, s13
	s_cselect_b32 s10, 0, s12
	s_lshl_b64 s[12:13], s[42:43], 1
	s_add_u32 s12, s18, s12
	s_addc_u32 s13, s19, s13
	v_lshl_add_u64 v[136:137], s[10:11], 0, v[128:129]
	v_lshl_add_u64 v[138:139], s[12:13], 0, v[128:129]
	s_mov_b64 s[10:11], 0xb0000
	v_lshl_add_u64 v[144:145], v[136:137], 0, s[10:11]
	v_lshl_add_u64 v[146:147], v[138:139], 0, s[10:11]
	s_mov_b64 s[10:11], 0x58000
	v_lshl_add_u64 v[150:151], v[138:139], 0, s[10:11]
	v_lshl_add_u64 v[154:155], v[136:137], 0, s[10:11]
	v_readfirstlane_b32 s10, v133
	s_mov_b64 s[12:13], 0x108000
	s_mov_b32 m0, s10
	v_lshl_add_u64 v[152:153], v[136:137], 0, s[12:13]
	global_load_lds_dwordx4 v[136:137], off
	v_add_u32_e32 v136, 0x2000, v133
	v_add_u32_e32 v143, 0x4000, v133
	v_readfirstlane_b32 s10, v136
	s_mov_b32 m0, s10
	v_readfirstlane_b32 s10, v143
	v_add_u32_e32 v136, 0x6000, v133
	global_load_lds_dwordx4 v[154:155], off
	s_mov_b32 m0, s10
	v_readfirstlane_b32 s10, v136
	v_add_u32_e32 v136, 0x8000, v133
	global_load_lds_dwordx4 v[144:145], off
	s_mov_b32 m0, s10
	v_readfirstlane_b32 s10, v136
	v_add_u32_e32 v136, 0xa000, v133
	v_add_u32_e32 v128, 0xc000, v133
	global_load_lds_dwordx4 v[152:153], off
	s_mov_b32 m0, s10
	v_readfirstlane_b32 s10, v136
	global_load_lds_dwordx4 v[138:139], off
	s_mov_b32 m0, s10
	v_readfirstlane_b32 s10, v128
	v_add_u32_e32 v128, 0xe000, v133
	global_load_lds_dwordx4 v[150:151], off
	s_mov_b32 m0, s10
	v_readfirstlane_b32 s10, v128
	v_lshl_add_u64 v[148:149], v[138:139], 0, s[12:13]
	global_load_lds_dwordx4 v[146:147], off
	s_mov_b32 m0, s10
	s_nop 0
	global_load_lds_dwordx4 v[148:149], off

; DI int otid() { int t = threadIdx.x; asm volatile("" : "+v"(t)); return t; }
; DI void glds16(const void* g, unsigned char* l) { __builtin_amdgcn_global_load_lds((const unsigned*)g, (lds_u32*)l, 16, 0, 0); }
;     ...
;   const int tid = otid(), lane = tid & 63, w = tid >> 6, wr = w / WC, wc = w % WC, fr = lane & 15, fq = lane >> 4;
;   const int srow = tid >> 3, kch = (tid & 7) ^ ((tid >> 4) & 7);
;   const unsigned voA = (unsigned)(srow * lda + kch * 8) * 2u, voB = (unsigned)(srow * ldb + kch * 8) * 2u;
;   const char* Ab = (const char*)A;
;   const char* Bb = (const char*)B;
;   const int nk = K >> 6;
;   if (!primed) {
; #pragma unroll
;     for (int i = 0; i < NA; ++i) glds16(Ab + (size_t)i * 128 * lda + voA, smem + (i * 512 + tid) * 16);
; #pragma unroll
;     for (int i = 0; i < NB; ++i) glds16(Bb + (size_t)i * 128 * ldb + voB, smem + AB + (i * 512 + tid) * 16);
;   }
;   const int sw = (fr >> 1) & 7;
;   const unsigned lds_base = (unsigned)(size_t)(__attribute__((address_space(3))) unsigned char*)smem;
;   const unsigned a_row = (wr * 16 * MT + fr) * 128, b_row = AB + (wc * 16 * NT + fr) * 128;
; template <int MT, int NT>
; DI void zero_acc(f32x4 (&acc)[MT][NT]) {
; #pragma unroll
;   for (int m = 0; m < MT; ++m)
; #pragma unroll
;     for (int n = 0; n < NT; ++n) acc[m][n] = (f32x4){0.f, 0.f, 0.f, 0.f};
; }
.LBB0_334:
	v_ashrrev_i32_e32 v1, 6, v0
	v_lshrrev_b32_e32 v5, 30, v1
	v_add_u32_e32 v5, v1, v5
	v_ashrrev_i32_e32 v5, 2, v5
	s_add_i32 s16, s20, s21
	v_mul_i32_i24_e32 v6, 4, v5
	v_bfe_u32 v7, v0, 1, 3
	v_lshlrev_b32_e32 v0, 7, v0
	s_ashr_i32 s17, s16, 31
	v_sub_u32_e32 v1, v1, v6
	v_and_b32_e32 v0, 0x780, v0
	s_lshl_b64 s[16:17], s[16:17], 19
	v_readlane_b32 s20, v252, 0
	v_lshl_or_b32 v142, v5, 14, v0
	v_lshl_or_b32 v0, v1, 13, v0
	v_readlane_b32 s21, v252, 1
	s_add_u32 s16, s20, s16
	v_and_b32_e32 v6, 3, v4
	v_add_u32_e32 v143, 0x8000, v0
	v_bitop3_b32 v0, v4, v7, 3 bitop3:0x6c
	s_addc_u32 s17, s21, s17
	v_lshlrev_b32_e32 v141, 4, v0
	v_bitop3_b32 v0, v6, v7, 4 bitop3:0x36
	s_add_u32 s14, s2, s14
	v_lshlrev_b32_e32 v131, 4, v0
	v_add_u32_e32 v0, v2, v3
	v_mov_b32_e32 v1, v129
	s_addc_u32 s15, s18, s15
	v_lshl_add_u64 v[136:137], s[16:17], 0, v[0:1]
	v_lshl_add_u64 v[138:139], s[14:15], 0, v[0:1]
	v_mov_b32_e32 v0, 0
	s_mov_b32 s14, 0
	s_mov_b64 s[42:43], 0
	v_mov_b32_e32 v1, v0
	v_mov_b32_e32 v2, v0
	v_mov_b32_e32 v3, v0
	v_mov_b32_e32 v4, v0
	v_mov_b32_e32 v5, v0
	v_mov_b32_e32 v6, v0
	v_mov_b32_e32 v7, v0
	v_mov_b32_e32 v8, v0
	v_mov_b32_e32 v9, v0
	v_mov_b32_e32 v10, v0
	v_mov_b32_e32 v11, v0
	v_mov_b32_e32 v12, v0
	v_mov_b32_e32 v13, v0
	v_mov_b32_e32 v14, v0
	v_mov_b32_e32 v15, v0
	v_mov_b32_e32 v16, v0
	v_mov_b32_e32 v17, v0
	v_mov_b32_e32 v18, v0
	v_mov_b32_e32 v19, v0
	v_mov_b32_e32 v20, v0
	v_mov_b32_e32 v21, v0
	v_mov_b32_e32 v22, v0
	v_mov_b32_e32 v23, v0
	v_mov_b32_e32 v24, v0
	v_mov_b32_e32 v25, v0
	v_mov_b32_e32 v26, v0
	v_mov_b32_e32 v27, v0
	v_mov_b32_e32 v28, v0
	v_mov_b32_e32 v29, v0
	v_mov_b32_e32 v30, v0
	v_mov_b32_e32 v31, v0
	v_mov_b32_e32 v32, v0
	v_mov_b32_e32 v33, v0
	v_mov_b32_e32 v34, v0
	v_mov_b32_e32 v35, v0
	v_mov_b32_e32 v36, v0
	v_mov_b32_e32 v37, v0
	v_mov_b32_e32 v38, v0
	v_mov_b32_e32 v39, v0
	v_mov_b32_e32 v40, v0
	v_mov_b32_e32 v41, v0
	v_mov_b32_e32 v42, v0
	v_mov_b32_e32 v43, v0
	v_mov_b32_e32 v44, v0
	v_mov_b32_e32 v45, v0
	v_mov_b32_e32 v46, v0
	v_mov_b32_e32 v47, v0
	v_mov_b32_e32 v48, v0
	v_mov_b32_e32 v49, v0
	v_mov_b32_e32 v50, v0
	v_mov_b32_e32 v51, v0
	v_mov_b32_e32 v52, v0
	v_mov_b32_e32 v53, v0
	v_mov_b32_e32 v54, v0
	v_mov_b32_e32 v55, v0
	v_mov_b32_e32 v56, v0
	v_mov_b32_e32 v57, v0
	v_mov_b32_e32 v58, v0
	v_mov_b32_e32 v59, v0
	v_mov_b32_e32 v60, v0
	v_mov_b32_e32 v61, v0
	v_mov_b32_e32 v62, v0
	v_mov_b32_e32 v63, v0
	v_mov_b32_e32 v64, v0
	v_mov_b32_e32 v65, v0
	v_mov_b32_e32 v66, v0
	v_mov_b32_e32 v67, v0
	v_mov_b32_e32 v68, v0
	v_mov_b32_e32 v69, v0
	v_mov_b32_e32 v70, v0
	v_mov_b32_e32 v71, v0
	v_mov_b32_e32 v72, v0
	v_mov_b32_e32 v73, v0
	v_mov_b32_e32 v74, v0
	v_mov_b32_e32 v75, v0
	v_mov_b32_e32 v76, v0
	v_mov_b32_e32 v77, v0
	v_mov_b32_e32 v78, v0
	v_mov_b32_e32 v79, v0
	v_mov_b32_e32 v80, v0
	v_mov_b32_e32 v81, v0
	v_mov_b32_e32 v82, v0
	v_mov_b32_e32 v83, v0
	v_mov_b32_e32 v84, v0
	v_mov_b32_e32 v85, v0
	v_mov_b32_e32 v86, v0
	v_mov_b32_e32 v87, v0
	v_mov_b32_e32 v88, v0
	v_mov_b32_e32 v89, v0
	v_mov_b32_e32 v90, v0
	v_mov_b32_e32 v91, v0
	v_mov_b32_e32 v92, v0
	v_mov_b32_e32 v93, v0
	v_mov_b32_e32 v94, v0
	v_mov_b32_e32 v95, v0
	v_mov_b32_e32 v96, v0
	v_mov_b32_e32 v97, v0
	v_mov_b32_e32 v98, v0
	v_mov_b32_e32 v99, v0
	v_mov_b32_e32 v100, v0
	v_mov_b32_e32 v101, v0
	v_mov_b32_e32 v102, v0
	v_mov_b32_e32 v103, v0
	v_mov_b32_e32 v104, v0
	v_mov_b32_e32 v105, v0
	v_mov_b32_e32 v106, v0
	v_mov_b32_e32 v107, v0
	v_mov_b32_e32 v108, v0
	v_mov_b32_e32 v109, v0
	v_mov_b32_e32 v110, v0
	v_mov_b32_e32 v111, v0
	v_mov_b32_e32 v112, v0
	v_mov_b32_e32 v113, v0
	v_mov_b32_e32 v114, v0
	v_mov_b32_e32 v115, v0
	v_mov_b32_e32 v116, v0
	v_mov_b32_e32 v117, v0
	v_mov_b32_e32 v118, v0
	v_mov_b32_e32 v119, v0
	v_mov_b32_e32 v120, v0
	v_mov_b32_e32 v121, v0
	v_mov_b32_e32 v122, v0
	v_mov_b32_e32 v123, v0
	v_mov_b32_e32 v124, v0
	v_mov_b32_e32 v125, v0
	v_mov_b32_e32 v126, v0
	v_mov_b32_e32 v127, v0
	v_readlane_b32 s22, v252, 2
	v_readlane_b32 s23, v252, 3
	v_mov_b32_e32 v188, 0
	v_mov_b32_e32 v189, 0
	v_mov_b32_e32 v190, 0
	v_mov_b32_e32 v191, 0
	v_mov_b32_e32 v192, 0
	v_mov_b32_e32 v193, 0
	v_mov_b32_e32 v194, 0
	v_mov_b32_e32 v195, 0
	v_mov_b32_e32 v196, 0
	v_mov_b32_e32 v197, 0
	v_mov_b32_e32 v198, 0
	v_mov_b32_e32 v199, 0
	v_mov_b32_e32 v200, 0
	v_mov_b32_e32 v201, 0
	v_mov_b32_e32 v202, 0
	v_mov_b32_e32 v203, 0
	v_mov_b32_e32 v204, 0
	v_mov_b32_e32 v205, 0
	v_mov_b32_e32 v206, 0
	v_mov_b32_e32 v207, 0
	v_mov_b32_e32 v208, 0
	v_mov_b32_e32 v209, 0
	v_mov_b32_e32 v210, 0
	v_mov_b32_e32 v211, 0
	v_mov_b32_e32 v228, 0
	v_mov_b32_e32 v229, 0
	v_mov_b32_e32 v230, 0
	v_mov_b32_e32 v231, 0
	v_mov_b32_e32 v232, 0
	v_mov_b32_e32 v233, 0
	v_mov_b32_e32 v234, 0
	v_mov_b32_e32 v235, 0
	v_lshrrev_b32_e32 v240, 8, v212
	s_nop 0
	v_readfirstlane_b32 s98, v240
	s_cmp_eq_u32 s98, 0
	s_cbranch_scc1 .Lprio_2
	s_setprio 1
; #define MFMA16(a, b, c) __builtin_amdgcn_mfma_f32_16x16x32_bf16((a), (b), (c), 0, 0, 0)
; DI void glds16(const void* g, unsigned char* l) { __builtin_amdgcn_global_load_lds((const unsigned*)g, (lds_u32*)l, 16, 0, 0); }
; template <int N> DI void wait_vm() { asm volatile("s_waitcnt vmcnt(%0)" :: "n"(N) : "memory"); }
;     ...
;   for (int kt = 0; kt < nk; ++kt) {
;     wait_vm<0>();
;     __builtin_amdgcn_s_barrier();
;     if (kt + 1 < nk) {
;       unsigned char* sn = smem + ((kt + 1) & 1) * STG;
;       const int ko = (kt + 1) * 64;
; #pragma unroll
;       for (int i = 0; i < NA; ++i) glds16(Ab + ((size_t)i * 128 * lda + ko * 2) + voA, sn + (i * 512 + tid) * 16);
; #pragma unroll
;       for (int i = 0; i < NB; ++i) glds16(Bb + ((size_t)i * 128 * ldb + ko * 2) + voB, sn + AB + (i * 512 + tid) * 16);
;     } else if (nA) {
;       const unsigned nvoA = (unsigned)(srow * nlda + kch * 8) * 2u, nvoB = (unsigned)(srow * nldb + kch * 8) * 2u;
; #pragma unroll
;       for (int i = 0; i < NA; ++i) glds16((const char*)nA + (size_t)i * 128 * nlda + nvoA, smem + (i * 512 + tid) * 16);
; #pragma unroll
;       for (int i = 0; i < NB; ++i) glds16((const char*)nB + (size_t)i * 128 * nldb + nvoB, smem + AB + (i * 512 + tid) * 16);
;     }
;     const unsigned stb = lds_base + (kt & 1) * STG;
; #pragma unroll
;     for (int ks = 0; ks < 2; ++ks) {
;       const unsigned co = ((ks * 4 + fq) ^ sw) * 16;
;       const unsigned sa = stb + a_row + co, sb = stb + b_row + co;
;       bf16x8 af[4], bfr[NT];
; #pragma unroll
;       for (int n = 0; n < NT; ++n) asm volatile("ds_read_b128 %0, %1 offset:%2" : "=v"(bfr[n]) : "v"(sb), "n"(n * 2048) : "memory");
; #pragma unroll
;       for (int mg = 0; mg < MT / 4; ++mg) {
; #pragma unroll
;         for (int m = 0; m < 4; ++m) asm volatile("ds_read_b128 %0, %1 offset:%2" : "=v"(af[m]) : "v"(sa), "n"((mg * 4 + m) * 2048) : "memory");
;         if (mg == 0) {
; #pragma unroll
;           for (int n = 0; n < NT; ++n) asm volatile("s_waitcnt lgkmcnt(%1)" : "+v"(bfr[n]) : "n"(4 + NT - 1 - n) : "memory");
;         }
; #pragma unroll
;         for (int m = 0; m < 4; ++m) {
;           asm volatile("s_waitcnt lgkmcnt(%1)" : "+v"(af[m]) : "n"(3 - m) : "memory");
; #pragma unroll
;           for (int n = 0; n < NT; ++n) acc[mg * 4 + m][n] = MFMA16(bfr[n], af[m], acc[mg * 4 + m][n]);
;         }
;       }
.Lprio_2:
.LBB0_335:
	s_add_i32 s5, s14, 0x10000
	s_and_b32 s15, s5, 0x10000
	v_add_u32_e32 v148, s15, v140
	v_lshl_add_u64 v[144:145], v[136:137], 0, s[42:43]
	v_readfirstlane_b32 s15, v148
	v_add_u32_e32 v149, 0x2000, v148
	v_lshl_add_u64 v[146:147], v[144:145], 0, s[58:59]
	s_mov_b32 m0, s15
	v_readfirstlane_b32 s15, v149
	v_add_u32_e32 v149, 0x4000, v148
	s_waitcnt vmcnt(0)
	s_waitcnt lgkmcnt(0)
	s_barrier
	s_and_b32 s14, s14, 0x10000
	v_add_u32_e32 v240, s14, v143
	v_add_u32_e32 v236, v240, v141
	v_add_u32_e32 v237, v240, v131
	v_add_u32_e32 v240, s14, v142
	v_add_u32_e32 v238, v240, v141
	v_add_u32_e32 v239, v240, v131
	v_mfma_f32_16x16x32_bf16 v[60:63], v[188:191], v[204:207], v[60:63]
	ds_read_b128 v[152:155], v236 offset:0
	ds_read_b128 v[156:159], v236 offset:2048
	v_mfma_f32_16x16x32_bf16 v[56:59], v[192:195], v[204:207], v[56:59]
	ds_read_b128 v[160:163], v236 offset:4096
	ds_read_b128 v[164:167], v236 offset:6144
	global_load_lds_dwordx4 v[146:147], off
	v_mfma_f32_16x16x32_bf16 v[52:55], v[196:199], v[204:207], v[52:55]
	ds_read_b128 v[168:171], v238 offset:0
	ds_read_b128 v[172:175], v238 offset:2048
	v_mfma_f32_16x16x32_bf16 v[48:51], v[200:203], v[204:207], v[48:51]
	ds_read_b128 v[180:183], v238 offset:4096
	ds_read_b128 v[184:187], v238 offset:6144
	v_mfma_f32_16x16x32_bf16 v[44:47], v[188:191], v[208:211], v[44:47]
	v_mfma_f32_16x16x32_bf16 v[40:43], v[192:195], v[208:211], v[40:43]
	v_mfma_f32_16x16x32_bf16 v[36:39], v[196:199], v[208:211], v[36:39]
	v_lshl_add_u64 v[146:147], v[144:145], 0, s[60:61]
	s_mov_b32 m0, s15
	v_readfirstlane_b32 s15, v149
	global_load_lds_dwordx4 v[146:147], off
	v_mfma_f32_16x16x32_bf16 v[32:35], v[200:203], v[208:211], v[32:35]
	v_mfma_f32_16x16x32_bf16 v[28:31], v[188:191], v[228:231], v[28:31]
	v_mfma_f32_16x16x32_bf16 v[24:27], v[192:195], v[228:231], v[24:27]
	v_mfma_f32_16x16x32_bf16 v[20:23], v[196:199], v[228:231], v[20:23]
	v_mfma_f32_16x16x32_bf16 v[16:19], v[200:203], v[228:231], v[16:19]
	v_lshl_add_u64 v[146:147], v[144:145], 0, s[62:63]
	s_mov_b32 m0, s15
	v_lshl_add_u64 v[144:145], v[144:145], 0, s[64:65]
	global_load_lds_dwordx4 v[146:147], off
	v_mfma_f32_16x16x32_bf16 v[12:15], v[188:191], v[232:235], v[12:15]
	v_mfma_f32_16x16x32_bf16 v[8:11], v[192:195], v[232:235], v[8:11]
	v_mfma_f32_16x16x32_bf16 v[4:7], v[196:199], v[232:235], v[4:7]
	v_mfma_f32_16x16x32_bf16 v[0:3], v[200:203], v[232:235], v[0:3]
	s_waitcnt lgkmcnt(3)
	v_mfma_f32_16x16x32_bf16 v[124:127], v[152:155], v[168:171], v[124:127]
	v_add_u32_e32 v146, 0x6000, v148
	v_add_u32_e32 v149, 0x8000, v148
	v_readfirstlane_b32 s15, v146
	s_mov_b32 m0, s15
	v_readfirstlane_b32 s15, v149
	global_load_lds_dwordx4 v[144:145], off
	v_mfma_f32_16x16x32_bf16 v[120:123], v[156:159], v[168:171], v[120:123]
	ds_read_b128 v[204:207], v238 offset:8192
	v_mfma_f32_16x16x32_bf16 v[116:119], v[160:163], v[168:171], v[116:119]
	v_mfma_f32_16x16x32_bf16 v[112:115], v[164:167], v[168:171], v[112:115]
	ds_read_b128 v[208:211], v238 offset:10240
	s_waitcnt lgkmcnt(4)
	v_mfma_f32_16x16x32_bf16 v[108:111], v[152:155], v[172:175], v[108:111]
	v_mfma_f32_16x16x32_bf16 v[104:107], v[156:159], v[172:175], v[104:107]
	ds_read_b128 v[228:231], v238 offset:12288
	v_lshl_add_u64 v[144:145], v[138:139], 0, s[42:43]
	v_add_u32_e32 v149, 0xa000, v148
	v_lshl_add_u64 v[146:147], v[144:145], 0, s[72:73]
	s_mov_b32 m0, s15
	v_readfirstlane_b32 s15, v149
	v_add_u32_e32 v149, 0xc000, v148
	global_load_lds_dwordx4 v[146:147], off
	v_mfma_f32_16x16x32_bf16 v[100:103], v[160:163], v[172:175], v[100:103]
	v_mfma_f32_16x16x32_bf16 v[96:99], v[164:167], v[172:175], v[96:99]
	ds_read_b128 v[232:235], v238 offset:14336
	s_waitcnt lgkmcnt(5)
	v_mfma_f32_16x16x32_bf16 v[92:95], v[152:155], v[180:183], v[92:95]
	v_mfma_f32_16x16x32_bf16 v[88:91], v[156:159], v[180:183], v[88:91]
	ds_read_b128 v[188:191], v237 offset:0
	v_mfma_f32_16x16x32_bf16 v[84:87], v[160:163], v[180:183], v[84:87]
	v_lshl_add_u64 v[146:147], v[144:145], 0, s[74:75]
	s_mov_b32 m0, s15
	s_mov_b64 s[16:17], 0x2148080
	v_readfirstlane_b32 s15, v149
	global_load_lds_dwordx4 v[146:147], off
	v_mfma_f32_16x16x32_bf16 v[80:83], v[164:167], v[180:183], v[80:83]
	ds_read_b128 v[192:195], v237 offset:2048
	s_waitcnt lgkmcnt(6)
	v_mfma_f32_16x16x32_bf16 v[76:79], v[152:155], v[184:187], v[76:79]
	v_mfma_f32_16x16x32_bf16 v[72:75], v[156:159], v[184:187], v[72:75]
	ds_read_b128 v[196:199], v237 offset:4096
	v_mfma_f32_16x16x32_bf16 v[68:71], v[160:163], v[184:187], v[68:71]
	v_mfma_f32_16x16x32_bf16 v[64:67], v[164:167], v[184:187], v[64:67]
	ds_read_b128 v[200:203], v237 offset:6144
	v_lshl_add_u64 v[146:147], v[144:145], 0, s[16:17]
	s_mov_b32 m0, s15
	s_mov_b64 s[16:17], 0x2168080
	global_load_lds_dwordx4 v[146:147], off
	s_waitcnt lgkmcnt(7)
	v_mfma_f32_16x16x32_bf16 v[60:63], v[152:155], v[204:207], v[60:63]
	v_mfma_f32_16x16x32_bf16 v[56:59], v[156:159], v[204:207], v[56:59]
	ds_read_b128 v[168:171], v239 offset:0
	v_mfma_f32_16x16x32_bf16 v[52:55], v[160:163], v[204:207], v[52:55]
	v_mfma_f32_16x16x32_bf16 v[48:51], v[164:167], v[204:207], v[48:51]
	ds_read_b128 v[172:175], v239 offset:2048
	s_waitcnt lgkmcnt(8)
; #define MFMA16(a, b, c) __builtin_amdgcn_mfma_f32_16x16x32_bf16((a), (b), (c), 0, 0, 0)
; DI void glds16(const void* g, unsigned char* l) { __builtin_amdgcn_global_load_lds((const unsigned*)g, (lds_u32*)l, 16, 0, 0); }
; template <int N> DI void wait_vm() { asm volatile("s_waitcnt vmcnt(%0)" :: "n"(N) : "memory"); }
;     ...
;   for (int kt = 0; kt < nk; ++kt) {
;     wait_vm<0>();
;     __builtin_amdgcn_s_barrier();
;     if (kt + 1 < nk) {
;       unsigned char* sn = smem + ((kt + 1) & 1) * STG;
;       const int ko = (kt + 1) * 64;
; #pragma unroll
;       for (int i = 0; i < NA; ++i) glds16(Ab + ((size_t)i * 128 * lda + ko * 2) + voA, sn + (i * 512 + tid) * 16);
; #pragma unroll
;       for (int i = 0; i < NB; ++i) glds16(Bb + ((size_t)i * 128 * ldb + ko * 2) + voB, sn + AB + (i * 512 + tid) * 16);
;     } else if (nA) {
;       const unsigned nvoA = (unsigned)(srow * nlda + kch * 8) * 2u, nvoB = (unsigned)(srow * nldb + kch * 8) * 2u;
; #pragma unroll
;       for (int i = 0; i < NA; ++i) glds16((const char*)nA + (size_t)i * 128 * nlda + nvoA, smem + (i * 512 + tid) * 16);
; #pragma unroll
;       for (int i = 0; i < NB; ++i) glds16((const char*)nB + (size_t)i * 128 * nldb + nvoB, smem + AB + (i * 512 + tid) * 16);
;     }
;     const unsigned stb = lds_base + (kt & 1) * STG;
; #pragma unroll
;     for (int ks = 0; ks < 2; ++ks) {
;       const unsigned co = ((ks * 4 + fq) ^ sw) * 16;
;       const unsigned sa = stb + a_row + co, sb = stb + b_row + co;
;       bf16x8 af[4], bfr[NT];
; #pragma unroll
;       for (int n = 0; n < NT; ++n) asm volatile("ds_read_b128 %0, %1 offset:%2" : "=v"(bfr[n]) : "v"(sb), "n"(n * 2048) : "memory");
; #pragma unroll
;       for (int mg = 0; mg < MT / 4; ++mg) {
; #pragma unroll
;         for (int m = 0; m < 4; ++m) asm volatile("ds_read_b128 %0, %1 offset:%2" : "=v"(af[m]) : "v"(sa), "n"((mg * 4 + m) * 2048) : "memory");
;         if (mg == 0) {
; #pragma unroll
;           for (int n = 0; n < NT; ++n) asm volatile("s_waitcnt lgkmcnt(%1)" : "+v"(bfr[n]) : "n"(4 + NT - 1 - n) : "memory");
;         }
; #pragma unroll
;         for (int m = 0; m < 4; ++m) {
;           asm volatile("s_waitcnt lgkmcnt(%1)" : "+v"(af[m]) : "n"(3 - m) : "memory");
; #pragma unroll
;           for (int n = 0; n < NT; ++n) acc[mg * 4 + m][n] = MFMA16(bfr[n], af[m], acc[mg * 4 + m][n]);
;         }
;       }
;     }
	v_mfma_f32_16x16x32_bf16 v[44:47], v[152:155], v[208:211], v[44:47]
	v_add_u32_e32 v146, 0xe000, v148
	v_lshl_add_u64 v[144:145], v[144:145], 0, s[16:17]
	v_readfirstlane_b32 s15, v146
	s_mov_b32 m0, s15
	s_nop 0
	global_load_lds_dwordx4 v[144:145], off
	v_mfma_f32_16x16x32_bf16 v[40:43], v[156:159], v[208:211], v[40:43]
	ds_read_b128 v[180:183], v239 offset:4096
	v_mfma_f32_16x16x32_bf16 v[36:39], v[160:163], v[208:211], v[36:39]
	v_mfma_f32_16x16x32_bf16 v[32:35], v[164:167], v[208:211], v[32:35]
	ds_read_b128 v[184:187], v239 offset:6144
	s_waitcnt lgkmcnt(9)
	v_mfma_f32_16x16x32_bf16 v[28:31], v[152:155], v[228:231], v[28:31]
	v_mfma_f32_16x16x32_bf16 v[24:27], v[156:159], v[228:231], v[24:27]
	v_mfma_f32_16x16x32_bf16 v[20:23], v[160:163], v[228:231], v[20:23]
	v_mfma_f32_16x16x32_bf16 v[16:19], v[164:167], v[228:231], v[16:19]
	s_waitcnt lgkmcnt(8)
	v_mfma_f32_16x16x32_bf16 v[12:15], v[152:155], v[232:235], v[12:15]
	v_mfma_f32_16x16x32_bf16 v[8:11], v[156:159], v[232:235], v[8:11]
	v_mfma_f32_16x16x32_bf16 v[4:7], v[160:163], v[232:235], v[4:7]
	v_mfma_f32_16x16x32_bf16 v[0:3], v[164:167], v[232:235], v[0:3]
	s_waitcnt lgkmcnt(3)
	v_mfma_f32_16x16x32_bf16 v[124:127], v[188:191], v[168:171], v[124:127]
	v_mfma_f32_16x16x32_bf16 v[120:123], v[192:195], v[168:171], v[120:123]
	ds_read_b128 v[204:207], v239 offset:8192
	v_mfma_f32_16x16x32_bf16 v[116:119], v[196:199], v[168:171], v[116:119]
	v_mfma_f32_16x16x32_bf16 v[112:115], v[200:203], v[168:171], v[112:115]
	ds_read_b128 v[208:211], v239 offset:10240
	s_waitcnt lgkmcnt(4)
	v_mfma_f32_16x16x32_bf16 v[108:111], v[188:191], v[172:175], v[108:111]
	v_mfma_f32_16x16x32_bf16 v[104:107], v[192:195], v[172:175], v[104:107]
	ds_read_b128 v[228:231], v239 offset:12288
	v_mfma_f32_16x16x32_bf16 v[100:103], v[196:199], v[172:175], v[100:103]
	v_mfma_f32_16x16x32_bf16 v[96:99], v[200:203], v[172:175], v[96:99]
	ds_read_b128 v[232:235], v239 offset:14336
	s_waitcnt lgkmcnt(5)
	v_mfma_f32_16x16x32_bf16 v[92:95], v[188:191], v[180:183], v[92:95]
	v_mfma_f32_16x16x32_bf16 v[88:91], v[192:195], v[180:183], v[88:91]
	v_mfma_f32_16x16x32_bf16 v[84:87], v[196:199], v[180:183], v[84:87]
	v_mfma_f32_16x16x32_bf16 v[80:83], v[200:203], v[180:183], v[80:83]
	s_waitcnt lgkmcnt(4)
	v_mfma_f32_16x16x32_bf16 v[76:79], v[188:191], v[184:187], v[76:79]
	v_mfma_f32_16x16x32_bf16 v[72:75], v[192:195], v[184:187], v[72:75]
	v_mfma_f32_16x16x32_bf16 v[68:71], v[196:199], v[184:187], v[68:71]
	v_mfma_f32_16x16x32_bf16 v[64:67], v[200:203], v[184:187], v[64:67]
	s_add_u32 s42, s42, 0x80
	s_addc_u32 s43, s43, 0
	s_cmpk_eq_i32 s42, 0x780
	s_mov_b32 s14, s5
	s_cbranch_scc0 .LBB0_335
	s_waitcnt lgkmcnt(0)
	v_mfma_f32_16x16x32_bf16 v[60:63], v[188:191], v[204:207], v[60:63]
	v_mfma_f32_16x16x32_bf16 v[56:59], v[192:195], v[204:207], v[56:59]
	v_mfma_f32_16x16x32_bf16 v[52:55], v[196:199], v[204:207], v[52:55]
	v_mfma_f32_16x16x32_bf16 v[48:51], v[200:203], v[204:207], v[48:51]
	v_mfma_f32_16x16x32_bf16 v[44:47], v[188:191], v[208:211], v[44:47]
	v_mfma_f32_16x16x32_bf16 v[40:43], v[192:195], v[208:211], v[40:43]
	v_mfma_f32_16x16x32_bf16 v[36:39], v[196:199], v[208:211], v[36:39]
	v_mfma_f32_16x16x32_bf16 v[32:35], v[200:203], v[208:211], v[32:35]
	v_mfma_f32_16x16x32_bf16 v[28:31], v[188:191], v[228:231], v[28:31]
	v_mfma_f32_16x16x32_bf16 v[24:27], v[192:195], v[228:231], v[24:27]
	v_mfma_f32_16x16x32_bf16 v[20:23], v[196:199], v[228:231], v[20:23]
	v_mfma_f32_16x16x32_bf16 v[16:19], v[200:203], v[228:231], v[16:19]
	v_mfma_f32_16x16x32_bf16 v[12:15], v[188:191], v[232:235], v[12:15]
	v_mfma_f32_16x16x32_bf16 v[8:11], v[192:195], v[232:235], v[8:11]
	v_mfma_f32_16x16x32_bf16 v[4:7], v[196:199], v[232:235], v[4:7]
	v_mfma_f32_16x16x32_bf16 v[0:3], v[200:203], v[232:235], v[0:3]
	s_setprio 0
	s_waitcnt vmcnt(0)
	s_andn2_b64 vcc, exec, s[12:13]
	s_barrier
	s_cbranch_vccnz .LBB0_338
	s_add_u32 s5, s54, s10
	s_addc_u32 s12, s55, s11
	s_and_b64 s[10:11], exec, s[0:1]
	s_cselect_b32 s11, 0, s12
	s_cselect_b32 s10, 0, s5
	v_readfirstlane_b32 s5, v140
	v_lshl_add_u64 v[136:137], s[10:11], 0, v[128:129]
	s_mov_b32 m0, s5
	v_lshl_add_u64 v[144:145], v[136:137], 0, s[80:81]
	v_lshl_add_u64 v[152:153], v[136:137], 0, s[82:83]
	v_lshl_add_u64 v[154:155], v[136:137], 0, s[70:71]
	global_load_lds_dwordx4 v[136:137], off
	v_add_u32_e32 v136, 0x2000, v140
	v_add_u32_e32 v156, 0x4000, v140
	v_readfirstlane_b32 s5, v136
	s_mov_b32 m0, s5
	v_readfirstlane_b32 s5, v156
	v_add_u32_e32 v136, 0x6000, v140
	s_add_u32 s12, s35, s38
	global_load_lds_dwordx4 v[154:155], off
	s_mov_b32 m0, s5
	v_readfirstlane_b32 s5, v136
	v_add_u32_e32 v136, 0x8000, v140
	s_addc_u32 s13, s27, s39
	global_load_lds_dwordx4 v[144:145], off
	s_mov_b32 m0, s5
	v_readfirstlane_b32 s5, v136
	v_add_u32_e32 v136, 0xa000, v140
	v_lshl_add_u64 v[138:139], s[12:13], 0, v[128:129]
	v_add_u32_e32 v128, 0xc000, v140
	global_load_lds_dwordx4 v[152:153], off
	s_mov_b32 m0, s5
	v_readfirstlane_b32 s5, v136
	v_lshl_add_u64 v[150:151], v[138:139], 0, s[70:71]
	global_load_lds_dwordx4 v[138:139], off
	s_mov_b32 m0, s5
	v_readfirstlane_b32 s5, v128
	v_add_u32_e32 v128, 0xe000, v140
	v_lshl_add_u64 v[146:147], v[138:139], 0, s[80:81]
	global_load_lds_dwordx4 v[150:151], off
	s_mov_b32 m0, s5
	v_readfirstlane_b32 s5, v128
	v_lshl_add_u64 v[148:149], v[138:139], 0, s[82:83]
	global_load_lds_dwordx4 v[146:147], off
	s_mov_b32 m0, s5
	s_nop 0
	global_load_lds_dwordx4 v[148:149], off

; DI int otid() { int t = threadIdx.x; asm volatile("" : "+v"(t)); return t; }
; DI void glds16(const void* g, unsigned char* l) { __builtin_amdgcn_global_load_lds((const unsigned*)g, (lds_u32*)l, 16, 0, 0); }
;     ...
;   const int tid = otid(), lane = tid & 63, w = tid >> 6, wr = w / WC, wc = w % WC, fr = lane & 15, fq = lane >> 4;
;   const int srow = tid >> 3, kch = (tid & 7) ^ ((tid >> 4) & 7);
;   const unsigned voA = (unsigned)(srow * lda + kch * 8) * 2u, voB = (unsigned)(srow * ldb + kch * 8) * 2u;
;   const char* Ab = (const char*)A;
;   const char* Bb = (const char*)B;
;   const int nk = K >> 6;
;   if (!primed) {
; #pragma unroll
;     for (int i = 0; i < NA; ++i) glds16(Ab + (size_t)i * 128 * lda + voA, smem + (i * 512 + tid) * 16);
; #pragma unroll
;     for (int i = 0; i < NB; ++i) glds16(Bb + (size_t)i * 128 * ldb + voB, smem + AB + (i * 512 + tid) * 16);
;   }
;   const int sw = (fr >> 1) & 7;
;   const unsigned lds_base = (unsigned)(size_t)(__attribute__((address_space(3))) unsigned char*)smem;
;   const unsigned a_row = (wr * 16 * MT + fr) * 128, b_row = AB + (wc * 16 * NT + fr) * 128;
; template <int MT, int NT>
; DI void zero_acc(f32x4 (&acc)[MT][NT]) {
; #pragma unroll
;   for (int m = 0; m < MT; ++m)
; #pragma unroll
;     for (int n = 0; n < NT; ++n) acc[m][n] = (f32x4){0.f, 0.f, 0.f, 0.f};
; }
.LBB0_766:
	v_ashrrev_i32_e32 v1, 6, v0
	v_lshrrev_b32_e32 v5, 30, v1
	v_add_u32_e32 v5, v1, v5
	v_ashrrev_i32_e32 v5, 2, v5
	s_add_i32 s16, s2, s22
	v_mul_i32_i24_e32 v6, 4, v5
	v_bfe_u32 v7, v0, 1, 3
	v_lshlrev_b32_e32 v0, 7, v0
	s_ashr_i32 s17, s16, 31
	v_sub_u32_e32 v1, v1, v6
	v_and_b32_e32 v0, 0x780, v0
	s_lshl_b64 s[16:17], s[16:17], 19
	v_readlane_b32 s40, v252, 0
	v_lshl_or_b32 v141, v5, 14, v0
	v_lshl_or_b32 v0, v1, 13, v0
	v_readlane_b32 s41, v252, 1
	s_add_u32 s16, s40, s16
	v_and_b32_e32 v6, 3, v4
	v_add_u32_e32 v142, 0x8000, v0
	v_bitop3_b32 v0, v4, v7, 3 bitop3:0x6c
	s_addc_u32 s17, s41, s17
	v_lshlrev_b32_e32 v140, 4, v0
	v_bitop3_b32 v0, v6, v7, 4 bitop3:0x36
	s_add_u32 s14, s19, s14
	v_lshlrev_b32_e32 v131, 4, v0
	v_add_u32_e32 v0, v2, v3
	v_mov_b32_e32 v1, v129
	s_addc_u32 s15, s20, s15
	v_readlane_b32 s42, v252, 2
	v_readlane_b32 s43, v252, 3
	v_lshl_add_u64 v[136:137], s[16:17], 0, v[0:1]
	v_lshl_add_u64 v[138:139], s[14:15], 0, v[0:1]
	v_mov_b32_e32 v0, 0
	s_mov_b64 s[42:43], 0
	s_mov_b32 s7, 0
	v_mov_b32_e32 v1, v0
	v_mov_b32_e32 v2, v0
	v_mov_b32_e32 v3, v0
	v_mov_b32_e32 v4, v0
	v_mov_b32_e32 v5, v0
	v_mov_b32_e32 v6, v0
	v_mov_b32_e32 v7, v0
	v_mov_b32_e32 v8, v0
	v_mov_b32_e32 v9, v0
	v_mov_b32_e32 v10, v0
	v_mov_b32_e32 v11, v0
	v_mov_b32_e32 v12, v0
	v_mov_b32_e32 v13, v0
	v_mov_b32_e32 v14, v0
	v_mov_b32_e32 v15, v0
	v_mov_b32_e32 v16, v0
	v_mov_b32_e32 v17, v0
	v_mov_b32_e32 v18, v0
	v_mov_b32_e32 v19, v0
	v_mov_b32_e32 v20, v0
	v_mov_b32_e32 v21, v0
	v_mov_b32_e32 v22, v0
	v_mov_b32_e32 v23, v0
	v_mov_b32_e32 v24, v0
	v_mov_b32_e32 v25, v0
	v_mov_b32_e32 v26, v0
	v_mov_b32_e32 v27, v0
	v_mov_b32_e32 v28, v0
	v_mov_b32_e32 v29, v0
	v_mov_b32_e32 v30, v0
	v_mov_b32_e32 v31, v0
	v_mov_b32_e32 v32, v0
	v_mov_b32_e32 v33, v0
	v_mov_b32_e32 v34, v0
	v_mov_b32_e32 v35, v0
	v_mov_b32_e32 v36, v0
	v_mov_b32_e32 v37, v0
	v_mov_b32_e32 v38, v0
	v_mov_b32_e32 v39, v0
	v_mov_b32_e32 v40, v0
	v_mov_b32_e32 v41, v0
	v_mov_b32_e32 v42, v0
	v_mov_b32_e32 v43, v0
	v_mov_b32_e32 v44, v0
	v_mov_b32_e32 v45, v0
	v_mov_b32_e32 v46, v0
	v_mov_b32_e32 v47, v0
	v_mov_b32_e32 v48, v0
	v_mov_b32_e32 v49, v0
	v_mov_b32_e32 v50, v0
	v_mov_b32_e32 v51, v0
	v_mov_b32_e32 v52, v0
	v_mov_b32_e32 v53, v0
	v_mov_b32_e32 v54, v0
	v_mov_b32_e32 v55, v0
	v_mov_b32_e32 v56, v0
	v_mov_b32_e32 v57, v0
	v_mov_b32_e32 v58, v0
	v_mov_b32_e32 v59, v0
	v_mov_b32_e32 v60, v0
	v_mov_b32_e32 v61, v0
	v_mov_b32_e32 v62, v0
	v_mov_b32_e32 v63, v0
	v_mov_b32_e32 v64, v0
	v_mov_b32_e32 v65, v0
	v_mov_b32_e32 v66, v0
	v_mov_b32_e32 v67, v0
	v_mov_b32_e32 v68, v0
	v_mov_b32_e32 v69, v0
	v_mov_b32_e32 v70, v0
	v_mov_b32_e32 v71, v0
	v_mov_b32_e32 v72, v0
	v_mov_b32_e32 v73, v0
	v_mov_b32_e32 v74, v0
	v_mov_b32_e32 v75, v0
	v_mov_b32_e32 v76, v0
	v_mov_b32_e32 v77, v0
	v_mov_b32_e32 v78, v0
	v_mov_b32_e32 v79, v0
	v_mov_b32_e32 v80, v0
	v_mov_b32_e32 v81, v0
	v_mov_b32_e32 v82, v0
	v_mov_b32_e32 v83, v0
	v_mov_b32_e32 v84, v0
	v_mov_b32_e32 v85, v0
	v_mov_b32_e32 v86, v0
	v_mov_b32_e32 v87, v0
	v_mov_b32_e32 v88, v0
	v_mov_b32_e32 v89, v0
	v_mov_b32_e32 v90, v0
	v_mov_b32_e32 v91, v0
	v_mov_b32_e32 v92, v0
	v_mov_b32_e32 v93, v0
	v_mov_b32_e32 v94, v0
	v_mov_b32_e32 v95, v0
	v_mov_b32_e32 v96, v0
	v_mov_b32_e32 v97, v0
	v_mov_b32_e32 v98, v0
	v_mov_b32_e32 v99, v0
	v_mov_b32_e32 v100, v0
	v_mov_b32_e32 v101, v0
	v_mov_b32_e32 v102, v0
	v_mov_b32_e32 v103, v0
	v_mov_b32_e32 v104, v0
	v_mov_b32_e32 v105, v0
	v_mov_b32_e32 v106, v0
	v_mov_b32_e32 v107, v0
	v_mov_b32_e32 v108, v0
	v_mov_b32_e32 v109, v0
	v_mov_b32_e32 v110, v0
	v_mov_b32_e32 v111, v0
	v_mov_b32_e32 v112, v0
	v_mov_b32_e32 v113, v0
	v_mov_b32_e32 v114, v0
	v_mov_b32_e32 v115, v0
	v_mov_b32_e32 v116, v0
	v_mov_b32_e32 v117, v0
	v_mov_b32_e32 v118, v0
	v_mov_b32_e32 v119, v0
	v_mov_b32_e32 v120, v0
	v_mov_b32_e32 v121, v0
	v_mov_b32_e32 v122, v0
	v_mov_b32_e32 v123, v0
	v_mov_b32_e32 v124, v0
	v_mov_b32_e32 v125, v0
	v_mov_b32_e32 v126, v0
	v_mov_b32_e32 v127, v0
	v_mov_b32_e32 v188, 0
	v_mov_b32_e32 v189, 0
	v_mov_b32_e32 v190, 0
	v_mov_b32_e32 v191, 0
	v_mov_b32_e32 v192, 0
	v_mov_b32_e32 v193, 0
	v_mov_b32_e32 v194, 0
	v_mov_b32_e32 v195, 0
	v_mov_b32_e32 v196, 0
	v_mov_b32_e32 v197, 0
	v_mov_b32_e32 v198, 0
	v_mov_b32_e32 v199, 0
	v_mov_b32_e32 v200, 0
	v_mov_b32_e32 v201, 0
	v_mov_b32_e32 v202, 0
	v_mov_b32_e32 v203, 0
	v_mov_b32_e32 v204, 0
	v_mov_b32_e32 v205, 0
	v_mov_b32_e32 v206, 0
	v_mov_b32_e32 v207, 0
	v_mov_b32_e32 v208, 0
	v_mov_b32_e32 v209, 0
	v_mov_b32_e32 v210, 0
	v_mov_b32_e32 v211, 0
	v_mov_b32_e32 v228, 0
	v_mov_b32_e32 v229, 0
	v_mov_b32_e32 v230, 0
	v_mov_b32_e32 v231, 0
	v_mov_b32_e32 v232, 0
	v_mov_b32_e32 v233, 0
	v_mov_b32_e32 v234, 0
	v_mov_b32_e32 v235, 0
	v_lshrrev_b32_e32 v240, 8, v212
	s_nop 0
	v_readfirstlane_b32 s98, v240
	s_cmp_eq_u32 s98, 0
	s_cbranch_scc1 .Lprio_3
	s_setprio 1
; #define MFMA16(a, b, c) __builtin_amdgcn_mfma_f32_16x16x32_bf16((a), (b), (c), 0, 0, 0)
; DI void glds16(const void* g, unsigned char* l) { __builtin_amdgcn_global_load_lds((const unsigned*)g, (lds_u32*)l, 16, 0, 0); }
; template <int N> DI void wait_vm() { asm volatile("s_waitcnt vmcnt(%0)" :: "n"(N) : "memory"); }
;     ...
;   for (int kt = 0; kt < nk; ++kt) {
;     wait_vm<0>();
;     __builtin_amdgcn_s_barrier();
;     if (kt + 1 < nk) {
;       unsigned char* sn = smem + ((kt + 1) & 1) * STG;
;       const int ko = (kt + 1) * 64;
; #pragma unroll
;       for (int i = 0; i < NA; ++i) glds16(Ab + ((size_t)i * 128 * lda + ko * 2) + voA, sn + (i * 512 + tid) * 16);
; #pragma unroll
;       for (int i = 0; i < NB; ++i) glds16(Bb + ((size_t)i * 128 * ldb + ko * 2) + voB, sn + AB + (i * 512 + tid) * 16);
;     } else if (nA) {
;       const unsigned nvoA = (unsigned)(srow * nlda + kch * 8) * 2u, nvoB = (unsigned)(srow * nldb + kch * 8) * 2u;
; #pragma unroll
;       for (int i = 0; i < NA; ++i) glds16((const char*)nA + (size_t)i * 128 * nlda + nvoA, smem + (i * 512 + tid) * 16);
; #pragma unroll
;       for (int i = 0; i < NB; ++i) glds16((const char*)nB + (size_t)i * 128 * nldb + nvoB, smem + AB + (i * 512 + tid) * 16);
;     }
;     const unsigned stb = lds_base + (kt & 1) * STG;
; #pragma unroll
;     for (int ks = 0; ks < 2; ++ks) {
;       const unsigned co = ((ks * 4 + fq) ^ sw) * 16;
;       const unsigned sa = stb + a_row + co, sb = stb + b_row + co;
;       bf16x8 af[4], bfr[NT];
; #pragma unroll
;       for (int n = 0; n < NT; ++n) asm volatile("ds_read_b128 %0, %1 offset:%2" : "=v"(bfr[n]) : "v"(sb), "n"(n * 2048) : "memory");
; #pragma unroll
;       for (int mg = 0; mg < MT / 4; ++mg) {
; #pragma unroll
;         for (int m = 0; m < 4; ++m) asm volatile("ds_read_b128 %0, %1 offset:%2" : "=v"(af[m]) : "v"(sa), "n"((mg * 4 + m) * 2048) : "memory");
;         if (mg == 0) {
; #pragma unroll
;           for (int n = 0; n < NT; ++n) asm volatile("s_waitcnt lgkmcnt(%1)" : "+v"(bfr[n]) : "n"(4 + NT - 1 - n) : "memory");
;         }
; #pragma unroll
;         for (int m = 0; m < 4; ++m) {
;           asm volatile("s_waitcnt lgkmcnt(%1)" : "+v"(af[m]) : "n"(3 - m) : "memory");
; #pragma unroll
;           for (int n = 0; n < NT; ++n) acc[mg * 4 + m][n] = MFMA16(bfr[n], af[m], acc[mg * 4 + m][n]);
;         }
;       }
.Lprio_3:
.LBB0_767:
	s_add_i32 s2, s7, 0x10000
	s_and_b32 s14, s2, 0x10000
	v_add_u32_e32 v143, s14, v133
	v_lshl_add_u64 v[144:145], v[136:137], 0, s[42:43]
	v_readfirstlane_b32 s14, v143
	v_lshl_add_u64 v[146:147], v[144:145], 0, s[96:97]
	s_mov_b32 m0, s14
	s_mov_b64 s[14:15], 0xe368080
	v_add_u32_e32 v148, 0x2000, v143
	s_waitcnt vmcnt(0)
	s_waitcnt lgkmcnt(0)
	s_barrier
	s_and_b32 s7, s7, 0x10000
	v_add_u32_e32 v240, s7, v142
	v_add_u32_e32 v236, v240, v140
	v_add_u32_e32 v237, v240, v131
	v_add_u32_e32 v240, s7, v141
	v_add_u32_e32 v238, v240, v140
	v_add_u32_e32 v239, v240, v131
	v_mfma_f32_16x16x32_bf16 v[60:63], v[188:191], v[204:207], v[60:63]
	ds_read_b128 v[152:155], v236 offset:0
	ds_read_b128 v[156:159], v236 offset:2048
	v_mfma_f32_16x16x32_bf16 v[56:59], v[192:195], v[204:207], v[56:59]
	ds_read_b128 v[160:163], v236 offset:4096
	ds_read_b128 v[164:167], v236 offset:6144
	global_load_lds_dwordx4 v[146:147], off
	v_mfma_f32_16x16x32_bf16 v[52:55], v[196:199], v[204:207], v[52:55]
	ds_read_b128 v[168:171], v238 offset:0
	ds_read_b128 v[172:175], v238 offset:2048
	v_mfma_f32_16x16x32_bf16 v[48:51], v[200:203], v[204:207], v[48:51]
	ds_read_b128 v[180:183], v238 offset:4096
	ds_read_b128 v[184:187], v238 offset:6144
	v_mfma_f32_16x16x32_bf16 v[44:47], v[188:191], v[208:211], v[44:47]
	v_mfma_f32_16x16x32_bf16 v[40:43], v[192:195], v[208:211], v[40:43]
	v_mfma_f32_16x16x32_bf16 v[36:39], v[196:199], v[208:211], v[36:39]
	v_lshl_add_u64 v[146:147], v[144:145], 0, s[14:15]
	v_readfirstlane_b32 s14, v148
	s_mov_b32 m0, s14
	s_mov_b64 s[14:15], 0xe388080
	v_add_u32_e32 v148, 0x4000, v143
	global_load_lds_dwordx4 v[146:147], off
	v_mfma_f32_16x16x32_bf16 v[32:35], v[200:203], v[208:211], v[32:35]
	v_mfma_f32_16x16x32_bf16 v[28:31], v[188:191], v[228:231], v[28:31]
	v_mfma_f32_16x16x32_bf16 v[24:27], v[192:195], v[228:231], v[24:27]
	v_mfma_f32_16x16x32_bf16 v[20:23], v[196:199], v[228:231], v[20:23]
	v_mfma_f32_16x16x32_bf16 v[16:19], v[200:203], v[228:231], v[16:19]
	v_lshl_add_u64 v[146:147], v[144:145], 0, s[14:15]
	v_readfirstlane_b32 s14, v148
	s_mov_b32 m0, s14
	s_mov_b64 s[14:15], 0xe3a8080
	global_load_lds_dwordx4 v[146:147], off
	v_mfma_f32_16x16x32_bf16 v[12:15], v[188:191], v[232:235], v[12:15]
	v_mfma_f32_16x16x32_bf16 v[8:11], v[192:195], v[232:235], v[8:11]
	v_mfma_f32_16x16x32_bf16 v[4:7], v[196:199], v[232:235], v[4:7]
	v_mfma_f32_16x16x32_bf16 v[0:3], v[200:203], v[232:235], v[0:3]
	s_waitcnt lgkmcnt(3)
	v_mfma_f32_16x16x32_bf16 v[124:127], v[152:155], v[168:171], v[124:127]
	v_add_u32_e32 v146, 0x6000, v143
	v_lshl_add_u64 v[144:145], v[144:145], 0, s[14:15]
	v_readfirstlane_b32 s14, v146
	s_mov_b32 m0, s14
	v_add_u32_e32 v148, 0x8000, v143
	global_load_lds_dwordx4 v[144:145], off
	v_mfma_f32_16x16x32_bf16 v[120:123], v[156:159], v[168:171], v[120:123]
	ds_read_b128 v[204:207], v238 offset:8192
	v_mfma_f32_16x16x32_bf16 v[116:119], v[160:163], v[168:171], v[116:119]
	v_mfma_f32_16x16x32_bf16 v[112:115], v[164:167], v[168:171], v[112:115]
	ds_read_b128 v[208:211], v238 offset:10240
	s_waitcnt lgkmcnt(4)
	v_mfma_f32_16x16x32_bf16 v[108:111], v[152:155], v[172:175], v[108:111]
	v_mfma_f32_16x16x32_bf16 v[104:107], v[156:159], v[172:175], v[104:107]
	ds_read_b128 v[228:231], v238 offset:12288
	v_lshl_add_u64 v[144:145], v[138:139], 0, s[42:43]
	s_mov_b64 s[14:15], 0x2f88080
	v_lshl_add_u64 v[146:147], v[144:145], 0, s[14:15]
	v_readfirstlane_b32 s14, v148
	s_mov_b32 m0, s14
	s_mov_b64 s[14:15], 0x2fa8080
	v_add_u32_e32 v148, 0xa000, v143
	global_load_lds_dwordx4 v[146:147], off
	v_mfma_f32_16x16x32_bf16 v[100:103], v[160:163], v[172:175], v[100:103]
	v_mfma_f32_16x16x32_bf16 v[96:99], v[164:167], v[172:175], v[96:99]
	ds_read_b128 v[232:235], v238 offset:14336
	s_waitcnt lgkmcnt(5)
	v_mfma_f32_16x16x32_bf16 v[92:95], v[152:155], v[180:183], v[92:95]
	v_mfma_f32_16x16x32_bf16 v[88:91], v[156:159], v[180:183], v[88:91]
	ds_read_b128 v[188:191], v237 offset:0
	v_mfma_f32_16x16x32_bf16 v[84:87], v[160:163], v[180:183], v[84:87]
	v_lshl_add_u64 v[146:147], v[144:145], 0, s[14:15]
	v_readfirstlane_b32 s14, v148
	s_mov_b32 m0, s14
	s_mov_b64 s[14:15], 0x2fc8080
	v_add_u32_e32 v148, 0xc000, v143
	global_load_lds_dwordx4 v[146:147], off
	v_mfma_f32_16x16x32_bf16 v[80:83], v[164:167], v[180:183], v[80:83]
	ds_read_b128 v[192:195], v237 offset:2048
	s_waitcnt lgkmcnt(6)
	v_mfma_f32_16x16x32_bf16 v[76:79], v[152:155], v[184:187], v[76:79]
	v_mfma_f32_16x16x32_bf16 v[72:75], v[156:159], v[184:187], v[72:75]
	ds_read_b128 v[196:199], v237 offset:4096
	v_mfma_f32_16x16x32_bf16 v[68:71], v[160:163], v[184:187], v[68:71]
	v_mfma_f32_16x16x32_bf16 v[64:67], v[164:167], v[184:187], v[64:67]
	ds_read_b128 v[200:203], v237 offset:6144
	v_lshl_add_u64 v[146:147], v[144:145], 0, s[14:15]
	v_readfirstlane_b32 s14, v148
	s_mov_b32 m0, s14
	s_mov_b64 s[14:15], 0x2fe8080
	v_add_u32_e32 v143, 0xe000, v143
	v_lshl_add_u64 v[144:145], v[144:145], 0, s[14:15]
	v_readfirstlane_b32 s14, v143
	global_load_lds_dwordx4 v[146:147], off
	s_waitcnt lgkmcnt(7)
	v_mfma_f32_16x16x32_bf16 v[60:63], v[152:155], v[204:207], v[60:63]
	v_mfma_f32_16x16x32_bf16 v[56:59], v[156:159], v[204:207], v[56:59]
	ds_read_b128 v[168:171], v239 offset:0
	v_mfma_f32_16x16x32_bf16 v[52:55], v[160:163], v[204:207], v[52:55]
	v_mfma_f32_16x16x32_bf16 v[48:51], v[164:167], v[204:207], v[48:51]
	ds_read_b128 v[172:175], v239 offset:2048
	s_waitcnt lgkmcnt(8)
; #define MFMA16(a, b, c) __builtin_amdgcn_mfma_f32_16x16x32_bf16((a), (b), (c), 0, 0, 0)
; DI void glds16(const void* g, unsigned char* l) { __builtin_amdgcn_global_load_lds((const unsigned*)g, (lds_u32*)l, 16, 0, 0); }
; template <int N> DI void wait_vm() { asm volatile("s_waitcnt vmcnt(%0)" :: "n"(N) : "memory"); }
;     ...
;   for (int kt = 0; kt < nk; ++kt) {
;     wait_vm<0>();
;     __builtin_amdgcn_s_barrier();
;     if (kt + 1 < nk) {
;       unsigned char* sn = smem + ((kt + 1) & 1) * STG;
;       const int ko = (kt + 1) * 64;
; #pragma unroll
;       for (int i = 0; i < NA; ++i) glds16(Ab + ((size_t)i * 128 * lda + ko * 2) + voA, sn + (i * 512 + tid) * 16);
; #pragma unroll
;       for (int i = 0; i < NB; ++i) glds16(Bb + ((size_t)i * 128 * ldb + ko * 2) + voB, sn + AB + (i * 512 + tid) * 16);
;     } else if (nA) {
;       const unsigned nvoA = (unsigned)(srow * nlda + kch * 8) * 2u, nvoB = (unsigned)(srow * nldb + kch * 8) * 2u;
; #pragma unroll
;       for (int i = 0; i < NA; ++i) glds16((const char*)nA + (size_t)i * 128 * nlda + nvoA, smem + (i * 512 + tid) * 16);
; #pragma unroll
;       for (int i = 0; i < NB; ++i) glds16((const char*)nB + (size_t)i * 128 * nldb + nvoB, smem + AB + (i * 512 + tid) * 16);
;     }
;     const unsigned stb = lds_base + (kt & 1) * STG;
; #pragma unroll
;     for (int ks = 0; ks < 2; ++ks) {
;       const unsigned co = ((ks * 4 + fq) ^ sw) * 16;
;       const unsigned sa = stb + a_row + co, sb = stb + b_row + co;
;       bf16x8 af[4], bfr[NT];
; #pragma unroll
;       for (int n = 0; n < NT; ++n) asm volatile("ds_read_b128 %0, %1 offset:%2" : "=v"(bfr[n]) : "v"(sb), "n"(n * 2048) : "memory");
; #pragma unroll
;       for (int mg = 0; mg < MT / 4; ++mg) {
; #pragma unroll
;         for (int m = 0; m < 4; ++m) asm volatile("ds_read_b128 %0, %1 offset:%2" : "=v"(af[m]) : "v"(sa), "n"((mg * 4 + m) * 2048) : "memory");
;         if (mg == 0) {
; #pragma unroll
;           for (int n = 0; n < NT; ++n) asm volatile("s_waitcnt lgkmcnt(%1)" : "+v"(bfr[n]) : "n"(4 + NT - 1 - n) : "memory");
;         }
; #pragma unroll
;         for (int m = 0; m < 4; ++m) {
;           asm volatile("s_waitcnt lgkmcnt(%1)" : "+v"(af[m]) : "n"(3 - m) : "memory");
; #pragma unroll
;           for (int n = 0; n < NT; ++n) acc[mg * 4 + m][n] = MFMA16(bfr[n], af[m], acc[mg * 4 + m][n]);
;         }
;       }
;     }
	v_mfma_f32_16x16x32_bf16 v[44:47], v[152:155], v[208:211], v[44:47]
	s_mov_b32 m0, s14
	s_nop 0
	global_load_lds_dwordx4 v[144:145], off
	v_mfma_f32_16x16x32_bf16 v[40:43], v[156:159], v[208:211], v[40:43]
	ds_read_b128 v[180:183], v239 offset:4096
	v_mfma_f32_16x16x32_bf16 v[36:39], v[160:163], v[208:211], v[36:39]
	v_mfma_f32_16x16x32_bf16 v[32:35], v[164:167], v[208:211], v[32:35]
	ds_read_b128 v[184:187], v239 offset:6144
	s_waitcnt lgkmcnt(9)
	v_mfma_f32_16x16x32_bf16 v[28:31], v[152:155], v[228:231], v[28:31]
	v_mfma_f32_16x16x32_bf16 v[24:27], v[156:159], v[228:231], v[24:27]
	v_mfma_f32_16x16x32_bf16 v[20:23], v[160:163], v[228:231], v[20:23]
	v_mfma_f32_16x16x32_bf16 v[16:19], v[164:167], v[228:231], v[16:19]
	s_waitcnt lgkmcnt(8)
	v_mfma_f32_16x16x32_bf16 v[12:15], v[152:155], v[232:235], v[12:15]
	v_mfma_f32_16x16x32_bf16 v[8:11], v[156:159], v[232:235], v[8:11]
	v_mfma_f32_16x16x32_bf16 v[4:7], v[160:163], v[232:235], v[4:7]
	v_mfma_f32_16x16x32_bf16 v[0:3], v[164:167], v[232:235], v[0:3]
	s_waitcnt lgkmcnt(3)
	v_mfma_f32_16x16x32_bf16 v[124:127], v[188:191], v[168:171], v[124:127]
	v_mfma_f32_16x16x32_bf16 v[120:123], v[192:195], v[168:171], v[120:123]
	ds_read_b128 v[204:207], v239 offset:8192
	v_mfma_f32_16x16x32_bf16 v[116:119], v[196:199], v[168:171], v[116:119]
	v_mfma_f32_16x16x32_bf16 v[112:115], v[200:203], v[168:171], v[112:115]
	ds_read_b128 v[208:211], v239 offset:10240
	s_waitcnt lgkmcnt(4)
	v_mfma_f32_16x16x32_bf16 v[108:111], v[188:191], v[172:175], v[108:111]
	v_mfma_f32_16x16x32_bf16 v[104:107], v[192:195], v[172:175], v[104:107]
	ds_read_b128 v[228:231], v239 offset:12288
	v_mfma_f32_16x16x32_bf16 v[100:103], v[196:199], v[172:175], v[100:103]
	v_mfma_f32_16x16x32_bf16 v[96:99], v[200:203], v[172:175], v[96:99]
	ds_read_b128 v[232:235], v239 offset:14336
	s_waitcnt lgkmcnt(5)
	v_mfma_f32_16x16x32_bf16 v[92:95], v[188:191], v[180:183], v[92:95]
	v_mfma_f32_16x16x32_bf16 v[88:91], v[192:195], v[180:183], v[88:91]
	v_mfma_f32_16x16x32_bf16 v[84:87], v[196:199], v[180:183], v[84:87]
	v_mfma_f32_16x16x32_bf16 v[80:83], v[200:203], v[180:183], v[80:83]
	s_waitcnt lgkmcnt(4)
	v_mfma_f32_16x16x32_bf16 v[76:79], v[188:191], v[184:187], v[76:79]
	v_mfma_f32_16x16x32_bf16 v[72:75], v[192:195], v[184:187], v[72:75]
	v_mfma_f32_16x16x32_bf16 v[68:71], v[196:199], v[184:187], v[68:71]
	v_mfma_f32_16x16x32_bf16 v[64:67], v[200:203], v[184:187], v[64:67]
	s_add_u32 s42, s42, 0x80
	s_addc_u32 s43, s43, 0
	s_cmpk_eq_i32 s42, 0x780
	s_mov_b32 s7, s2
	s_cbranch_scc0 .LBB0_767
	s_waitcnt lgkmcnt(0)
	v_mfma_f32_16x16x32_bf16 v[60:63], v[188:191], v[204:207], v[60:63]
	v_mfma_f32_16x16x32_bf16 v[56:59], v[192:195], v[204:207], v[56:59]
	v_mfma_f32_16x16x32_bf16 v[52:55], v[196:199], v[204:207], v[52:55]
	v_mfma_f32_16x16x32_bf16 v[48:51], v[200:203], v[204:207], v[48:51]
	v_mfma_f32_16x16x32_bf16 v[44:47], v[188:191], v[208:211], v[44:47]
	v_mfma_f32_16x16x32_bf16 v[40:43], v[192:195], v[208:211], v[40:43]
	v_mfma_f32_16x16x32_bf16 v[36:39], v[196:199], v[208:211], v[36:39]
	v_mfma_f32_16x16x32_bf16 v[32:35], v[200:203], v[208:211], v[32:35]
	v_mfma_f32_16x16x32_bf16 v[28:31], v[188:191], v[228:231], v[28:31]
	v_mfma_f32_16x16x32_bf16 v[24:27], v[192:195], v[228:231], v[24:27]
	v_mfma_f32_16x16x32_bf16 v[20:23], v[196:199], v[228:231], v[20:23]
	v_mfma_f32_16x16x32_bf16 v[16:19], v[200:203], v[228:231], v[16:19]
	v_mfma_f32_16x16x32_bf16 v[12:15], v[188:191], v[232:235], v[12:15]
	v_mfma_f32_16x16x32_bf16 v[8:11], v[192:195], v[232:235], v[8:11]
	v_mfma_f32_16x16x32_bf16 v[4:7], v[196:199], v[232:235], v[4:7]
	v_mfma_f32_16x16x32_bf16 v[0:3], v[200:203], v[232:235], v[0:3]
	s_setprio 0
	s_waitcnt vmcnt(0)
	s_andn2_b64 vcc, exec, s[12:13]
	s_barrier
	v_readlane_b32 s41, v254, 60
	s_cbranch_vccnz .LBB0_770
	s_lshl_b64 s[10:11], s[10:11], 1
	s_add_u32 s2, s52, s10
	s_addc_u32 s7, s53, s11
	s_and_b64 s[10:11], exec, s[0:1]
	s_cselect_b32 s11, 0, s7
	s_cselect_b32 s10, 0, s2
	v_readfirstlane_b32 s2, v133
	v_lshl_add_u64 v[136:137], s[10:11], 0, v[128:129]
	s_mov_b32 m0, s2
	v_lshl_add_u64 v[144:145], v[136:137], 0, s[80:81]
	v_lshl_add_u64 v[152:153], v[136:137], 0, s[82:83]
	v_lshl_add_u64 v[154:155], v[136:137], 0, s[70:71]
	global_load_lds_dwordx4 v[136:137], off
	v_add_u32_e32 v136, 0x2000, v133
	v_add_u32_e32 v143, 0x4000, v133
	v_readfirstlane_b32 s2, v136
	s_lshl_b64 s[12:13], s[38:39], 1
	s_mov_b32 m0, s2
	v_readfirstlane_b32 s2, v143
	v_add_u32_e32 v136, 0x6000, v133
	s_add_u32 s12, s8, s12
	global_load_lds_dwordx4 v[154:155], off
	s_mov_b32 m0, s2
	v_readfirstlane_b32 s2, v136
	v_add_u32_e32 v136, 0x8000, v133
	s_addc_u32 s13, s18, s13
	global_load_lds_dwordx4 v[144:145], off
	s_mov_b32 m0, s2
	v_readfirstlane_b32 s2, v136
	v_add_u32_e32 v136, 0xa000, v133
	v_lshl_add_u64 v[138:139], s[12:13], 0, v[128:129]
	v_add_u32_e32 v128, 0xc000, v133
	global_load_lds_dwordx4 v[152:153], off
	s_mov_b32 m0, s2
	v_readfirstlane_b32 s2, v136
	v_lshl_add_u64 v[150:151], v[138:139], 0, s[70:71]
	global_load_lds_dwordx4 v[138:139], off
	s_mov_b32 m0, s2
	v_readfirstlane_b32 s2, v128
	v_add_u32_e32 v128, 0xe000, v133
	v_lshl_add_u64 v[146:147], v[138:139], 0, s[80:81]
	global_load_lds_dwordx4 v[150:151], off
	s_mov_b32 m0, s2
	v_readfirstlane_b32 s2, v128
	v_lshl_add_u64 v[148:149], v[138:139], 0, s[82:83]
	global_load_lds_dwordx4 v[146:147], off
	s_mov_b32 m0, s2
	s_nop 0
	global_load_lds_dwordx4 v[148:149], off

; DI int otid() { int t = threadIdx.x; asm volatile("" : "+v"(t)); return t; }
; DI void glds16(const void* g, unsigned char* l) { __builtin_amdgcn_global_load_lds((const unsigned*)g, (lds_u32*)l, 16, 0, 0); }
;     ...
;   const int tid = otid(), lane = tid & 63, w = tid >> 6, wr = w / WC, wc = w % WC, fr = lane & 15, fq = lane >> 4;
;   const int srow = tid >> 3, kch = (tid & 7) ^ ((tid >> 4) & 7);
;   const unsigned voA = (unsigned)(srow * lda + kch * 8) * 2u, voB = (unsigned)(srow * ldb + kch * 8) * 2u;
;   const char* Ab = (const char*)A;
;   const char* Bb = (const char*)B;
;   const int nk = K >> 6;
;   if (!primed) {
; #pragma unroll
;     for (int i = 0; i < NA; ++i) glds16(Ab + (size_t)i * 128 * lda + voA, smem + (i * 512 + tid) * 16);
; #pragma unroll
;     for (int i = 0; i < NB; ++i) glds16(Bb + (size_t)i * 128 * ldb + voB, smem + AB + (i * 512 + tid) * 16);
;   }
;   const int sw = (fr >> 1) & 7;
;   const unsigned lds_base = (unsigned)(size_t)(__attribute__((address_space(3))) unsigned char*)smem;
;   const unsigned a_row = (wr * 16 * MT + fr) * 128, b_row = AB + (wc * 16 * NT + fr) * 128;
; template <int MT, int NT>
; DI void zero_acc(f32x4 (&acc)[MT][NT]) {
; #pragma unroll
;   for (int m = 0; m < MT; ++m)
; #pragma unroll
;     for (int n = 0; n < NT; ++n) acc[m][n] = (f32x4){0.f, 0.f, 0.f, 0.f};
; }
.LBB0_898:
	v_ashrrev_i32_e32 v1, 6, v0
	v_lshrrev_b32_e32 v5, 30, v1
	v_add_u32_e32 v5, v1, v5
	v_ashrrev_i32_e32 v5, 2, v5
	s_add_i32 s16, s2, s22
	v_mul_i32_i24_e32 v6, 4, v5
	v_bfe_u32 v7, v0, 1, 3
	v_lshlrev_b32_e32 v0, 7, v0
	s_ashr_i32 s17, s16, 31
	v_sub_u32_e32 v1, v1, v6
	v_and_b32_e32 v0, 0x780, v0
	s_lshl_b64 s[16:17], s[16:17], 19
	v_readlane_b32 s40, v252, 0
	v_lshl_or_b32 v141, v5, 14, v0
	v_lshl_or_b32 v0, v1, 13, v0
	v_readlane_b32 s41, v252, 1
	s_add_u32 s16, s40, s16
	v_and_b32_e32 v6, 3, v4
	v_add_u32_e32 v142, 0x8000, v0
	v_bitop3_b32 v0, v4, v7, 3 bitop3:0x6c
	s_addc_u32 s17, s41, s17
	v_lshlrev_b32_e32 v140, 4, v0
	v_bitop3_b32 v0, v6, v7, 4 bitop3:0x36
	s_add_u32 s14, s19, s14
	v_lshlrev_b32_e32 v138, 4, v0
	v_add_u32_e32 v0, v2, v3
	v_mov_b32_e32 v1, v129
	s_addc_u32 s15, s20, s15
	v_readlane_b32 s42, v252, 2
	v_readlane_b32 s43, v252, 3
	v_lshl_add_u64 v[134:135], s[16:17], 0, v[0:1]
	v_lshl_add_u64 v[136:137], s[14:15], 0, v[0:1]
	v_mov_b32_e32 v0, 0
	s_mov_b32 s7, 0
	s_mov_b64 s[42:43], 0
	v_mov_b32_e32 v1, v0
	v_mov_b32_e32 v2, v0
	v_mov_b32_e32 v3, v0
	v_mov_b32_e32 v4, v0
	v_mov_b32_e32 v5, v0
	v_mov_b32_e32 v6, v0
	v_mov_b32_e32 v7, v0
	v_mov_b32_e32 v8, v0
	v_mov_b32_e32 v9, v0
	v_mov_b32_e32 v10, v0
	v_mov_b32_e32 v11, v0
	v_mov_b32_e32 v12, v0
	v_mov_b32_e32 v13, v0
	v_mov_b32_e32 v14, v0
	v_mov_b32_e32 v15, v0
	v_mov_b32_e32 v16, v0
	v_mov_b32_e32 v17, v0
	v_mov_b32_e32 v18, v0
	v_mov_b32_e32 v19, v0
	v_mov_b32_e32 v20, v0
	v_mov_b32_e32 v21, v0
	v_mov_b32_e32 v22, v0
	v_mov_b32_e32 v23, v0
	v_mov_b32_e32 v24, v0
	v_mov_b32_e32 v25, v0
	v_mov_b32_e32 v26, v0
	v_mov_b32_e32 v27, v0
	v_mov_b32_e32 v28, v0
	v_mov_b32_e32 v29, v0
	v_mov_b32_e32 v30, v0
	v_mov_b32_e32 v31, v0
	v_mov_b32_e32 v32, v0
	v_mov_b32_e32 v33, v0
	v_mov_b32_e32 v34, v0
	v_mov_b32_e32 v35, v0
	v_mov_b32_e32 v36, v0
	v_mov_b32_e32 v37, v0
	v_mov_b32_e32 v38, v0
	v_mov_b32_e32 v39, v0
	v_mov_b32_e32 v40, v0
	v_mov_b32_e32 v41, v0
	v_mov_b32_e32 v42, v0
	v_mov_b32_e32 v43, v0
	v_mov_b32_e32 v44, v0
	v_mov_b32_e32 v45, v0
	v_mov_b32_e32 v46, v0
	v_mov_b32_e32 v47, v0
	v_mov_b32_e32 v48, v0
	v_mov_b32_e32 v49, v0
	v_mov_b32_e32 v50, v0
	v_mov_b32_e32 v51, v0
	v_mov_b32_e32 v52, v0
	v_mov_b32_e32 v53, v0
	v_mov_b32_e32 v54, v0
	v_mov_b32_e32 v55, v0
	v_mov_b32_e32 v56, v0
	v_mov_b32_e32 v57, v0
	v_mov_b32_e32 v58, v0
	v_mov_b32_e32 v59, v0
	v_mov_b32_e32 v60, v0
	v_mov_b32_e32 v61, v0
	v_mov_b32_e32 v62, v0
	v_mov_b32_e32 v63, v0
	v_mov_b32_e32 v64, v0
	v_mov_b32_e32 v65, v0
	v_mov_b32_e32 v66, v0
	v_mov_b32_e32 v67, v0
	v_mov_b32_e32 v68, v0
	v_mov_b32_e32 v69, v0
	v_mov_b32_e32 v70, v0
	v_mov_b32_e32 v71, v0
	v_mov_b32_e32 v72, v0
	v_mov_b32_e32 v73, v0
	v_mov_b32_e32 v74, v0
	v_mov_b32_e32 v75, v0
	v_mov_b32_e32 v76, v0
	v_mov_b32_e32 v77, v0
	v_mov_b32_e32 v78, v0
	v_mov_b32_e32 v79, v0
	v_mov_b32_e32 v80, v0
	v_mov_b32_e32 v81, v0
	v_mov_b32_e32 v82, v0
	v_mov_b32_e32 v83, v0
	v_mov_b32_e32 v84, v0
	v_mov_b32_e32 v85, v0
	v_mov_b32_e32 v86, v0
	v_mov_b32_e32 v87, v0
	v_mov_b32_e32 v88, v0
	v_mov_b32_e32 v89, v0
	v_mov_b32_e32 v90, v0
	v_mov_b32_e32 v91, v0
	v_mov_b32_e32 v92, v0
	v_mov_b32_e32 v93, v0
	v_mov_b32_e32 v94, v0
	v_mov_b32_e32 v95, v0
	v_mov_b32_e32 v96, v0
	v_mov_b32_e32 v97, v0
	v_mov_b32_e32 v98, v0
	v_mov_b32_e32 v99, v0
	v_mov_b32_e32 v100, v0
	v_mov_b32_e32 v101, v0
	v_mov_b32_e32 v102, v0
	v_mov_b32_e32 v103, v0
	v_mov_b32_e32 v104, v0
	v_mov_b32_e32 v105, v0
	v_mov_b32_e32 v106, v0
	v_mov_b32_e32 v107, v0
	v_mov_b32_e32 v108, v0
	v_mov_b32_e32 v109, v0
	v_mov_b32_e32 v110, v0
	v_mov_b32_e32 v111, v0
	v_mov_b32_e32 v112, v0
	v_mov_b32_e32 v113, v0
	v_mov_b32_e32 v114, v0
	v_mov_b32_e32 v115, v0
	v_mov_b32_e32 v116, v0
	v_mov_b32_e32 v117, v0
	v_mov_b32_e32 v118, v0
	v_mov_b32_e32 v119, v0
	v_mov_b32_e32 v120, v0
	v_mov_b32_e32 v121, v0
	v_mov_b32_e32 v122, v0
	v_mov_b32_e32 v123, v0
	v_mov_b32_e32 v124, v0
	v_mov_b32_e32 v125, v0
	v_mov_b32_e32 v126, v0
	v_mov_b32_e32 v127, v0
	v_mov_b32_e32 v188, 0
	v_mov_b32_e32 v189, 0
	v_mov_b32_e32 v190, 0
	v_mov_b32_e32 v191, 0
	v_mov_b32_e32 v192, 0
	v_mov_b32_e32 v193, 0
	v_mov_b32_e32 v194, 0
	v_mov_b32_e32 v195, 0
	v_mov_b32_e32 v196, 0
	v_mov_b32_e32 v197, 0
	v_mov_b32_e32 v198, 0
	v_mov_b32_e32 v199, 0
	v_mov_b32_e32 v200, 0
	v_mov_b32_e32 v201, 0
	v_mov_b32_e32 v202, 0
	v_mov_b32_e32 v203, 0
	v_mov_b32_e32 v204, 0
	v_mov_b32_e32 v205, 0
	v_mov_b32_e32 v206, 0
	v_mov_b32_e32 v207, 0
	v_mov_b32_e32 v208, 0
	v_mov_b32_e32 v209, 0
	v_mov_b32_e32 v210, 0
	v_mov_b32_e32 v211, 0
	v_mov_b32_e32 v228, 0
	v_mov_b32_e32 v229, 0
	v_mov_b32_e32 v230, 0
	v_mov_b32_e32 v231, 0
	v_mov_b32_e32 v232, 0
	v_mov_b32_e32 v233, 0
	v_mov_b32_e32 v234, 0
	v_mov_b32_e32 v235, 0
	v_lshrrev_b32_e32 v240, 8, v212
	s_nop 0
	v_readfirstlane_b32 s98, v240
	s_cmp_eq_u32 s98, 0
	s_cbranch_scc1 .Lprio_4
	s_setprio 1
; #define MFMA16(a, b, c) __builtin_amdgcn_mfma_f32_16x16x32_bf16((a), (b), (c), 0, 0, 0)
; DI void glds16(const void* g, unsigned char* l) { __builtin_amdgcn_global_load_lds((const unsigned*)g, (lds_u32*)l, 16, 0, 0); }
; template <int N> DI void wait_vm() { asm volatile("s_waitcnt vmcnt(%0)" :: "n"(N) : "memory"); }
;     ...
;   for (int kt = 0; kt < nk; ++kt) {
;     wait_vm<0>();
;     __builtin_amdgcn_s_barrier();
;     if (kt + 1 < nk) {
;       unsigned char* sn = smem + ((kt + 1) & 1) * STG;
;       const int ko = (kt + 1) * 64;
; #pragma unroll
;       for (int i = 0; i < NA; ++i) glds16(Ab + ((size_t)i * 128 * lda + ko * 2) + voA, sn + (i * 512 + tid) * 16);
; #pragma unroll
;       for (int i = 0; i < NB; ++i) glds16(Bb + ((size_t)i * 128 * ldb + ko * 2) + voB, sn + AB + (i * 512 + tid) * 16);
;     } else if (nA) {
;       const unsigned nvoA = (unsigned)(srow * nlda + kch * 8) * 2u, nvoB = (unsigned)(srow * nldb + kch * 8) * 2u;
; #pragma unroll
;       for (int i = 0; i < NA; ++i) glds16((const char*)nA + (size_t)i * 128 * nlda + nvoA, smem + (i * 512 + tid) * 16);
; #pragma unroll
;       for (int i = 0; i < NB; ++i) glds16((const char*)nB + (size_t)i * 128 * nldb + nvoB, smem + AB + (i * 512 + tid) * 16);
;     }
;     const unsigned stb = lds_base + (kt & 1) * STG;
; #pragma unroll
;     for (int ks = 0; ks < 2; ++ks) {
;       const unsigned co = ((ks * 4 + fq) ^ sw) * 16;
;       const unsigned sa = stb + a_row + co, sb = stb + b_row + co;
;       bf16x8 af[4], bfr[NT];
; #pragma unroll
;       for (int n = 0; n < NT; ++n) asm volatile("ds_read_b128 %0, %1 offset:%2" : "=v"(bfr[n]) : "v"(sb), "n"(n * 2048) : "memory");
; #pragma unroll
;       for (int mg = 0; mg < MT / 4; ++mg) {
; #pragma unroll
;         for (int m = 0; m < 4; ++m) asm volatile("ds_read_b128 %0, %1 offset:%2" : "=v"(af[m]) : "v"(sa), "n"((mg * 4 + m) * 2048) : "memory");
;         if (mg == 0) {
; #pragma unroll
;           for (int n = 0; n < NT; ++n) asm volatile("s_waitcnt lgkmcnt(%1)" : "+v"(bfr[n]) : "n"(4 + NT - 1 - n) : "memory");
;         }
; #pragma unroll
;         for (int m = 0; m < 4; ++m) {
;           asm volatile("s_waitcnt lgkmcnt(%1)" : "+v"(af[m]) : "n"(3 - m) : "memory");
; #pragma unroll
;           for (int n = 0; n < NT; ++n) acc[mg * 4 + m][n] = MFMA16(bfr[n], af[m], acc[mg * 4 + m][n]);
;         }
;       }
.Lprio_4:
.LBB0_899:
	s_add_i32 s2, s7, 0x10000
	s_and_b32 s14, s2, 0x10000
	v_add_u32_e32 v143, s14, v139
	v_lshl_add_u64 v[144:145], v[134:135], 0, s[42:43]
	v_readfirstlane_b32 s14, v143
	v_add_u32_e32 v148, 0x2000, v143
	v_lshl_add_u64 v[146:147], v[144:145], 0, s[58:59]
	s_mov_b32 m0, s14
	v_readfirstlane_b32 s14, v148
	v_add_u32_e32 v148, 0x4000, v143
	s_waitcnt vmcnt(0)
	s_waitcnt lgkmcnt(0)
	s_barrier
	s_and_b32 s7, s7, 0x10000
	v_add_u32_e32 v240, s7, v142
	v_add_u32_e32 v236, v240, v140
	v_add_u32_e32 v237, v240, v138
	v_add_u32_e32 v240, s7, v141
	v_add_u32_e32 v238, v240, v140
	v_add_u32_e32 v239, v240, v138
	v_mfma_f32_16x16x32_bf16 v[60:63], v[188:191], v[204:207], v[60:63]
	ds_read_b128 v[152:155], v236 offset:0
	ds_read_b128 v[156:159], v236 offset:2048
	v_mfma_f32_16x16x32_bf16 v[56:59], v[192:195], v[204:207], v[56:59]
	ds_read_b128 v[160:163], v236 offset:4096
	ds_read_b128 v[164:167], v236 offset:6144
	global_load_lds_dwordx4 v[146:147], off
	v_mfma_f32_16x16x32_bf16 v[52:55], v[196:199], v[204:207], v[52:55]
	ds_read_b128 v[168:171], v238 offset:0
	ds_read_b128 v[172:175], v238 offset:2048
	v_mfma_f32_16x16x32_bf16 v[48:51], v[200:203], v[204:207], v[48:51]
	ds_read_b128 v[180:183], v238 offset:4096
	ds_read_b128 v[184:187], v238 offset:6144
	v_mfma_f32_16x16x32_bf16 v[44:47], v[188:191], v[208:211], v[44:47]
	v_mfma_f32_16x16x32_bf16 v[40:43], v[192:195], v[208:211], v[40:43]
	v_mfma_f32_16x16x32_bf16 v[36:39], v[196:199], v[208:211], v[36:39]
	v_lshl_add_u64 v[146:147], v[144:145], 0, s[60:61]
	s_mov_b32 m0, s14
	v_readfirstlane_b32 s14, v148
	global_load_lds_dwordx4 v[146:147], off
	v_mfma_f32_16x16x32_bf16 v[32:35], v[200:203], v[208:211], v[32:35]
	v_mfma_f32_16x16x32_bf16 v[28:31], v[188:191], v[228:231], v[28:31]
	v_mfma_f32_16x16x32_bf16 v[24:27], v[192:195], v[228:231], v[24:27]
	v_mfma_f32_16x16x32_bf16 v[20:23], v[196:199], v[228:231], v[20:23]
	v_mfma_f32_16x16x32_bf16 v[16:19], v[200:203], v[228:231], v[16:19]
	v_lshl_add_u64 v[146:147], v[144:145], 0, s[62:63]
	s_mov_b32 m0, s14
	v_lshl_add_u64 v[144:145], v[144:145], 0, s[64:65]
	global_load_lds_dwordx4 v[146:147], off
	v_mfma_f32_16x16x32_bf16 v[12:15], v[188:191], v[232:235], v[12:15]
	v_mfma_f32_16x16x32_bf16 v[8:11], v[192:195], v[232:235], v[8:11]
	v_mfma_f32_16x16x32_bf16 v[4:7], v[196:199], v[232:235], v[4:7]
	v_mfma_f32_16x16x32_bf16 v[0:3], v[200:203], v[232:235], v[0:3]
	s_waitcnt lgkmcnt(3)
	v_mfma_f32_16x16x32_bf16 v[124:127], v[152:155], v[168:171], v[124:127]
	v_add_u32_e32 v146, 0x6000, v143
	v_add_u32_e32 v148, 0x8000, v143
	v_readfirstlane_b32 s14, v146
	s_mov_b32 m0, s14
	s_mov_b64 s[14:15], 0x1088080
	global_load_lds_dwordx4 v[144:145], off
	v_mfma_f32_16x16x32_bf16 v[120:123], v[156:159], v[168:171], v[120:123]
	ds_read_b128 v[204:207], v238 offset:8192
	v_mfma_f32_16x16x32_bf16 v[116:119], v[160:163], v[168:171], v[116:119]
	v_mfma_f32_16x16x32_bf16 v[112:115], v[164:167], v[168:171], v[112:115]
	ds_read_b128 v[208:211], v238 offset:10240
	s_waitcnt lgkmcnt(4)
	v_mfma_f32_16x16x32_bf16 v[108:111], v[152:155], v[172:175], v[108:111]
	v_mfma_f32_16x16x32_bf16 v[104:107], v[156:159], v[172:175], v[104:107]
	ds_read_b128 v[228:231], v238 offset:12288
	v_lshl_add_u64 v[144:145], v[136:137], 0, s[42:43]
	v_lshl_add_u64 v[146:147], v[144:145], 0, s[14:15]
	v_readfirstlane_b32 s14, v148
	s_mov_b32 m0, s14
	s_mov_b64 s[14:15], 0x10a8080
	v_add_u32_e32 v148, 0xa000, v143
	global_load_lds_dwordx4 v[146:147], off
	v_mfma_f32_16x16x32_bf16 v[100:103], v[160:163], v[172:175], v[100:103]
	v_mfma_f32_16x16x32_bf16 v[96:99], v[164:167], v[172:175], v[96:99]
	ds_read_b128 v[232:235], v238 offset:14336
	s_waitcnt lgkmcnt(5)
	v_mfma_f32_16x16x32_bf16 v[92:95], v[152:155], v[180:183], v[92:95]
	v_mfma_f32_16x16x32_bf16 v[88:91], v[156:159], v[180:183], v[88:91]
	ds_read_b128 v[188:191], v237 offset:0
	v_mfma_f32_16x16x32_bf16 v[84:87], v[160:163], v[180:183], v[84:87]
	v_lshl_add_u64 v[146:147], v[144:145], 0, s[14:15]
	v_readfirstlane_b32 s14, v148
	s_mov_b32 m0, s14
	s_mov_b64 s[14:15], 0x10c8080
	v_add_u32_e32 v148, 0xc000, v143
	global_load_lds_dwordx4 v[146:147], off
	v_mfma_f32_16x16x32_bf16 v[80:83], v[164:167], v[180:183], v[80:83]
	ds_read_b128 v[192:195], v237 offset:2048
	s_waitcnt lgkmcnt(6)
	v_mfma_f32_16x16x32_bf16 v[76:79], v[152:155], v[184:187], v[76:79]
	v_mfma_f32_16x16x32_bf16 v[72:75], v[156:159], v[184:187], v[72:75]
	ds_read_b128 v[196:199], v237 offset:4096
	v_mfma_f32_16x16x32_bf16 v[68:71], v[160:163], v[184:187], v[68:71]
	v_mfma_f32_16x16x32_bf16 v[64:67], v[164:167], v[184:187], v[64:67]
	ds_read_b128 v[200:203], v237 offset:6144
	v_lshl_add_u64 v[146:147], v[144:145], 0, s[14:15]
	v_readfirstlane_b32 s14, v148
	s_mov_b32 m0, s14
	s_mov_b64 s[14:15], 0x10e8080
	v_add_u32_e32 v143, 0xe000, v143
	v_lshl_add_u64 v[144:145], v[144:145], 0, s[14:15]
	v_readfirstlane_b32 s14, v143
	global_load_lds_dwordx4 v[146:147], off
	s_waitcnt lgkmcnt(7)
	v_mfma_f32_16x16x32_bf16 v[60:63], v[152:155], v[204:207], v[60:63]
	v_mfma_f32_16x16x32_bf16 v[56:59], v[156:159], v[204:207], v[56:59]
	ds_read_b128 v[168:171], v239 offset:0
	v_mfma_f32_16x16x32_bf16 v[52:55], v[160:163], v[204:207], v[52:55]
	v_mfma_f32_16x16x32_bf16 v[48:51], v[164:167], v[204:207], v[48:51]
	ds_read_b128 v[172:175], v239 offset:2048
	s_waitcnt lgkmcnt(8)
; #define MFMA16(a, b, c) __builtin_amdgcn_mfma_f32_16x16x32_bf16((a), (b), (c), 0, 0, 0)
; DI void glds16(const void* g, unsigned char* l) { __builtin_amdgcn_global_load_lds((const unsigned*)g, (lds_u32*)l, 16, 0, 0); }
; template <int N> DI void wait_vm() { asm volatile("s_waitcnt vmcnt(%0)" :: "n"(N) : "memory"); }
;     ...
;   for (int kt = 0; kt < nk; ++kt) {
;     wait_vm<0>();
;     __builtin_amdgcn_s_barrier();
;     if (kt + 1 < nk) {
;       unsigned char* sn = smem + ((kt + 1) & 1) * STG;
;       const int ko = (kt + 1) * 64;
; #pragma unroll
;       for (int i = 0; i < NA; ++i) glds16(Ab + ((size_t)i * 128 * lda + ko * 2) + voA, sn + (i * 512 + tid) * 16);
; #pragma unroll
;       for (int i = 0; i < NB; ++i) glds16(Bb + ((size_t)i * 128 * ldb + ko * 2) + voB, sn + AB + (i * 512 + tid) * 16);
;     } else if (nA) {
;       const unsigned nvoA = (unsigned)(srow * nlda + kch * 8) * 2u, nvoB = (unsigned)(srow * nldb + kch * 8) * 2u;
; #pragma unroll
;       for (int i = 0; i < NA; ++i) glds16((const char*)nA + (size_t)i * 128 * nlda + nvoA, smem + (i * 512 + tid) * 16);
; #pragma unroll
;       for (int i = 0; i < NB; ++i) glds16((const char*)nB + (size_t)i * 128 * nldb + nvoB, smem + AB + (i * 512 + tid) * 16);
;     }
;     const unsigned stb = lds_base + (kt & 1) * STG;
; #pragma unroll
;     for (int ks = 0; ks < 2; ++ks) {
;       const unsigned co = ((ks * 4 + fq) ^ sw) * 16;
;       const unsigned sa = stb + a_row + co, sb = stb + b_row + co;
;       bf16x8 af[4], bfr[NT];
; #pragma unroll
;       for (int n = 0; n < NT; ++n) asm volatile("ds_read_b128 %0, %1 offset:%2" : "=v"(bfr[n]) : "v"(sb), "n"(n * 2048) : "memory");
; #pragma unroll
;       for (int mg = 0; mg < MT / 4; ++mg) {
; #pragma unroll
;         for (int m = 0; m < 4; ++m) asm volatile("ds_read_b128 %0, %1 offset:%2" : "=v"(af[m]) : "v"(sa), "n"((mg * 4 + m) * 2048) : "memory");
;         if (mg == 0) {
; #pragma unroll
;           for (int n = 0; n < NT; ++n) asm volatile("s_waitcnt lgkmcnt(%1)" : "+v"(bfr[n]) : "n"(4 + NT - 1 - n) : "memory");
;         }
; #pragma unroll
;         for (int m = 0; m < 4; ++m) {
;           asm volatile("s_waitcnt lgkmcnt(%1)" : "+v"(af[m]) : "n"(3 - m) : "memory");
; #pragma unroll
;           for (int n = 0; n < NT; ++n) acc[mg * 4 + m][n] = MFMA16(bfr[n], af[m], acc[mg * 4 + m][n]);
;         }
;       }
	v_mfma_f32_16x16x32_bf16 v[44:47], v[152:155], v[208:211], v[44:47]
	s_mov_b32 m0, s14
	s_nop 0
	global_load_lds_dwordx4 v[144:145], off
	v_mfma_f32_16x16x32_bf16 v[40:43], v[156:159], v[208:211], v[40:43]
	ds_read_b128 v[180:183], v239 offset:4096
	v_mfma_f32_16x16x32_bf16 v[36:39], v[160:163], v[208:211], v[36:39]
	v_mfma_f32_16x16x32_bf16 v[32:35], v[164:167], v[208:211], v[32:35]
	ds_read_b128 v[184:187], v239 offset:6144
	s_waitcnt lgkmcnt(9)
	v_mfma_f32_16x16x32_bf16 v[28:31], v[152:155], v[228:231], v[28:31]
	v_mfma_f32_16x16x32_bf16 v[24:27], v[156:159], v[228:231], v[24:27]
	v_mfma_f32_16x16x32_bf16 v[20:23], v[160:163], v[228:231], v[20:23]
	v_mfma_f32_16x16x32_bf16 v[16:19], v[164:167], v[228:231], v[16:19]
	s_waitcnt lgkmcnt(8)
	v_mfma_f32_16x16x32_bf16 v[12:15], v[152:155], v[232:235], v[12:15]
	v_mfma_f32_16x16x32_bf16 v[8:11], v[156:159], v[232:235], v[8:11]
	v_mfma_f32_16x16x32_bf16 v[4:7], v[160:163], v[232:235], v[4:7]
	v_mfma_f32_16x16x32_bf16 v[0:3], v[164:167], v[232:235], v[0:3]
	s_waitcnt lgkmcnt(3)
	v_mfma_f32_16x16x32_bf16 v[124:127], v[188:191], v[168:171], v[124:127]
	v_mfma_f32_16x16x32_bf16 v[120:123], v[192:195], v[168:171], v[120:123]
	ds_read_b128 v[204:207], v239 offset:8192
	v_mfma_f32_16x16x32_bf16 v[116:119], v[196:199], v[168:171], v[116:119]
	v_mfma_f32_16x16x32_bf16 v[112:115], v[200:203], v[168:171], v[112:115]
	ds_read_b128 v[208:211], v239 offset:10240
	s_waitcnt lgkmcnt(4)
	v_mfma_f32_16x16x32_bf16 v[108:111], v[188:191], v[172:175], v[108:111]
	v_mfma_f32_16x16x32_bf16 v[104:107], v[192:195], v[172:175], v[104:107]
	ds_read_b128 v[228:231], v239 offset:12288
	v_mfma_f32_16x16x32_bf16 v[100:103], v[196:199], v[172:175], v[100:103]
	v_mfma_f32_16x16x32_bf16 v[96:99], v[200:203], v[172:175], v[96:99]
	ds_read_b128 v[232:235], v239 offset:14336
	s_waitcnt lgkmcnt(5)
	v_mfma_f32_16x16x32_bf16 v[92:95], v[188:191], v[180:183], v[92:95]
	v_mfma_f32_16x16x32_bf16 v[88:91], v[192:195], v[180:183], v[88:91]
	v_mfma_f32_16x16x32_bf16 v[84:87], v[196:199], v[180:183], v[84:87]
	v_mfma_f32_16x16x32_bf16 v[80:83], v[200:203], v[180:183], v[80:83]
	s_waitcnt lgkmcnt(4)
	v_mfma_f32_16x16x32_bf16 v[76:79], v[188:191], v[184:187], v[76:79]
	v_mfma_f32_16x16x32_bf16 v[72:75], v[192:195], v[184:187], v[72:75]
	v_mfma_f32_16x16x32_bf16 v[68:71], v[196:199], v[184:187], v[68:71]
	v_mfma_f32_16x16x32_bf16 v[64:67], v[200:203], v[184:187], v[64:67]
	s_add_u32 s42, s42, 0x80
	s_addc_u32 s43, s43, 0
	s_cmpk_eq_i32 s42, 0x780
	s_mov_b32 s7, s2
	s_cbranch_scc0 .LBB0_899
	s_waitcnt lgkmcnt(0)
	v_mfma_f32_16x16x32_bf16 v[60:63], v[188:191], v[204:207], v[60:63]
	v_mfma_f32_16x16x32_bf16 v[56:59], v[192:195], v[204:207], v[56:59]
	v_mfma_f32_16x16x32_bf16 v[52:55], v[196:199], v[204:207], v[52:55]
	v_mfma_f32_16x16x32_bf16 v[48:51], v[200:203], v[204:207], v[48:51]
	v_mfma_f32_16x16x32_bf16 v[44:47], v[188:191], v[208:211], v[44:47]
	v_mfma_f32_16x16x32_bf16 v[40:43], v[192:195], v[208:211], v[40:43]
	v_mfma_f32_16x16x32_bf16 v[36:39], v[196:199], v[208:211], v[36:39]
	v_mfma_f32_16x16x32_bf16 v[32:35], v[200:203], v[208:211], v[32:35]
	v_mfma_f32_16x16x32_bf16 v[28:31], v[188:191], v[228:231], v[28:31]
	v_mfma_f32_16x16x32_bf16 v[24:27], v[192:195], v[228:231], v[24:27]
	v_mfma_f32_16x16x32_bf16 v[20:23], v[196:199], v[228:231], v[20:23]
	v_mfma_f32_16x16x32_bf16 v[16:19], v[200:203], v[228:231], v[16:19]
	v_mfma_f32_16x16x32_bf16 v[12:15], v[188:191], v[232:235], v[12:15]
	v_mfma_f32_16x16x32_bf16 v[8:11], v[192:195], v[232:235], v[8:11]
	v_mfma_f32_16x16x32_bf16 v[4:7], v[196:199], v[232:235], v[4:7]
	v_mfma_f32_16x16x32_bf16 v[0:3], v[200:203], v[232:235], v[0:3]
	s_setprio 0
	s_waitcnt vmcnt(0)
	s_andn2_b64 vcc, exec, s[12:13]
	s_barrier
	v_readlane_b32 s41, v254, 60
	s_cbranch_vccnz .LBB0_902
	s_add_u32 s2, s54, s10
	s_addc_u32 s7, s55, s11
	s_and_b64 s[10:11], exec, s[0:1]
	s_cselect_b32 s11, 0, s7
	s_cselect_b32 s10, 0, s2
	v_readfirstlane_b32 s2, v139
	v_lshl_add_u64 v[134:135], s[10:11], 0, v[128:129]
	s_mov_b32 m0, s2
	v_lshl_add_u64 v[144:145], v[134:135], 0, s[80:81]
	v_lshl_add_u64 v[152:153], v[134:135], 0, s[82:83]
	v_lshl_add_u64 v[154:155], v[134:135], 0, s[70:71]
	global_load_lds_dwordx4 v[134:135], off
	v_add_u32_e32 v134, 0x2000, v139
	v_add_u32_e32 v143, 0x4000, v139
	v_readfirstlane_b32 s2, v134
	s_mov_b32 m0, s2
	v_readfirstlane_b32 s2, v143
	v_add_u32_e32 v134, 0x6000, v139
	s_add_u32 s12, s8, s38
	global_load_lds_dwordx4 v[154:155], off
	s_mov_b32 m0, s2
	v_readfirstlane_b32 s2, v134
	v_add_u32_e32 v134, 0x8000, v139
	s_addc_u32 s13, s18, s39
	global_load_lds_dwordx4 v[144:145], off
	s_mov_b32 m0, s2
	v_readfirstlane_b32 s2, v134
	v_add_u32_e32 v134, 0xa000, v139
	v_lshl_add_u64 v[136:137], s[12:13], 0, v[128:129]
	v_add_u32_e32 v128, 0xc000, v139
	global_load_lds_dwordx4 v[152:153], off
	s_mov_b32 m0, s2
	v_readfirstlane_b32 s2, v134
	v_lshl_add_u64 v[150:151], v[136:137], 0, s[70:71]
	global_load_lds_dwordx4 v[136:137], off
	s_mov_b32 m0, s2
	v_readfirstlane_b32 s2, v128
	v_add_u32_e32 v128, 0xe000, v139
	v_lshl_add_u64 v[146:147], v[136:137], 0, s[80:81]
	global_load_lds_dwordx4 v[150:151], off
	s_mov_b32 m0, s2
	v_readfirstlane_b32 s2, v128
	v_lshl_add_u64 v[148:149], v[136:137], 0, s[82:83]
	global_load_lds_dwordx4 v[146:147], off
	s_mov_b32 m0, s2
	s_nop 0
	global_load_lds_dwordx4 v[148:149], off

; template <int MT, int NT>
; DI void zero_acc(f32x4 (&acc)[MT][NT]) {
; #pragma unroll
;   for (int m = 0; m < MT; ++m)
; #pragma unroll
;     for (int n = 0; n < NT; ++n) acc[m][n] = (f32x4){0.f, 0.f, 0.f, 0.f};
; }
; DI void phase_gemm_resid(const bf16_t* __restrict__ A, int K, const bf16_t* __restrict__ Bt, const float* __restrict__ xin, float* __restrict__ xout, float alpha, unsigned char* smem) {
;     ...
;   for (int id = blockIdx.x; id < nM * nN; id += gridDim.x) {
;     int pm, pn; tile_coords(id, nN, pm, pn);
;     f32x4 acc[8][4]; zero_acc(acc);
;     {
;       const int idn = id + gridDim.x; int pm2 = 0, pn2 = 0; const bool hn = idn < nM * nN; if (hn) tile_coords(idn, nN, pm2, pn2);
;       gemm_block<8, 4, 2, 4>(A + (size_t)pm * 256 * K, K, Bt + (size_t)pn * 256 * K, K, K, acc, smem, id != (int)blockIdx.x,
;                              hn ? A + (size_t)pm2 * 256 * K : nullptr, K, Bt + (size_t)pn2 * 256 * K, K);
.LBB0_966:
	v_ashrrev_i32_e32 v1, 6, v0
	v_lshrrev_b32_e32 v5, 30, v1
	v_add_u32_e32 v5, v1, v5
	v_ashrrev_i32_e32 v5, 2, v5
	v_mul_i32_i24_e32 v6, 4, v5
	v_bfe_u32 v7, v0, 1, 3
	v_lshlrev_b32_e32 v0, 7, v0
	v_sub_u32_e32 v1, v1, v6
	v_and_b32_e32 v0, 0x780, v0
	s_add_i32 s16, s22, s23
	v_lshl_or_b32 v141, v5, 14, v0
	v_lshl_or_b32 v0, v1, 13, v0
	s_mul_hi_i32 s17, s16, 0x160000
	s_mul_i32 s16, s16, 0x160000
	v_readlane_b32 s36, v252, 0
	v_and_b32_e32 v6, 3, v4
	v_add_u32_e32 v142, 0x8000, v0
	v_bitop3_b32 v0, v4, v7, 3 bitop3:0x6c
	v_readlane_b32 s37, v252, 1
	s_add_u32 s16, s36, s16
	v_lshlrev_b32_e32 v140, 4, v0
	v_bitop3_b32 v0, v6, v7, 4 bitop3:0x36
	s_movk_i32 s22, 0x1600
	s_addc_u32 s17, s37, s17
	s_lshl_b64 s[14:15], s[14:15], 1
	v_lshlrev_b32_e32 v131, 4, v0
	v_mul_lo_u32 v0, v2, s22
	v_and_b32_e32 v1, 7, v3
	s_add_u32 s14, s19, s14
	v_lshl_or_b32 v0, v1, 4, v0
	v_mov_b32_e32 v1, v129
	s_addc_u32 s15, s20, s15
	v_readlane_b32 s38, v252, 2
	v_readlane_b32 s39, v252, 3
	v_lshl_add_u64 v[136:137], s[16:17], 0, v[0:1]
	v_lshl_add_u64 v[138:139], s[14:15], 0, v[0:1]
	v_mov_b32_e32 v0, 0
	s_mov_b64 s[38:39], 0
	s_mov_b32 s15, 0
	v_mov_b32_e32 v1, v0
	v_mov_b32_e32 v2, v0
	v_mov_b32_e32 v3, v0
	v_mov_b32_e32 v4, v0
	v_mov_b32_e32 v5, v0
	v_mov_b32_e32 v6, v0
	v_mov_b32_e32 v7, v0
	v_mov_b32_e32 v8, v0
	v_mov_b32_e32 v9, v0
	v_mov_b32_e32 v10, v0
	v_mov_b32_e32 v11, v0
	v_mov_b32_e32 v12, v0
	v_mov_b32_e32 v13, v0
	v_mov_b32_e32 v14, v0
	v_mov_b32_e32 v15, v0
	v_mov_b32_e32 v16, v0
	v_mov_b32_e32 v17, v0
	v_mov_b32_e32 v18, v0
	v_mov_b32_e32 v19, v0
	v_mov_b32_e32 v20, v0
	v_mov_b32_e32 v21, v0
	v_mov_b32_e32 v22, v0
	v_mov_b32_e32 v23, v0
	v_mov_b32_e32 v24, v0
	v_mov_b32_e32 v25, v0
	v_mov_b32_e32 v26, v0
	v_mov_b32_e32 v27, v0
	v_mov_b32_e32 v28, v0
	v_mov_b32_e32 v29, v0
	v_mov_b32_e32 v30, v0
	v_mov_b32_e32 v31, v0
	v_mov_b32_e32 v32, v0
	v_mov_b32_e32 v33, v0
	v_mov_b32_e32 v34, v0
	v_mov_b32_e32 v35, v0
	v_mov_b32_e32 v36, v0
	v_mov_b32_e32 v37, v0
	v_mov_b32_e32 v38, v0
	v_mov_b32_e32 v39, v0
	v_mov_b32_e32 v40, v0
	v_mov_b32_e32 v41, v0
	v_mov_b32_e32 v42, v0
	v_mov_b32_e32 v43, v0
	v_mov_b32_e32 v44, v0
	v_mov_b32_e32 v45, v0
	v_mov_b32_e32 v46, v0
	v_mov_b32_e32 v47, v0
	v_mov_b32_e32 v48, v0
	v_mov_b32_e32 v49, v0
	v_mov_b32_e32 v50, v0
	v_mov_b32_e32 v51, v0
	v_mov_b32_e32 v52, v0
	v_mov_b32_e32 v53, v0
	v_mov_b32_e32 v54, v0
	v_mov_b32_e32 v55, v0
	v_mov_b32_e32 v56, v0
	v_mov_b32_e32 v57, v0
	v_mov_b32_e32 v58, v0
	v_mov_b32_e32 v59, v0
	v_mov_b32_e32 v60, v0
	v_mov_b32_e32 v61, v0
	v_mov_b32_e32 v62, v0
	v_mov_b32_e32 v63, v0
	v_mov_b32_e32 v64, v0
	v_mov_b32_e32 v65, v0
	v_mov_b32_e32 v66, v0
	v_mov_b32_e32 v67, v0
	v_mov_b32_e32 v68, v0
	v_mov_b32_e32 v69, v0
	v_mov_b32_e32 v70, v0
	v_mov_b32_e32 v71, v0
	v_mov_b32_e32 v72, v0
	v_mov_b32_e32 v73, v0
	v_mov_b32_e32 v74, v0
	v_mov_b32_e32 v75, v0
	v_mov_b32_e32 v76, v0
	v_mov_b32_e32 v77, v0
	v_mov_b32_e32 v78, v0
	v_mov_b32_e32 v79, v0
	v_mov_b32_e32 v80, v0
	v_mov_b32_e32 v81, v0
	v_mov_b32_e32 v82, v0
	v_mov_b32_e32 v83, v0
	v_mov_b32_e32 v84, v0
	v_mov_b32_e32 v85, v0
	v_mov_b32_e32 v86, v0
	v_mov_b32_e32 v87, v0
	v_mov_b32_e32 v88, v0
	v_mov_b32_e32 v89, v0
	v_mov_b32_e32 v90, v0
	v_mov_b32_e32 v91, v0
	v_mov_b32_e32 v92, v0
	v_mov_b32_e32 v93, v0
	v_mov_b32_e32 v94, v0
	v_mov_b32_e32 v95, v0
	v_mov_b32_e32 v96, v0
	v_mov_b32_e32 v97, v0
	v_mov_b32_e32 v98, v0
	v_mov_b32_e32 v99, v0
	v_mov_b32_e32 v100, v0
	v_mov_b32_e32 v101, v0
	v_mov_b32_e32 v102, v0
	v_mov_b32_e32 v103, v0
	v_mov_b32_e32 v104, v0
	v_mov_b32_e32 v105, v0
	v_mov_b32_e32 v106, v0
	v_mov_b32_e32 v107, v0
	v_mov_b32_e32 v108, v0
	v_mov_b32_e32 v109, v0
	v_mov_b32_e32 v110, v0
	v_mov_b32_e32 v111, v0
	v_mov_b32_e32 v112, v0
	v_mov_b32_e32 v113, v0
	v_mov_b32_e32 v114, v0
	v_mov_b32_e32 v115, v0
	v_mov_b32_e32 v116, v0
	v_mov_b32_e32 v117, v0
	v_mov_b32_e32 v118, v0
	v_mov_b32_e32 v119, v0
	v_mov_b32_e32 v120, v0
	v_mov_b32_e32 v121, v0
	v_mov_b32_e32 v122, v0
	v_mov_b32_e32 v123, v0
	v_mov_b32_e32 v124, v0
	v_mov_b32_e32 v125, v0
	v_mov_b32_e32 v126, v0
	v_mov_b32_e32 v127, v0
	s_mov_b64 s[22:23], 0xe450080
	v_mov_b32_e32 v188, 0
	v_mov_b32_e32 v189, 0
	v_mov_b32_e32 v190, 0
	v_mov_b32_e32 v191, 0
	v_mov_b32_e32 v192, 0
	v_mov_b32_e32 v193, 0
	v_mov_b32_e32 v194, 0
	v_mov_b32_e32 v195, 0
	v_mov_b32_e32 v196, 0
	v_mov_b32_e32 v197, 0
	v_mov_b32_e32 v198, 0
	v_mov_b32_e32 v199, 0
	v_mov_b32_e32 v200, 0
	v_mov_b32_e32 v201, 0
	v_mov_b32_e32 v202, 0
	v_mov_b32_e32 v203, 0
	v_mov_b32_e32 v204, 0
	v_mov_b32_e32 v205, 0
	v_mov_b32_e32 v206, 0
	v_mov_b32_e32 v207, 0
	v_mov_b32_e32 v208, 0
	v_mov_b32_e32 v209, 0
	v_mov_b32_e32 v210, 0
	v_mov_b32_e32 v211, 0
	v_mov_b32_e32 v228, 0
	v_mov_b32_e32 v229, 0
	v_mov_b32_e32 v230, 0
	v_mov_b32_e32 v231, 0
	v_mov_b32_e32 v232, 0
	v_mov_b32_e32 v233, 0
	v_mov_b32_e32 v234, 0
	v_mov_b32_e32 v235, 0
	v_lshrrev_b32_e32 v240, 8, v212
	s_nop 0
	v_readfirstlane_b32 s98, v240
	s_cmp_eq_u32 s98, 0
	s_cbranch_scc1 .Lprio_5
	s_setprio 1
; #define MFMA16(a, b, c) __builtin_amdgcn_mfma_f32_16x16x32_bf16((a), (b), (c), 0, 0, 0)
; DI void glds16(const void* g, unsigned char* l) { __builtin_amdgcn_global_load_lds((const unsigned*)g, (lds_u32*)l, 16, 0, 0); }
; template <int N> DI void wait_vm() { asm volatile("s_waitcnt vmcnt(%0)" :: "n"(N) : "memory"); }
;     ...
;   for (int kt = 0; kt < nk; ++kt) {
;     wait_vm<0>();
;     __builtin_amdgcn_s_barrier();
;     if (kt + 1 < nk) {
;       unsigned char* sn = smem + ((kt + 1) & 1) * STG;
;       const int ko = (kt + 1) * 64;
; #pragma unroll
;       for (int i = 0; i < NA; ++i) glds16(Ab + ((size_t)i * 128 * lda + ko * 2) + voA, sn + (i * 512 + tid) * 16);
; #pragma unroll
;       for (int i = 0; i < NB; ++i) glds16(Bb + ((size_t)i * 128 * ldb + ko * 2) + voB, sn + AB + (i * 512 + tid) * 16);
;     } else if (nA) {
;       const unsigned nvoA = (unsigned)(srow * nlda + kch * 8) * 2u, nvoB = (unsigned)(srow * nldb + kch * 8) * 2u;
; #pragma unroll
;       for (int i = 0; i < NA; ++i) glds16((const char*)nA + (size_t)i * 128 * nlda + nvoA, smem + (i * 512 + tid) * 16);
; #pragma unroll
;       for (int i = 0; i < NB; ++i) glds16((const char*)nB + (size_t)i * 128 * nldb + nvoB, smem + AB + (i * 512 + tid) * 16);
;     }
;     const unsigned stb = lds_base + (kt & 1) * STG;
; #pragma unroll
;     for (int ks = 0; ks < 2; ++ks) {
;       const unsigned co = ((ks * 4 + fq) ^ sw) * 16;
;       const unsigned sa = stb + a_row + co, sb = stb + b_row + co;
;       bf16x8 af[4], bfr[NT];
; #pragma unroll
;       for (int n = 0; n < NT; ++n) asm volatile("ds_read_b128 %0, %1 offset:%2" : "=v"(bfr[n]) : "v"(sb), "n"(n * 2048) : "memory");
; #pragma unroll
;       for (int mg = 0; mg < MT / 4; ++mg) {
; #pragma unroll
;         for (int m = 0; m < 4; ++m) asm volatile("ds_read_b128 %0, %1 offset:%2" : "=v"(af[m]) : "v"(sa), "n"((mg * 4 + m) * 2048) : "memory");
;         if (mg == 0) {
; #pragma unroll
;           for (int n = 0; n < NT; ++n) asm volatile("s_waitcnt lgkmcnt(%1)" : "+v"(bfr[n]) : "n"(4 + NT - 1 - n) : "memory");
;         }
; #pragma unroll
;         for (int m = 0; m < 4; ++m) {
;           asm volatile("s_waitcnt lgkmcnt(%1)" : "+v"(af[m]) : "n"(3 - m) : "memory");
; #pragma unroll
;           for (int n = 0; n < NT; ++n) acc[mg * 4 + m][n] = MFMA16(bfr[n], af[m], acc[mg * 4 + m][n]);
;         }
;       }
.Lprio_5:
.LBB0_967:
	s_add_i32 s14, s15, 0x10000
	s_and_b32 s16, s14, 0x10000
	v_add_u32_e32 v143, s16, v133
	v_lshl_add_u64 v[144:145], v[136:137], 0, s[38:39]
	v_readfirstlane_b32 s16, v143
	v_add_u32_e32 v148, 0x2000, v143
	v_lshl_add_u64 v[146:147], v[144:145], 0, s[96:97]
	s_mov_b32 m0, s16
	v_readfirstlane_b32 s16, v148
	v_add_u32_e32 v148, 0x4000, v143
	s_waitcnt vmcnt(0)
	s_waitcnt lgkmcnt(0)
	s_barrier
	s_and_b32 s15, s15, 0x10000
	v_add_u32_e32 v240, s15, v142
	v_add_u32_e32 v236, v240, v140
	v_add_u32_e32 v237, v240, v131
	v_add_u32_e32 v240, s15, v141
	v_add_u32_e32 v238, v240, v140
	v_add_u32_e32 v239, v240, v131
	v_mfma_f32_16x16x32_bf16 v[60:63], v[188:191], v[204:207], v[60:63]
	ds_read_b128 v[152:155], v236 offset:0
	ds_read_b128 v[156:159], v236 offset:2048
	v_mfma_f32_16x16x32_bf16 v[56:59], v[192:195], v[204:207], v[56:59]
	ds_read_b128 v[160:163], v236 offset:4096
	ds_read_b128 v[164:167], v236 offset:6144
	global_load_lds_dwordx4 v[146:147], off
	v_mfma_f32_16x16x32_bf16 v[52:55], v[196:199], v[204:207], v[52:55]
	ds_read_b128 v[168:171], v238 offset:0
	ds_read_b128 v[172:175], v238 offset:2048
	v_mfma_f32_16x16x32_bf16 v[48:51], v[200:203], v[204:207], v[48:51]
	ds_read_b128 v[180:183], v238 offset:4096
	ds_read_b128 v[184:187], v238 offset:6144
	v_mfma_f32_16x16x32_bf16 v[44:47], v[188:191], v[208:211], v[44:47]
	v_mfma_f32_16x16x32_bf16 v[40:43], v[192:195], v[208:211], v[40:43]
	v_mfma_f32_16x16x32_bf16 v[36:39], v[196:199], v[208:211], v[36:39]
	v_lshl_add_u64 v[146:147], v[144:145], 0, s[78:79]
	s_mov_b32 m0, s16
	v_readfirstlane_b32 s16, v148
	global_load_lds_dwordx4 v[146:147], off
	v_mfma_f32_16x16x32_bf16 v[32:35], v[200:203], v[208:211], v[32:35]
	v_mfma_f32_16x16x32_bf16 v[28:31], v[188:191], v[228:231], v[28:31]
	v_mfma_f32_16x16x32_bf16 v[24:27], v[192:195], v[228:231], v[24:27]
	v_mfma_f32_16x16x32_bf16 v[20:23], v[196:199], v[228:231], v[20:23]
	v_mfma_f32_16x16x32_bf16 v[16:19], v[200:203], v[228:231], v[16:19]
	v_lshl_add_u64 v[146:147], v[144:145], 0, s[50:51]
	s_mov_b32 m0, s16
	v_lshl_add_u64 v[144:145], v[144:145], 0, s[22:23]
	global_load_lds_dwordx4 v[146:147], off
	v_mfma_f32_16x16x32_bf16 v[12:15], v[188:191], v[232:235], v[12:15]
	v_mfma_f32_16x16x32_bf16 v[8:11], v[192:195], v[232:235], v[8:11]
	v_mfma_f32_16x16x32_bf16 v[4:7], v[196:199], v[232:235], v[4:7]
	v_mfma_f32_16x16x32_bf16 v[0:3], v[200:203], v[232:235], v[0:3]
	s_waitcnt lgkmcnt(3)
	v_mfma_f32_16x16x32_bf16 v[124:127], v[152:155], v[168:171], v[124:127]
	v_add_u32_e32 v146, 0x6000, v143
	v_add_u32_e32 v148, 0x8000, v143
	v_readfirstlane_b32 s16, v146
	s_mov_b32 m0, s16
	s_mov_b64 s[16:17], 0x1b88080
	global_load_lds_dwordx4 v[144:145], off
	v_mfma_f32_16x16x32_bf16 v[120:123], v[156:159], v[168:171], v[120:123]
	ds_read_b128 v[204:207], v238 offset:8192
	v_mfma_f32_16x16x32_bf16 v[116:119], v[160:163], v[168:171], v[116:119]
	v_mfma_f32_16x16x32_bf16 v[112:115], v[164:167], v[168:171], v[112:115]
	ds_read_b128 v[208:211], v238 offset:10240
	s_waitcnt lgkmcnt(4)
	v_mfma_f32_16x16x32_bf16 v[108:111], v[152:155], v[172:175], v[108:111]
	v_mfma_f32_16x16x32_bf16 v[104:107], v[156:159], v[172:175], v[104:107]
	ds_read_b128 v[228:231], v238 offset:12288
	v_lshl_add_u64 v[144:145], v[138:139], 0, s[38:39]
	v_lshl_add_u64 v[146:147], v[144:145], 0, s[16:17]
	v_readfirstlane_b32 s16, v148
	s_mov_b32 m0, s16
	s_mov_b64 s[16:17], 0x1be0080
	v_add_u32_e32 v148, 0xa000, v143
	global_load_lds_dwordx4 v[146:147], off
	v_mfma_f32_16x16x32_bf16 v[100:103], v[160:163], v[172:175], v[100:103]
	v_mfma_f32_16x16x32_bf16 v[96:99], v[164:167], v[172:175], v[96:99]
	ds_read_b128 v[232:235], v238 offset:14336
	s_waitcnt lgkmcnt(5)
	v_mfma_f32_16x16x32_bf16 v[92:95], v[152:155], v[180:183], v[92:95]
	v_mfma_f32_16x16x32_bf16 v[88:91], v[156:159], v[180:183], v[88:91]
	ds_read_b128 v[188:191], v237 offset:0
	v_mfma_f32_16x16x32_bf16 v[84:87], v[160:163], v[180:183], v[84:87]
	v_lshl_add_u64 v[146:147], v[144:145], 0, s[16:17]
	v_readfirstlane_b32 s16, v148
	s_mov_b32 m0, s16
	s_mov_b64 s[16:17], 0x1c38080
	v_add_u32_e32 v148, 0xc000, v143
	global_load_lds_dwordx4 v[146:147], off
	v_mfma_f32_16x16x32_bf16 v[80:83], v[164:167], v[180:183], v[80:83]
	ds_read_b128 v[192:195], v237 offset:2048
	s_waitcnt lgkmcnt(6)
	v_mfma_f32_16x16x32_bf16 v[76:79], v[152:155], v[184:187], v[76:79]
	v_mfma_f32_16x16x32_bf16 v[72:75], v[156:159], v[184:187], v[72:75]
	ds_read_b128 v[196:199], v237 offset:4096
	v_mfma_f32_16x16x32_bf16 v[68:71], v[160:163], v[184:187], v[68:71]
	v_mfma_f32_16x16x32_bf16 v[64:67], v[164:167], v[184:187], v[64:67]
	ds_read_b128 v[200:203], v237 offset:6144
	v_lshl_add_u64 v[146:147], v[144:145], 0, s[16:17]
	v_readfirstlane_b32 s16, v148
	s_mov_b32 m0, s16
	s_mov_b64 s[16:17], 0x1c90080
	v_add_u32_e32 v143, 0xe000, v143
	v_lshl_add_u64 v[144:145], v[144:145], 0, s[16:17]
	v_readfirstlane_b32 s16, v143
	global_load_lds_dwordx4 v[146:147], off
	s_waitcnt lgkmcnt(7)
	v_mfma_f32_16x16x32_bf16 v[60:63], v[152:155], v[204:207], v[60:63]
	v_mfma_f32_16x16x32_bf16 v[56:59], v[156:159], v[204:207], v[56:59]
	ds_read_b128 v[168:171], v239 offset:0
	v_mfma_f32_16x16x32_bf16 v[52:55], v[160:163], v[204:207], v[52:55]
	v_mfma_f32_16x16x32_bf16 v[48:51], v[164:167], v[204:207], v[48:51]
	ds_read_b128 v[172:175], v239 offset:2048
	s_waitcnt lgkmcnt(8)
; #define MFMA16(a, b, c) __builtin_amdgcn_mfma_f32_16x16x32_bf16((a), (b), (c), 0, 0, 0)
; DI void glds16(const void* g, unsigned char* l) { __builtin_amdgcn_global_load_lds((const unsigned*)g, (lds_u32*)l, 16, 0, 0); }
; template <int N> DI void wait_vm() { asm volatile("s_waitcnt vmcnt(%0)" :: "n"(N) : "memory"); }
;     ...
;   for (int kt = 0; kt < nk; ++kt) {
;     wait_vm<0>();
;     __builtin_amdgcn_s_barrier();
;     if (kt + 1 < nk) {
;       unsigned char* sn = smem + ((kt + 1) & 1) * STG;
;       const int ko = (kt + 1) * 64;
; #pragma unroll
;       for (int i = 0; i < NA; ++i) glds16(Ab + ((size_t)i * 128 * lda + ko * 2) + voA, sn + (i * 512 + tid) * 16);
; #pragma unroll
;       for (int i = 0; i < NB; ++i) glds16(Bb + ((size_t)i * 128 * ldb + ko * 2) + voB, sn + AB + (i * 512 + tid) * 16);
;     } else if (nA) {
;       const unsigned nvoA = (unsigned)(srow * nlda + kch * 8) * 2u, nvoB = (unsigned)(srow * nldb + kch * 8) * 2u;
; #pragma unroll
;       for (int i = 0; i < NA; ++i) glds16((const char*)nA + (size_t)i * 128 * nlda + nvoA, smem + (i * 512 + tid) * 16);
; #pragma unroll
;       for (int i = 0; i < NB; ++i) glds16((const char*)nB + (size_t)i * 128 * nldb + nvoB, smem + AB + (i * 512 + tid) * 16);
;     }
;     const unsigned stb = lds_base + (kt & 1) * STG;
; #pragma unroll
;     for (int ks = 0; ks < 2; ++ks) {
;       const unsigned co = ((ks * 4 + fq) ^ sw) * 16;
;       const unsigned sa = stb + a_row + co, sb = stb + b_row + co;
;       bf16x8 af[4], bfr[NT];
; #pragma unroll
;       for (int n = 0; n < NT; ++n) asm volatile("ds_read_b128 %0, %1 offset:%2" : "=v"(bfr[n]) : "v"(sb), "n"(n * 2048) : "memory");
; #pragma unroll
;       for (int mg = 0; mg < MT / 4; ++mg) {
; #pragma unroll
;         for (int m = 0; m < 4; ++m) asm volatile("ds_read_b128 %0, %1 offset:%2" : "=v"(af[m]) : "v"(sa), "n"((mg * 4 + m) * 2048) : "memory");
;         if (mg == 0) {
; #pragma unroll
;           for (int n = 0; n < NT; ++n) asm volatile("s_waitcnt lgkmcnt(%1)" : "+v"(bfr[n]) : "n"(4 + NT - 1 - n) : "memory");
;         }
; #pragma unroll
;         for (int m = 0; m < 4; ++m) {
;           asm volatile("s_waitcnt lgkmcnt(%1)" : "+v"(af[m]) : "n"(3 - m) : "memory");
; #pragma unroll
;           for (int n = 0; n < NT; ++n) acc[mg * 4 + m][n] = MFMA16(bfr[n], af[m], acc[mg * 4 + m][n]);
;         }
;       }
	v_mfma_f32_16x16x32_bf16 v[44:47], v[152:155], v[208:211], v[44:47]
	s_mov_b32 m0, s16
	s_nop 0
	global_load_lds_dwordx4 v[144:145], off
	v_mfma_f32_16x16x32_bf16 v[40:43], v[156:159], v[208:211], v[40:43]
	ds_read_b128 v[180:183], v239 offset:4096
	v_mfma_f32_16x16x32_bf16 v[36:39], v[160:163], v[208:211], v[36:39]
	v_mfma_f32_16x16x32_bf16 v[32:35], v[164:167], v[208:211], v[32:35]
	ds_read_b128 v[184:187], v239 offset:6144
	s_waitcnt lgkmcnt(9)
	v_mfma_f32_16x16x32_bf16 v[28:31], v[152:155], v[228:231], v[28:31]
	v_mfma_f32_16x16x32_bf16 v[24:27], v[156:159], v[228:231], v[24:27]
	v_mfma_f32_16x16x32_bf16 v[20:23], v[160:163], v[228:231], v[20:23]
	v_mfma_f32_16x16x32_bf16 v[16:19], v[164:167], v[228:231], v[16:19]
	s_waitcnt lgkmcnt(8)
	v_mfma_f32_16x16x32_bf16 v[12:15], v[152:155], v[232:235], v[12:15]
	v_mfma_f32_16x16x32_bf16 v[8:11], v[156:159], v[232:235], v[8:11]
	v_mfma_f32_16x16x32_bf16 v[4:7], v[160:163], v[232:235], v[4:7]
	v_mfma_f32_16x16x32_bf16 v[0:3], v[164:167], v[232:235], v[0:3]
	s_waitcnt lgkmcnt(3)
	v_mfma_f32_16x16x32_bf16 v[124:127], v[188:191], v[168:171], v[124:127]
	v_mfma_f32_16x16x32_bf16 v[120:123], v[192:195], v[168:171], v[120:123]
	ds_read_b128 v[204:207], v239 offset:8192
	v_mfma_f32_16x16x32_bf16 v[116:119], v[196:199], v[168:171], v[116:119]
	v_mfma_f32_16x16x32_bf16 v[112:115], v[200:203], v[168:171], v[112:115]
	ds_read_b128 v[208:211], v239 offset:10240
	s_waitcnt lgkmcnt(4)
	v_mfma_f32_16x16x32_bf16 v[108:111], v[188:191], v[172:175], v[108:111]
	v_mfma_f32_16x16x32_bf16 v[104:107], v[192:195], v[172:175], v[104:107]
	ds_read_b128 v[228:231], v239 offset:12288
	v_mfma_f32_16x16x32_bf16 v[100:103], v[196:199], v[172:175], v[100:103]
	v_mfma_f32_16x16x32_bf16 v[96:99], v[200:203], v[172:175], v[96:99]
	ds_read_b128 v[232:235], v239 offset:14336
	s_waitcnt lgkmcnt(5)
	v_mfma_f32_16x16x32_bf16 v[92:95], v[188:191], v[180:183], v[92:95]
	v_mfma_f32_16x16x32_bf16 v[88:91], v[192:195], v[180:183], v[88:91]
	v_mfma_f32_16x16x32_bf16 v[84:87], v[196:199], v[180:183], v[84:87]
	v_mfma_f32_16x16x32_bf16 v[80:83], v[200:203], v[180:183], v[80:83]
	s_waitcnt lgkmcnt(4)
	v_mfma_f32_16x16x32_bf16 v[76:79], v[188:191], v[184:187], v[76:79]
	v_mfma_f32_16x16x32_bf16 v[72:75], v[192:195], v[184:187], v[72:75]
	v_mfma_f32_16x16x32_bf16 v[68:71], v[196:199], v[184:187], v[68:71]
	v_mfma_f32_16x16x32_bf16 v[64:67], v[200:203], v[184:187], v[64:67]
	s_add_u32 s38, s38, 0x80
	s_addc_u32 s39, s39, 0
	s_cmpk_eq_i32 s38, 0x1580
	s_mov_b32 s15, s14
	s_cbranch_scc0 .LBB0_967
	s_waitcnt lgkmcnt(0)
	v_mfma_f32_16x16x32_bf16 v[60:63], v[188:191], v[204:207], v[60:63]
	v_mfma_f32_16x16x32_bf16 v[56:59], v[192:195], v[204:207], v[56:59]
	v_mfma_f32_16x16x32_bf16 v[52:55], v[196:199], v[204:207], v[52:55]
	v_mfma_f32_16x16x32_bf16 v[48:51], v[200:203], v[204:207], v[48:51]
	v_mfma_f32_16x16x32_bf16 v[44:47], v[188:191], v[208:211], v[44:47]
	v_mfma_f32_16x16x32_bf16 v[40:43], v[192:195], v[208:211], v[40:43]
	v_mfma_f32_16x16x32_bf16 v[36:39], v[196:199], v[208:211], v[36:39]
	v_mfma_f32_16x16x32_bf16 v[32:35], v[200:203], v[208:211], v[32:35]
	v_mfma_f32_16x16x32_bf16 v[28:31], v[188:191], v[228:231], v[28:31]
	v_mfma_f32_16x16x32_bf16 v[24:27], v[192:195], v[228:231], v[24:27]
	v_mfma_f32_16x16x32_bf16 v[20:23], v[196:199], v[228:231], v[20:23]
	v_mfma_f32_16x16x32_bf16 v[16:19], v[200:203], v[228:231], v[16:19]
	v_mfma_f32_16x16x32_bf16 v[12:15], v[188:191], v[232:235], v[12:15]
	v_mfma_f32_16x16x32_bf16 v[8:11], v[192:195], v[232:235], v[8:11]
	v_mfma_f32_16x16x32_bf16 v[4:7], v[196:199], v[232:235], v[4:7]
	v_mfma_f32_16x16x32_bf16 v[0:3], v[200:203], v[232:235], v[0:3]
	s_setprio 0
	s_waitcnt vmcnt(0)
	s_andn2_b64 vcc, exec, s[6:7]
	s_mov_b32 s23, 0x10000
	s_barrier
	s_cbranch_vccnz .LBB0_970
	s_lshl_b64 s[6:7], s[12:13], 1
	s_add_u32 s12, s52, s6
	s_addc_u32 s13, s53, s7
	s_and_b64 s[6:7], exec, s[0:1]
	s_cselect_b32 s7, 0, s13
	s_cselect_b32 s6, 0, s12
	s_lshl_b64 s[10:11], s[10:11], 1
	s_add_u32 s10, s8, s10
	s_addc_u32 s11, s18, s11
	v_lshl_add_u64 v[136:137], s[6:7], 0, v[128:129]
	v_lshl_add_u64 v[138:139], s[10:11], 0, v[128:129]
	s_mov_b64 s[6:7], 0xb0000
	v_lshl_add_u64 v[144:145], v[136:137], 0, s[6:7]
	v_lshl_add_u64 v[146:147], v[138:139], 0, s[6:7]
	s_mov_b64 s[6:7], 0x58000
	v_lshl_add_u64 v[150:151], v[138:139], 0, s[6:7]
	v_lshl_add_u64 v[154:155], v[136:137], 0, s[6:7]
	v_readfirstlane_b32 s6, v133
	s_mov_b64 s[10:11], 0x108000
	s_mov_b32 m0, s6
	v_lshl_add_u64 v[152:153], v[136:137], 0, s[10:11]
	global_load_lds_dwordx4 v[136:137], off
	v_add_u32_e32 v136, 0x2000, v133
	v_add_u32_e32 v143, 0x4000, v133
	v_readfirstlane_b32 s6, v136
	s_mov_b32 m0, s6
	v_readfirstlane_b32 s6, v143
	v_add_u32_e32 v136, 0x6000, v133
	global_load_lds_dwordx4 v[154:155], off
	s_mov_b32 m0, s6
	v_readfirstlane_b32 s6, v136
	v_add_u32_e32 v136, 0x8000, v133
	global_load_lds_dwordx4 v[144:145], off
	s_mov_b32 m0, s6
	v_readfirstlane_b32 s6, v136
	v_add_u32_e32 v136, 0xa000, v133
	v_add_u32_e32 v128, 0xc000, v133
	global_load_lds_dwordx4 v[152:153], off
	s_mov_b32 m0, s6
	v_readfirstlane_b32 s6, v136
	global_load_lds_dwordx4 v[138:139], off
	s_mov_b32 m0, s6
	v_readfirstlane_b32 s6, v128
	v_add_u32_e32 v128, 0xe000, v133
	global_load_lds_dwordx4 v[150:151], off
	s_mov_b32 m0, s6
	v_readfirstlane_b32 s6, v128
	v_lshl_add_u64 v[148:149], v[138:139], 0, s[10:11]
	global_load_lds_dwordx4 v[146:147], off
	s_mov_b32 m0, s6
	s_nop 0
	global_load_lds_dwordx4 v[148:149], off
